# GEMM K-loops: the lgkmcnt(0) wait that hipcc repeats behind each barrier (LDS already drained by the wait in front of it) removed, 36 sites; on top of all54 (no s_setprio toggles)
# baseline (speedup 1.0000x reference)
; template <class Epi, class Sched, bool ALIGN_EPI = false, bool SP2 = false>
; __device__ __forceinline__ void gemm_phase(PG8_LAS unsigned char* lds, const Gemm g, const Sched& S, const Epi& E, const int wid) {
;     ...
;         const bool has_next = S.next(ui + 1, nxt);
;         const char* nA = has_next ? (const char*)g.A + (size_t)nxt.pm * tstep : cA; const char* nB = has_next ? (const char*)g.Bt + (size_t)nxt.pn * tstep : cB;
;         for (int t = 0; t < nt; t += 2) {
;             const bool last = (t == nt - 2);
;             const char* a1 = cA + (size_t)(t + 1) * kstep;
;             const char* a2 = last ? nA : cA + (size_t)(t + 2) * kstep; const char* b2 = last ? nB : cB + (size_t)(t + 2) * kstep;
;             const char* a3 = a2 + kstep; const char* b3 = b2 + kstep;
.LBB0_268:
	s_ashr_i32 s15, s14, 31
	s_lshl_b64 s[16:17], s[14:15], 19
	s_add_u32 s16, s80, s16
	s_addc_u32 s17, s81, s17
	s_and_b64 s[18:19], s[4:5], exec
	s_cselect_b32 s15, s17, s23
	s_cselect_b32 s44, s16, s22
	s_ashr_i32 s13, s12, 31
	s_lshl_b64 s[18:19], s[12:13], 19
	s_add_u32 s18, s10, s18
	s_addc_u32 s19, s11, s19
	s_and_b64 s[26:27], s[4:5], exec
	s_cselect_b32 s13, s19, s25
	s_cselect_b32 s45, s18, s24
	s_add_u32 s22, s22, 0x40080
	s_addc_u32 s23, s23, 0
	s_add_u32 s46, s24, 0x100

; template <class Epi, class Sched, bool ALIGN_EPI = false, bool SP2 = false>
; __device__ __forceinline__ void gemm_phase(PG8_LAS unsigned char* lds, const Gemm g, const Sched& S, const Epi& E, const int wid) {
;     ...
;         for (int t = 0; t < nt; t += 2) {
;             const bool last = (t == nt - 2);
;             const char* a1 = cA + (size_t)(t + 1) * kstep;
;             const char* a2 = last ? nA : cA + (size_t)(t + 2) * kstep; const char* b2 = last ? nB : cB + (size_t)(t + 2) * kstep;
	s_addc_u32 s47, s25, 0
	s_mov_b32 s48, -2


; #define PG8_STAGE(bufoff, gbase, voff) do { _Pragma("unroll") for (int _i = 0; _i < 2; ++_i) \
;         __builtin_amdgcn_global_load_lds((const unsigned*)((const char*)(gbase) + (voff)[_i]), (PG8_LAS unsigned*)(lds + (bufoff) + ldsw + _i * 8192), 16, 0, 0); } while (0)
; #define PG8_LDA(dst, b, h) do { _Pragma("unroll") for (int m = 0; m < 4; ++m) _Pragma("unroll") for (int k = 0; k < 2; ++k) dst[m][k] = *(const PG8_LAS bf16x8*)(lds + PG8_SA(b, h) + aoff + m * 2048 + k * 1024); } while (0)
; #define PG8_LDB(dst, b, h) do { _Pragma("unroll") for (int n = 0; n < 2; ++n) _Pragma("unroll") for (int k = 0; k < 2; ++k) dst[n][k] = *(const PG8_LAS bf16x8*)(lds + PG8_SB(b, h) + boff + n * 2048 + k * 1024); } while (0)
; #define PG8_MMA(ai, bj, At, Bt) do { __builtin_amdgcn_s_setprio(1); _Pragma("unroll") for (int m = 0; m < 4; ++m) _Pragma("unroll") for (int n = 0; n < 2; ++n) _Pragma("unroll") for (int k = 0; k < 2; ++k) \
;         acc[ai][bj][m][n] = __builtin_amdgcn_mfma_f32_16x16x32_bf16(Bt[n][k], At[m][k], acc[ai][bj][m][n], 0, 0, 0); __builtin_amdgcn_s_setprio(0); } while (0)
; #define PG8_WAIT_V(n) asm volatile("s_waitcnt vmcnt(" #n ")" ::: "memory")
; #define PG8_BAR __builtin_amdgcn_s_barrier()
; template <class Epi, class Sched, bool ALIGN_EPI = false, bool SP2 = false>
; __device__ __forceinline__ void gemm_phase(PG8_LAS unsigned char* lds, const Gemm g, const Sched& S, const Epi& E, const int wid) {
;     ...
;         for (int t = 0; t < nt; t += 2) {
;             const bool last = (t == nt - 2);
;             const char* a1 = cA + (size_t)(t + 1) * kstep;
;             const char* a2 = last ? nA : cA + (size_t)(t + 2) * kstep; const char* b2 = last ? nB : cB + (size_t)(t + 2) * kstep;
;             const char* a3 = a2 + kstep; const char* b3 = b2 + kstep;
;             if (last && has_next) S.a_ready(nxt);
;             if constexpr (SP2) {
;             PG8_LDB(B0, 0, 0); PG8_LDB(B1, 0, 1); PG8_SCHED; PG8_LDA(At, 0, 0); PG8_STAGE(PG8_SA(1, 1), a1 + hstep, voffA);
;             PG8_WAIT_V(8); PG8_WAIT_L(0); PG8_BAR; PG8_MMA(0, 0, At, B0); PG8_MMA(0, 1, At, B1); PG8_BAR; PG8_SCHED;
;             PG8_LDA(At, 0, 1); PG8_STAGE(PG8_SB(0, 0), b2, voffB); PG8_STAGE(PG8_SB(0, 1), b2 + hstep, voffB); PG8_STAGE(PG8_SA(0, 0), a2, voffA);
;             PG8_WAIT_V(8); PG8_WAIT_L(0); PG8_BAR; PG8_MMA(1, 0, At, B0); PG8_MMA(1, 1, At, B1); PG8_BAR; PG8_SCHED;
	ds_read_b128 v[144:147], v151
	ds_read_b128 v[154:157], v151 offset:1024
	ds_read_b128 v[158:161], v151 offset:2048
	ds_read_b128 v[162:165], v151 offset:3072
	ds_read_b128 v[166:169], v152
	ds_read_b128 v[170:173], v152 offset:1024
	ds_read_b128 v[174:177], v152 offset:2048
	ds_read_b128 v[178:181], v152 offset:3072
	s_add_u32 s24, s22, 0xfffc0080
	s_addc_u32 s25, s23, -1
	s_cmp_eq_u32 s48, 12
	s_cselect_b32 s27, s15, s25
	s_cselect_b32 s26, s44, s24
	s_cselect_b32 s25, s13, s47
	s_cselect_b32 s24, s45, s46
	v_lshl_add_u64 v[206:207], s[22:23], 0, v[136:137]
	s_add_i32 m0, s21, 0xc000
	ds_read_b128 v[182:185], v153
	ds_read_b128 v[186:189], v153 offset:1024
	ds_read_b128 v[190:193], v153 offset:2048
	ds_read_b128 v[194:197], v153 offset:3072
	ds_read_b128 v[198:201], v153 offset:4096
	ds_read_b128 v[202:205], v153 offset:5120
	ds_read_b128 v[212:215], v153 offset:6144
	ds_read_b128 v[216:219], v153 offset:7168
	global_load_lds_dwordx4 v[206:207], off
	v_lshl_add_u64 v[206:207], s[22:23], 0, v[138:139]
	s_add_i32 m0, s21, 0xe000
	s_nop 0
	global_load_lds_dwordx4 v[206:207], off
	s_waitcnt vmcnt(8)
	s_waitcnt lgkmcnt(0)
	s_barrier
	v_mfma_f32_16x16x32_bf16 v[124:127], v[144:147], v[182:185], 0
	v_mfma_f32_16x16x32_bf16 v[116:119], v[158:161], v[182:185], 0
	v_mfma_f32_16x16x32_bf16 v[108:111], v[144:147], v[190:193], 0
	v_mfma_f32_16x16x32_bf16 v[100:103], v[158:161], v[190:193], 0
	v_mfma_f32_16x16x32_bf16 v[92:95], v[144:147], v[198:201], 0
	v_mfma_f32_16x16x32_bf16 v[84:87], v[158:161], v[198:201], 0
	v_mfma_f32_16x16x32_bf16 v[76:79], v[144:147], v[212:215], 0
	v_mfma_f32_16x16x32_bf16 v[68:71], v[158:161], v[212:215], 0
	v_mfma_f32_16x16x32_bf16 v[124:127], v[154:157], v[186:189], v[124:127]
	v_mfma_f32_16x16x32_bf16 v[116:119], v[162:165], v[186:189], v[116:119]
	v_mfma_f32_16x16x32_bf16 v[108:111], v[154:157], v[194:197], v[108:111]
	v_mfma_f32_16x16x32_bf16 v[100:103], v[162:165], v[194:197], v[100:103]
	v_mfma_f32_16x16x32_bf16 v[92:95], v[154:157], v[202:205], v[92:95]
	v_mfma_f32_16x16x32_bf16 v[84:87], v[162:165], v[202:205], v[84:87]
	v_mfma_f32_16x16x32_bf16 v[76:79], v[154:157], v[216:219], v[76:79]
	v_mfma_f32_16x16x32_bf16 v[68:71], v[162:165], v[216:219], v[68:71]
	v_mfma_f32_16x16x32_bf16 v[120:123], v[166:169], v[182:185], 0
	v_mfma_f32_16x16x32_bf16 v[112:115], v[174:177], v[182:185], 0
	v_mfma_f32_16x16x32_bf16 v[104:107], v[166:169], v[190:193], 0
	v_mfma_f32_16x16x32_bf16 v[96:99], v[174:177], v[190:193], 0
	v_mfma_f32_16x16x32_bf16 v[88:91], v[166:169], v[198:201], 0
	v_mfma_f32_16x16x32_bf16 v[80:83], v[174:177], v[198:201], 0
	v_mfma_f32_16x16x32_bf16 v[72:75], v[166:169], v[212:215], 0
	v_mfma_f32_16x16x32_bf16 v[64:67], v[174:177], v[212:215], 0
	v_mfma_f32_16x16x32_bf16 v[120:123], v[170:173], v[186:189], v[120:123]
	v_mfma_f32_16x16x32_bf16 v[112:115], v[178:181], v[186:189], v[112:115]
	v_mfma_f32_16x16x32_bf16 v[104:107], v[170:173], v[194:197], v[104:107]
	v_mfma_f32_16x16x32_bf16 v[96:99], v[178:181], v[194:197], v[96:99]
	v_mfma_f32_16x16x32_bf16 v[88:91], v[170:173], v[202:205], v[88:91]
	v_mfma_f32_16x16x32_bf16 v[80:83], v[178:181], v[202:205], v[80:83]
	v_mfma_f32_16x16x32_bf16 v[72:75], v[170:173], v[216:219], v[72:75]
	v_mfma_f32_16x16x32_bf16 v[64:67], v[178:181], v[216:219], v[64:67]
	s_barrier
	s_add_i32 s49, s40, s9
	v_lshl_add_u64 v[206:207], s[24:25], 0, v[132:133]
	s_mov_b32 m0, s49
	ds_read_b128 v[182:185], v153 offset:16384
	ds_read_b128 v[186:189], v153 offset:17408
	ds_read_b128 v[190:193], v153 offset:18432
	ds_read_b128 v[194:197], v153 offset:19456
	ds_read_b128 v[198:201], v153 offset:20480
	ds_read_b128 v[202:205], v153 offset:21504
	ds_read_b128 v[212:215], v153 offset:22528
	ds_read_b128 v[216:219], v153 offset:23552
	global_load_lds_dwordx4 v[206:207], off
	s_add_i32 m0, s49, 0x2000
	s_add_u32 s50, s24, 0x40000
	v_lshl_add_u64 v[220:221], s[24:25], 0, v[128:129]
	s_addc_u32 s51, s25, 0
	s_add_i32 s49, s41, s9
	global_load_lds_dwordx4 v[220:221], off
	v_lshl_add_u64 v[222:223], s[50:51], 0, v[132:133]
	s_mov_b32 m0, s49
	v_lshl_add_u64 v[224:225], s[26:27], 0, v[130:131]
	global_load_lds_dwordx4 v[222:223], off
	v_lshl_add_u64 v[222:223], s[50:51], 0, v[128:129]
	s_add_i32 m0, s49, 0x2000
	s_nop 0
	global_load_lds_dwordx4 v[222:223], off
	v_lshl_add_u64 v[222:223], s[26:27], 0, v[134:135]
	s_mov_b32 m0, s21
	s_nop 0
	global_load_lds_dwordx4 v[222:223], off
	s_mov_b32 m0, s30
	s_nop 0
	global_load_lds_dwordx4 v[224:225], off
	s_waitcnt vmcnt(8)
	s_waitcnt lgkmcnt(0)
	s_barrier
	v_mfma_f32_16x16x32_bf16 v[60:63], v[144:147], v[182:185], 0
	v_mfma_f32_16x16x32_bf16 v[52:55], v[158:161], v[182:185], 0
	v_mfma_f32_16x16x32_bf16 v[44:47], v[144:147], v[190:193], 0
	v_mfma_f32_16x16x32_bf16 v[36:39], v[158:161], v[190:193], 0
	v_mfma_f32_16x16x32_bf16 v[28:31], v[144:147], v[198:201], 0
	v_mfma_f32_16x16x32_bf16 v[20:23], v[158:161], v[198:201], 0
	v_mfma_f32_16x16x32_bf16 v[12:15], v[144:147], v[212:215], 0
	v_mfma_f32_16x16x32_bf16 v[4:7], v[158:161], v[212:215], 0
	v_mfma_f32_16x16x32_bf16 v[60:63], v[154:157], v[186:189], v[60:63]
	v_mfma_f32_16x16x32_bf16 v[52:55], v[162:165], v[186:189], v[52:55]
	v_mfma_f32_16x16x32_bf16 v[44:47], v[154:157], v[194:197], v[44:47]
	v_mfma_f32_16x16x32_bf16 v[36:39], v[162:165], v[194:197], v[36:39]
	v_mfma_f32_16x16x32_bf16 v[28:31], v[154:157], v[202:205], v[28:31]
	v_mfma_f32_16x16x32_bf16 v[20:23], v[162:165], v[202:205], v[20:23]
	v_mfma_f32_16x16x32_bf16 v[12:15], v[154:157], v[216:219], v[12:15]
	v_mfma_f32_16x16x32_bf16 v[4:7], v[162:165], v[216:219], v[4:7]
	v_mfma_f32_16x16x32_bf16 v[56:59], v[166:169], v[182:185], 0
	v_mfma_f32_16x16x32_bf16 v[48:51], v[174:177], v[182:185], 0
	v_mfma_f32_16x16x32_bf16 v[40:43], v[166:169], v[190:193], 0
	v_mfma_f32_16x16x32_bf16 v[32:35], v[174:177], v[190:193], 0
	v_mfma_f32_16x16x32_bf16 v[24:27], v[166:169], v[198:201], 0
	v_mfma_f32_16x16x32_bf16 v[16:19], v[174:177], v[198:201], 0
	v_mfma_f32_16x16x32_bf16 v[8:11], v[166:169], v[212:215], 0
	v_mfma_f32_16x16x32_bf16 v[0:3], v[174:177], v[212:215], 0
	v_mfma_f32_16x16x32_bf16 v[56:59], v[170:173], v[186:189], v[56:59]
	v_mfma_f32_16x16x32_bf16 v[48:51], v[178:181], v[186:189], v[48:51]
	v_mfma_f32_16x16x32_bf16 v[40:43], v[170:173], v[194:197], v[40:43]
	v_mfma_f32_16x16x32_bf16 v[32:35], v[178:181], v[194:197], v[32:35]
	v_mfma_f32_16x16x32_bf16 v[24:27], v[170:173], v[202:205], v[24:27]
	v_mfma_f32_16x16x32_bf16 v[16:19], v[178:181], v[202:205], v[16:19]
	v_mfma_f32_16x16x32_bf16 v[8:11], v[170:173], v[216:219], v[8:11]
	v_mfma_f32_16x16x32_bf16 v[0:3], v[178:181], v[216:219], v[0:3]
	s_barrier
; #define PG8_STAGE(bufoff, gbase, voff) do { _Pragma("unroll") for (int _i = 0; _i < 2; ++_i) \
;         __builtin_amdgcn_global_load_lds((const unsigned*)((const char*)(gbase) + (voff)[_i]), (PG8_LAS unsigned*)(lds + (bufoff) + ldsw + _i * 8192), 16, 0, 0); } while (0)
; #define PG8_LDA(dst, b, h) do { _Pragma("unroll") for (int m = 0; m < 4; ++m) _Pragma("unroll") for (int k = 0; k < 2; ++k) dst[m][k] = *(const PG8_LAS bf16x8*)(lds + PG8_SA(b, h) + aoff + m * 2048 + k * 1024); } while (0)
; #define PG8_WAIT_V(n) asm volatile("s_waitcnt vmcnt(" #n ")" ::: "memory")
; #define PG8_WAIT_L(n) asm volatile("s_waitcnt lgkmcnt(" #n ")" ::: "memory")
; #define PG8_BAR __builtin_amdgcn_s_barrier()
; template <class Epi, class Sched, bool ALIGN_EPI = false, bool SP2 = false>
; __device__ __forceinline__ void gemm_phase(PG8_LAS unsigned char* lds, const Gemm g, const Sched& S, const Epi& E, const int wid) {
;     ...
;         for (int t = 0; t < nt; t += 2) {
;             const bool last = (t == nt - 2);
;             const char* a1 = cA + (size_t)(t + 1) * kstep;
;             const char* a2 = last ? nA : cA + (size_t)(t + 2) * kstep; const char* b2 = last ? nB : cB + (size_t)(t + 2) * kstep;
;             const char* a3 = a2 + kstep; const char* b3 = b2 + kstep;
;             if (last && has_next) S.a_ready(nxt);
;             if constexpr (SP2) {
;             PG8_LDB(B0, 0, 0); PG8_LDB(B1, 0, 1); PG8_SCHED; PG8_LDA(At, 0, 0); PG8_STAGE(PG8_SA(1, 1), a1 + hstep, voffA);
;             PG8_WAIT_V(8); PG8_WAIT_L(0); PG8_BAR; PG8_MMA(0, 0, At, B0); PG8_MMA(0, 1, At, B1); PG8_BAR; PG8_SCHED;
;             PG8_LDA(At, 0, 1); PG8_STAGE(PG8_SB(0, 0), b2, voffB); PG8_STAGE(PG8_SB(0, 1), b2 + hstep, voffB); PG8_STAGE(PG8_SA(0, 0), a2, voffA);
;             PG8_WAIT_V(8); PG8_WAIT_L(0); PG8_BAR; PG8_MMA(1, 0, At, B0); PG8_MMA(1, 1, At, B1); PG8_BAR; PG8_SCHED;
;             PG8_LDB(B0, 1, 0); PG8_LDB(B1, 1, 1); PG8_SCHED; PG8_LDA(At, 1, 0); PG8_STAGE(PG8_SA(0, 1), a2 + hstep, voffA);
;             PG8_WAIT_V(8); PG8_WAIT_L(0); PG8_BAR; PG8_MMA(0, 0, At, B0); PG8_MMA(0, 1, At, B1); PG8_BAR; PG8_SCHED;
;             PG8_LDA(At, 1, 1); PG8_STAGE(PG8_SB(1, 0), b3, voffB); PG8_STAGE(PG8_SB(1, 1), b3 + hstep, voffB); PG8_STAGE(PG8_SA(1, 0), a3, voffA);
;             PG8_WAIT_V(8); PG8_WAIT_L(0); PG8_BAR; PG8_MMA(1, 0, At, B0); PG8_MMA(1, 1, At, B1); PG8_BAR; PG8_SCHED;
	s_add_i32 s49, 0, 0x18000
	s_add_i32 s50, 0, 0x1c000
	v_add_u32_e32 v162, s49, v149
	v_add_u32_e32 v178, s50, v149
	ds_read_b128 v[144:147], v162
	ds_read_b128 v[154:157], v162 offset:1024
	ds_read_b128 v[158:161], v162 offset:2048
	ds_read_b128 v[162:165], v162 offset:3072
	ds_read_b128 v[166:169], v178
	ds_read_b128 v[170:173], v178 offset:1024
	ds_read_b128 v[174:177], v178 offset:2048
	ds_read_b128 v[178:181], v178 offset:3072
	s_add_u32 s26, s26, 0x40000
	s_addc_u32 s27, s27, 0
	s_mov_b32 m0, s31
	v_lshl_add_u64 v[226:227], s[26:27], 0, v[134:135]
	ds_read_b128 v[182:185], v153 offset:32768
	ds_read_b128 v[186:189], v153 offset:33792
	ds_read_b128 v[190:193], v153 offset:34816
	ds_read_b128 v[194:197], v153 offset:35840
	ds_read_b128 v[198:201], v153 offset:36864
	ds_read_b128 v[202:205], v153 offset:37888
	ds_read_b128 v[212:215], v153 offset:38912
	ds_read_b128 v[216:219], v153 offset:39936
	global_load_lds_dwordx4 v[226:227], off
	v_lshl_add_u64 v[226:227], s[26:27], 0, v[130:131]
	s_mov_b32 m0, s33
	s_nop 0
	global_load_lds_dwordx4 v[226:227], off
	s_waitcnt vmcnt(8)
	s_waitcnt lgkmcnt(0)
	s_barrier
	v_mfma_f32_16x16x32_bf16 v[124:127], v[144:147], v[182:185], v[124:127]
	v_mfma_f32_16x16x32_bf16 v[116:119], v[158:161], v[182:185], v[116:119]
	v_mfma_f32_16x16x32_bf16 v[108:111], v[144:147], v[190:193], v[108:111]
	v_mfma_f32_16x16x32_bf16 v[100:103], v[158:161], v[190:193], v[100:103]
	v_mfma_f32_16x16x32_bf16 v[92:95], v[144:147], v[198:201], v[92:95]
	v_mfma_f32_16x16x32_bf16 v[84:87], v[158:161], v[198:201], v[84:87]
	v_mfma_f32_16x16x32_bf16 v[76:79], v[144:147], v[212:215], v[76:79]
	v_mfma_f32_16x16x32_bf16 v[68:71], v[158:161], v[212:215], v[68:71]
	v_mfma_f32_16x16x32_bf16 v[124:127], v[154:157], v[186:189], v[124:127]
	v_mfma_f32_16x16x32_bf16 v[116:119], v[162:165], v[186:189], v[116:119]
	v_mfma_f32_16x16x32_bf16 v[108:111], v[154:157], v[194:197], v[108:111]
	v_mfma_f32_16x16x32_bf16 v[100:103], v[162:165], v[194:197], v[100:103]
	v_mfma_f32_16x16x32_bf16 v[92:95], v[154:157], v[202:205], v[92:95]
	v_mfma_f32_16x16x32_bf16 v[84:87], v[162:165], v[202:205], v[84:87]
	v_mfma_f32_16x16x32_bf16 v[76:79], v[154:157], v[216:219], v[76:79]
	v_mfma_f32_16x16x32_bf16 v[68:71], v[162:165], v[216:219], v[68:71]
	v_mfma_f32_16x16x32_bf16 v[120:123], v[166:169], v[182:185], v[120:123]
	v_mfma_f32_16x16x32_bf16 v[112:115], v[174:177], v[182:185], v[112:115]
	v_mfma_f32_16x16x32_bf16 v[104:107], v[166:169], v[190:193], v[104:107]
	v_mfma_f32_16x16x32_bf16 v[96:99], v[174:177], v[190:193], v[96:99]
	v_mfma_f32_16x16x32_bf16 v[88:91], v[166:169], v[198:201], v[88:91]
	v_mfma_f32_16x16x32_bf16 v[80:83], v[174:177], v[198:201], v[80:83]
	v_mfma_f32_16x16x32_bf16 v[72:75], v[166:169], v[212:215], v[72:75]
	v_mfma_f32_16x16x32_bf16 v[64:67], v[174:177], v[212:215], v[64:67]
	v_mfma_f32_16x16x32_bf16 v[120:123], v[170:173], v[186:189], v[120:123]
	v_mfma_f32_16x16x32_bf16 v[112:115], v[178:181], v[186:189], v[112:115]
	v_mfma_f32_16x16x32_bf16 v[104:107], v[170:173], v[194:197], v[104:107]
	v_mfma_f32_16x16x32_bf16 v[96:99], v[178:181], v[194:197], v[96:99]
	v_mfma_f32_16x16x32_bf16 v[88:91], v[170:173], v[202:205], v[88:91]
	v_mfma_f32_16x16x32_bf16 v[80:83], v[178:181], v[202:205], v[80:83]
	v_mfma_f32_16x16x32_bf16 v[72:75], v[170:173], v[216:219], v[72:75]
	v_mfma_f32_16x16x32_bf16 v[64:67], v[178:181], v[216:219], v[64:67]
	s_barrier
	s_add_i32 s26, s49, s9
	v_lshl_add_u64 v[206:207], v[206:207], 0, s[6:7]
	s_mov_b32 m0, s26
	ds_read_b128 v[182:185], v153 offset:49152
	ds_read_b128 v[186:189], v153 offset:50176
	ds_read_b128 v[190:193], v153 offset:51200
	ds_read_b128 v[194:197], v153 offset:52224
	ds_read_b128 v[198:201], v153 offset:53248
	ds_read_b128 v[202:205], v153 offset:54272
	ds_read_b128 v[212:215], v153 offset:55296
	ds_read_b128 v[216:219], v153 offset:56320
	global_load_lds_dwordx4 v[206:207], off
	s_add_i32 m0, s26, 0x2000
	s_add_u32 s24, s24, 0x40080
	v_lshl_add_u64 v[206:207], v[220:221], 0, s[6:7]
	s_addc_u32 s25, s25, 0
	s_add_i32 s26, s50, s9
	global_load_lds_dwordx4 v[206:207], off
	v_lshl_add_u64 v[206:207], s[24:25], 0, v[132:133]
	s_mov_b32 m0, s26
	s_nop 0
	global_load_lds_dwordx4 v[206:207], off
	v_lshl_add_u64 v[206:207], s[24:25], 0, v[128:129]
	s_add_i32 m0, s26, 0x2000
	s_nop 0
	global_load_lds_dwordx4 v[206:207], off
	v_lshl_add_u64 v[206:207], v[222:223], 0, s[6:7]
	s_mov_b32 m0, s38
	s_nop 0
	global_load_lds_dwordx4 v[206:207], off
	v_lshl_add_u64 v[206:207], v[224:225], 0, s[6:7]
	s_mov_b32 m0, s39
	s_nop 0
	global_load_lds_dwordx4 v[206:207], off
	s_waitcnt vmcnt(8)
	s_waitcnt lgkmcnt(0)
	s_barrier
	v_mfma_f32_16x16x32_bf16 v[60:63], v[144:147], v[182:185], v[60:63]
	v_mfma_f32_16x16x32_bf16 v[52:55], v[158:161], v[182:185], v[52:55]
	v_mfma_f32_16x16x32_bf16 v[44:47], v[144:147], v[190:193], v[44:47]
	v_mfma_f32_16x16x32_bf16 v[36:39], v[158:161], v[190:193], v[36:39]
	v_mfma_f32_16x16x32_bf16 v[28:31], v[144:147], v[198:201], v[28:31]
	v_mfma_f32_16x16x32_bf16 v[20:23], v[158:161], v[198:201], v[20:23]
	v_mfma_f32_16x16x32_bf16 v[12:15], v[144:147], v[212:215], v[12:15]
	v_mfma_f32_16x16x32_bf16 v[4:7], v[158:161], v[212:215], v[4:7]
	v_mfma_f32_16x16x32_bf16 v[60:63], v[154:157], v[186:189], v[60:63]
	v_mfma_f32_16x16x32_bf16 v[52:55], v[162:165], v[186:189], v[52:55]
	v_mfma_f32_16x16x32_bf16 v[44:47], v[154:157], v[194:197], v[44:47]
	v_mfma_f32_16x16x32_bf16 v[36:39], v[162:165], v[194:197], v[36:39]
	v_mfma_f32_16x16x32_bf16 v[28:31], v[154:157], v[202:205], v[28:31]
	v_mfma_f32_16x16x32_bf16 v[20:23], v[162:165], v[202:205], v[20:23]
	v_mfma_f32_16x16x32_bf16 v[12:15], v[154:157], v[216:219], v[12:15]
	v_mfma_f32_16x16x32_bf16 v[4:7], v[162:165], v[216:219], v[4:7]
	v_mfma_f32_16x16x32_bf16 v[56:59], v[166:169], v[182:185], v[56:59]
	v_mfma_f32_16x16x32_bf16 v[48:51], v[174:177], v[182:185], v[48:51]
	v_mfma_f32_16x16x32_bf16 v[40:43], v[166:169], v[190:193], v[40:43]
	v_mfma_f32_16x16x32_bf16 v[32:35], v[174:177], v[190:193], v[32:35]
	v_mfma_f32_16x16x32_bf16 v[24:27], v[166:169], v[198:201], v[24:27]
	v_mfma_f32_16x16x32_bf16 v[16:19], v[174:177], v[198:201], v[16:19]
	v_mfma_f32_16x16x32_bf16 v[8:11], v[166:169], v[212:215], v[8:11]
	v_mfma_f32_16x16x32_bf16 v[0:3], v[174:177], v[212:215], v[0:3]
	v_mfma_f32_16x16x32_bf16 v[56:59], v[170:173], v[186:189], v[56:59]
	v_mfma_f32_16x16x32_bf16 v[48:51], v[178:181], v[186:189], v[48:51]
	v_mfma_f32_16x16x32_bf16 v[40:43], v[170:173], v[194:197], v[40:43]
	v_mfma_f32_16x16x32_bf16 v[32:35], v[178:181], v[194:197], v[32:35]
	v_mfma_f32_16x16x32_bf16 v[24:27], v[170:173], v[202:205], v[24:27]
	v_mfma_f32_16x16x32_bf16 v[16:19], v[178:181], v[202:205], v[16:19]
	v_mfma_f32_16x16x32_bf16 v[8:11], v[170:173], v[216:219], v[8:11]
	v_mfma_f32_16x16x32_bf16 v[0:3], v[178:181], v[216:219], v[0:3]
	s_barrier
	s_add_i32 s48, s48, 2
	s_add_u32 s22, s22, 0x100
	s_addc_u32 s23, s23, 0
	s_add_u32 s46, s46, 0x100
	s_addc_u32 s47, s47, 0
	s_cmp_gt_u32 s48, 13
	s_cbranch_scc0 .LBB0_269
	s_branch .Lkp_exit_0
; #define PG8_STAGE(bufoff, gbase, voff) do { _Pragma("unroll") for (int _i = 0; _i < 2; ++_i) \
;         __builtin_amdgcn_global_load_lds((const unsigned*)((const char*)(gbase) + (voff)[_i]), (PG8_LAS unsigned*)(lds + (bufoff) + ldsw + _i * 8192), 16, 0, 0); } while (0)
; #define PG8_LDA(dst, b, h) do { _Pragma("unroll") for (int m = 0; m < 4; ++m) _Pragma("unroll") for (int k = 0; k < 2; ++k) dst[m][k] = *(const PG8_LAS bf16x8*)(lds + PG8_SA(b, h) + aoff + m * 2048 + k * 1024); } while (0)
; #define PG8_LDB(dst, b, h) do { _Pragma("unroll") for (int n = 0; n < 2; ++n) _Pragma("unroll") for (int k = 0; k < 2; ++k) dst[n][k] = *(const PG8_LAS bf16x8*)(lds + PG8_SB(b, h) + boff + n * 2048 + k * 1024); } while (0)
; #define PG8_MMA(ai, bj, At, Bt) do { __builtin_amdgcn_s_setprio(1); _Pragma("unroll") for (int m = 0; m < 4; ++m) _Pragma("unroll") for (int n = 0; n < 2; ++n) _Pragma("unroll") for (int k = 0; k < 2; ++k) \
;         acc[ai][bj][m][n] = __builtin_amdgcn_mfma_f32_16x16x32_bf16(Bt[n][k], At[m][k], acc[ai][bj][m][n], 0, 0, 0); __builtin_amdgcn_s_setprio(0); } while (0)
; #define PG8_WAIT_V(n) asm volatile("s_waitcnt vmcnt(" #n ")" ::: "memory")
; #define PG8_WAIT_L(n) asm volatile("s_waitcnt lgkmcnt(" #n ")" ::: "memory")
; #define PG8_BAR __builtin_amdgcn_s_barrier()
; #define PG8_SCHED __builtin_amdgcn_sched_barrier(0)
; template <class Epi, class Sched, bool ALIGN_EPI = false, bool SP2 = false>
; __device__ __forceinline__ void gemm_phase(PG8_LAS unsigned char* lds, const Gemm g, const Sched& S, const Epi& E, const int wid) {
;     ...
;             PG8_LDB(B0, 0, 0); PG8_LDB(B1, 0, 1); PG8_SCHED; PG8_LDA(At, 0, 0); PG8_STAGE(PG8_SA(1, 1), a1 + hstep, voffA);
;             PG8_WAIT_V(8); PG8_WAIT_L(0); PG8_BAR; PG8_MMA(0, 0, At, B0); PG8_MMA(0, 1, At, B1); PG8_BAR; PG8_SCHED;
;             PG8_LDA(At, 0, 1); PG8_STAGE(PG8_SB(0, 0), b2, voffB); PG8_STAGE(PG8_SB(0, 1), b2 + hstep, voffB); PG8_STAGE(PG8_SA(0, 0), a2, voffA);
;             PG8_WAIT_V(8); PG8_WAIT_L(0); PG8_BAR; PG8_MMA(1, 0, At, B0); PG8_MMA(1, 1, At, B1); PG8_BAR; PG8_SCHED;
.LBB0_269:
	ds_read_b128 v[144:147], v151
	ds_read_b128 v[154:157], v151 offset:1024
	ds_read_b128 v[158:161], v151 offset:2048
	ds_read_b128 v[162:165], v151 offset:3072
	ds_read_b128 v[166:169], v152
	ds_read_b128 v[170:173], v152 offset:1024
	ds_read_b128 v[174:177], v152 offset:2048
	ds_read_b128 v[178:181], v152 offset:3072
	s_add_u32 s24, s22, 0xfffc0080
	s_addc_u32 s25, s23, -1
	s_cmp_eq_u32 s48, 12
	s_cselect_b32 s27, s15, s25
	s_cselect_b32 s26, s44, s24
	s_cselect_b32 s25, s13, s47
	s_cselect_b32 s24, s45, s46
	v_lshl_add_u64 v[206:207], s[22:23], 0, v[136:137]
	s_add_i32 m0, s21, 0xc000
	ds_read_b128 v[182:185], v153
	ds_read_b128 v[186:189], v153 offset:1024
	ds_read_b128 v[190:193], v153 offset:2048
	ds_read_b128 v[194:197], v153 offset:3072
	ds_read_b128 v[198:201], v153 offset:4096
	ds_read_b128 v[202:205], v153 offset:5120
	ds_read_b128 v[212:215], v153 offset:6144
	ds_read_b128 v[216:219], v153 offset:7168
	global_load_lds_dwordx4 v[206:207], off
	v_lshl_add_u64 v[206:207], s[22:23], 0, v[138:139]
	s_add_i32 m0, s21, 0xe000
	s_nop 0
	global_load_lds_dwordx4 v[206:207], off
	s_waitcnt vmcnt(8)
	s_waitcnt lgkmcnt(0)
	s_barrier
	v_mfma_f32_16x16x32_bf16 v[124:127], v[144:147], v[182:185], v[124:127]
	v_mfma_f32_16x16x32_bf16 v[116:119], v[158:161], v[182:185], v[116:119]
	v_mfma_f32_16x16x32_bf16 v[108:111], v[144:147], v[190:193], v[108:111]
	v_mfma_f32_16x16x32_bf16 v[100:103], v[158:161], v[190:193], v[100:103]
	v_mfma_f32_16x16x32_bf16 v[92:95], v[144:147], v[198:201], v[92:95]
	v_mfma_f32_16x16x32_bf16 v[84:87], v[158:161], v[198:201], v[84:87]
	v_mfma_f32_16x16x32_bf16 v[76:79], v[144:147], v[212:215], v[76:79]
	v_mfma_f32_16x16x32_bf16 v[68:71], v[158:161], v[212:215], v[68:71]
	v_mfma_f32_16x16x32_bf16 v[124:127], v[154:157], v[186:189], v[124:127]
	v_mfma_f32_16x16x32_bf16 v[116:119], v[162:165], v[186:189], v[116:119]
	v_mfma_f32_16x16x32_bf16 v[108:111], v[154:157], v[194:197], v[108:111]
	v_mfma_f32_16x16x32_bf16 v[100:103], v[162:165], v[194:197], v[100:103]
	v_mfma_f32_16x16x32_bf16 v[92:95], v[154:157], v[202:205], v[92:95]
	v_mfma_f32_16x16x32_bf16 v[84:87], v[162:165], v[202:205], v[84:87]
	v_mfma_f32_16x16x32_bf16 v[76:79], v[154:157], v[216:219], v[76:79]
	v_mfma_f32_16x16x32_bf16 v[68:71], v[162:165], v[216:219], v[68:71]
	v_mfma_f32_16x16x32_bf16 v[120:123], v[166:169], v[182:185], v[120:123]
	v_mfma_f32_16x16x32_bf16 v[112:115], v[174:177], v[182:185], v[112:115]
	v_mfma_f32_16x16x32_bf16 v[104:107], v[166:169], v[190:193], v[104:107]
	v_mfma_f32_16x16x32_bf16 v[96:99], v[174:177], v[190:193], v[96:99]
	v_mfma_f32_16x16x32_bf16 v[88:91], v[166:169], v[198:201], v[88:91]
	v_mfma_f32_16x16x32_bf16 v[80:83], v[174:177], v[198:201], v[80:83]
	v_mfma_f32_16x16x32_bf16 v[72:75], v[166:169], v[212:215], v[72:75]
	v_mfma_f32_16x16x32_bf16 v[64:67], v[174:177], v[212:215], v[64:67]
	v_mfma_f32_16x16x32_bf16 v[120:123], v[170:173], v[186:189], v[120:123]
	v_mfma_f32_16x16x32_bf16 v[112:115], v[178:181], v[186:189], v[112:115]
	v_mfma_f32_16x16x32_bf16 v[104:107], v[170:173], v[194:197], v[104:107]
	v_mfma_f32_16x16x32_bf16 v[96:99], v[178:181], v[194:197], v[96:99]
	v_mfma_f32_16x16x32_bf16 v[88:91], v[170:173], v[202:205], v[88:91]
	v_mfma_f32_16x16x32_bf16 v[80:83], v[178:181], v[202:205], v[80:83]
	v_mfma_f32_16x16x32_bf16 v[72:75], v[170:173], v[216:219], v[72:75]
	v_mfma_f32_16x16x32_bf16 v[64:67], v[178:181], v[216:219], v[64:67]
	s_barrier
	s_add_i32 s49, s40, s9
	v_lshl_add_u64 v[206:207], s[24:25], 0, v[132:133]
	s_mov_b32 m0, s49
	ds_read_b128 v[182:185], v153 offset:16384
	ds_read_b128 v[186:189], v153 offset:17408
	ds_read_b128 v[190:193], v153 offset:18432
	ds_read_b128 v[194:197], v153 offset:19456
	ds_read_b128 v[198:201], v153 offset:20480
	ds_read_b128 v[202:205], v153 offset:21504
	ds_read_b128 v[212:215], v153 offset:22528
	ds_read_b128 v[216:219], v153 offset:23552
	global_load_lds_dwordx4 v[206:207], off
	s_add_i32 m0, s49, 0x2000
	s_add_u32 s50, s24, 0x40000
	v_lshl_add_u64 v[220:221], s[24:25], 0, v[128:129]
	s_addc_u32 s51, s25, 0
	s_add_i32 s49, s41, s9
	global_load_lds_dwordx4 v[220:221], off
	v_lshl_add_u64 v[222:223], s[50:51], 0, v[132:133]
	s_mov_b32 m0, s49
	v_lshl_add_u64 v[224:225], s[26:27], 0, v[130:131]
	global_load_lds_dwordx4 v[222:223], off
	v_lshl_add_u64 v[222:223], s[50:51], 0, v[128:129]
	s_add_i32 m0, s49, 0x2000
	s_nop 0
	global_load_lds_dwordx4 v[222:223], off
	v_lshl_add_u64 v[222:223], s[26:27], 0, v[134:135]
	s_mov_b32 m0, s21
	s_nop 0
	global_load_lds_dwordx4 v[222:223], off
	s_mov_b32 m0, s30
	s_nop 0
	global_load_lds_dwordx4 v[224:225], off
	s_waitcnt vmcnt(8)
	s_waitcnt lgkmcnt(0)
	s_barrier
; #define PG8_STAGE(bufoff, gbase, voff) do { _Pragma("unroll") for (int _i = 0; _i < 2; ++_i) \
;         __builtin_amdgcn_global_load_lds((const unsigned*)((const char*)(gbase) + (voff)[_i]), (PG8_LAS unsigned*)(lds + (bufoff) + ldsw + _i * 8192), 16, 0, 0); } while (0)
; #define PG8_LDA(dst, b, h) do { _Pragma("unroll") for (int m = 0; m < 4; ++m) _Pragma("unroll") for (int k = 0; k < 2; ++k) dst[m][k] = *(const PG8_LAS bf16x8*)(lds + PG8_SA(b, h) + aoff + m * 2048 + k * 1024); } while (0)
; #define PG8_LDB(dst, b, h) do { _Pragma("unroll") for (int n = 0; n < 2; ++n) _Pragma("unroll") for (int k = 0; k < 2; ++k) dst[n][k] = *(const PG8_LAS bf16x8*)(lds + PG8_SB(b, h) + boff + n * 2048 + k * 1024); } while (0)
; #define PG8_MMA(ai, bj, At, Bt) do { __builtin_amdgcn_s_setprio(1); _Pragma("unroll") for (int m = 0; m < 4; ++m) _Pragma("unroll") for (int n = 0; n < 2; ++n) _Pragma("unroll") for (int k = 0; k < 2; ++k) \
;         acc[ai][bj][m][n] = __builtin_amdgcn_mfma_f32_16x16x32_bf16(Bt[n][k], At[m][k], acc[ai][bj][m][n], 0, 0, 0); __builtin_amdgcn_s_setprio(0); } while (0)
; #define PG8_WAIT_V(n) asm volatile("s_waitcnt vmcnt(" #n ")" ::: "memory")
; #define PG8_WAIT_L(n) asm volatile("s_waitcnt lgkmcnt(" #n ")" ::: "memory")
; #define PG8_BAR __builtin_amdgcn_s_barrier()
; #define PG8_SCHED __builtin_amdgcn_sched_barrier(0)
; template <class Epi, class Sched, bool ALIGN_EPI = false, bool SP2 = false>
; __device__ __forceinline__ void gemm_phase(PG8_LAS unsigned char* lds, const Gemm g, const Sched& S, const Epi& E, const int wid) {
;     ...
;             PG8_LDA(At, 0, 1); PG8_STAGE(PG8_SB(0, 0), b2, voffB); PG8_STAGE(PG8_SB(0, 1), b2 + hstep, voffB); PG8_STAGE(PG8_SA(0, 0), a2, voffA);
;             PG8_WAIT_V(8); PG8_WAIT_L(0); PG8_BAR; PG8_MMA(1, 0, At, B0); PG8_MMA(1, 1, At, B1); PG8_BAR; PG8_SCHED;
;             PG8_LDB(B0, 1, 0); PG8_LDB(B1, 1, 1); PG8_SCHED; PG8_LDA(At, 1, 0); PG8_STAGE(PG8_SA(0, 1), a2 + hstep, voffA);
;             PG8_WAIT_V(8); PG8_WAIT_L(0); PG8_BAR; PG8_MMA(0, 0, At, B0); PG8_MMA(0, 1, At, B1); PG8_BAR; PG8_SCHED;
;             PG8_LDA(At, 1, 1); PG8_STAGE(PG8_SB(1, 0), b3, voffB); PG8_STAGE(PG8_SB(1, 1), b3 + hstep, voffB); PG8_STAGE(PG8_SA(1, 0), a3, voffA);
	v_mfma_f32_16x16x32_bf16 v[60:63], v[144:147], v[182:185], v[60:63]
	v_mfma_f32_16x16x32_bf16 v[52:55], v[158:161], v[182:185], v[52:55]
	v_mfma_f32_16x16x32_bf16 v[44:47], v[144:147], v[190:193], v[44:47]
	v_mfma_f32_16x16x32_bf16 v[36:39], v[158:161], v[190:193], v[36:39]
	v_mfma_f32_16x16x32_bf16 v[28:31], v[144:147], v[198:201], v[28:31]
	v_mfma_f32_16x16x32_bf16 v[20:23], v[158:161], v[198:201], v[20:23]
	v_mfma_f32_16x16x32_bf16 v[12:15], v[144:147], v[212:215], v[12:15]
	v_mfma_f32_16x16x32_bf16 v[4:7], v[158:161], v[212:215], v[4:7]
	v_mfma_f32_16x16x32_bf16 v[60:63], v[154:157], v[186:189], v[60:63]
	v_mfma_f32_16x16x32_bf16 v[52:55], v[162:165], v[186:189], v[52:55]
	v_mfma_f32_16x16x32_bf16 v[44:47], v[154:157], v[194:197], v[44:47]
	v_mfma_f32_16x16x32_bf16 v[36:39], v[162:165], v[194:197], v[36:39]
	v_mfma_f32_16x16x32_bf16 v[28:31], v[154:157], v[202:205], v[28:31]
	v_mfma_f32_16x16x32_bf16 v[20:23], v[162:165], v[202:205], v[20:23]
	v_mfma_f32_16x16x32_bf16 v[12:15], v[154:157], v[216:219], v[12:15]
	v_mfma_f32_16x16x32_bf16 v[4:7], v[162:165], v[216:219], v[4:7]
	v_mfma_f32_16x16x32_bf16 v[56:59], v[166:169], v[182:185], v[56:59]
	v_mfma_f32_16x16x32_bf16 v[48:51], v[174:177], v[182:185], v[48:51]
	v_mfma_f32_16x16x32_bf16 v[40:43], v[166:169], v[190:193], v[40:43]
	v_mfma_f32_16x16x32_bf16 v[32:35], v[174:177], v[190:193], v[32:35]
	v_mfma_f32_16x16x32_bf16 v[24:27], v[166:169], v[198:201], v[24:27]
	v_mfma_f32_16x16x32_bf16 v[16:19], v[174:177], v[198:201], v[16:19]
	v_mfma_f32_16x16x32_bf16 v[8:11], v[166:169], v[212:215], v[8:11]
	v_mfma_f32_16x16x32_bf16 v[0:3], v[174:177], v[212:215], v[0:3]
	v_mfma_f32_16x16x32_bf16 v[56:59], v[170:173], v[186:189], v[56:59]
	v_mfma_f32_16x16x32_bf16 v[48:51], v[178:181], v[186:189], v[48:51]
	v_mfma_f32_16x16x32_bf16 v[40:43], v[170:173], v[194:197], v[40:43]
	v_mfma_f32_16x16x32_bf16 v[32:35], v[178:181], v[194:197], v[32:35]
	v_mfma_f32_16x16x32_bf16 v[24:27], v[170:173], v[202:205], v[24:27]
	v_mfma_f32_16x16x32_bf16 v[16:19], v[178:181], v[202:205], v[16:19]
	v_mfma_f32_16x16x32_bf16 v[8:11], v[170:173], v[216:219], v[8:11]
	v_mfma_f32_16x16x32_bf16 v[0:3], v[178:181], v[216:219], v[0:3]
	s_barrier
	s_add_i32 s49, 0, 0x18000
	s_add_i32 s50, 0, 0x1c000
	v_add_u32_e32 v162, s49, v149
	v_add_u32_e32 v178, s50, v149
	ds_read_b128 v[144:147], v162
	ds_read_b128 v[154:157], v162 offset:1024
	ds_read_b128 v[158:161], v162 offset:2048
	ds_read_b128 v[162:165], v162 offset:3072
	ds_read_b128 v[166:169], v178
	ds_read_b128 v[170:173], v178 offset:1024
	ds_read_b128 v[174:177], v178 offset:2048
	ds_read_b128 v[178:181], v178 offset:3072
	s_add_u32 s26, s26, 0x40000
	s_addc_u32 s27, s27, 0
	s_mov_b32 m0, s31
	v_lshl_add_u64 v[226:227], s[26:27], 0, v[134:135]
	ds_read_b128 v[182:185], v153 offset:32768
	ds_read_b128 v[186:189], v153 offset:33792
	ds_read_b128 v[190:193], v153 offset:34816
	ds_read_b128 v[194:197], v153 offset:35840
	ds_read_b128 v[198:201], v153 offset:36864
	ds_read_b128 v[202:205], v153 offset:37888
	ds_read_b128 v[212:215], v153 offset:38912
	ds_read_b128 v[216:219], v153 offset:39936
	global_load_lds_dwordx4 v[226:227], off
	v_lshl_add_u64 v[226:227], s[26:27], 0, v[130:131]
	s_mov_b32 m0, s33
	s_nop 0
	global_load_lds_dwordx4 v[226:227], off
	s_waitcnt vmcnt(8)
	s_waitcnt lgkmcnt(0)
	s_barrier
	v_mfma_f32_16x16x32_bf16 v[124:127], v[144:147], v[182:185], v[124:127]
	v_mfma_f32_16x16x32_bf16 v[116:119], v[158:161], v[182:185], v[116:119]
	v_mfma_f32_16x16x32_bf16 v[108:111], v[144:147], v[190:193], v[108:111]
	v_mfma_f32_16x16x32_bf16 v[100:103], v[158:161], v[190:193], v[100:103]
	v_mfma_f32_16x16x32_bf16 v[92:95], v[144:147], v[198:201], v[92:95]
	v_mfma_f32_16x16x32_bf16 v[84:87], v[158:161], v[198:201], v[84:87]
	v_mfma_f32_16x16x32_bf16 v[76:79], v[144:147], v[212:215], v[76:79]
	v_mfma_f32_16x16x32_bf16 v[68:71], v[158:161], v[212:215], v[68:71]
	v_mfma_f32_16x16x32_bf16 v[124:127], v[154:157], v[186:189], v[124:127]
	v_mfma_f32_16x16x32_bf16 v[116:119], v[162:165], v[186:189], v[116:119]
	v_mfma_f32_16x16x32_bf16 v[108:111], v[154:157], v[194:197], v[108:111]
	v_mfma_f32_16x16x32_bf16 v[100:103], v[162:165], v[194:197], v[100:103]
	v_mfma_f32_16x16x32_bf16 v[92:95], v[154:157], v[202:205], v[92:95]
	v_mfma_f32_16x16x32_bf16 v[84:87], v[162:165], v[202:205], v[84:87]
	v_mfma_f32_16x16x32_bf16 v[76:79], v[154:157], v[216:219], v[76:79]
	v_mfma_f32_16x16x32_bf16 v[68:71], v[162:165], v[216:219], v[68:71]
	v_mfma_f32_16x16x32_bf16 v[120:123], v[166:169], v[182:185], v[120:123]
	v_mfma_f32_16x16x32_bf16 v[112:115], v[174:177], v[182:185], v[112:115]
	v_mfma_f32_16x16x32_bf16 v[104:107], v[166:169], v[190:193], v[104:107]
	v_mfma_f32_16x16x32_bf16 v[96:99], v[174:177], v[190:193], v[96:99]
	v_mfma_f32_16x16x32_bf16 v[88:91], v[166:169], v[198:201], v[88:91]
	v_mfma_f32_16x16x32_bf16 v[80:83], v[174:177], v[198:201], v[80:83]
	v_mfma_f32_16x16x32_bf16 v[72:75], v[166:169], v[212:215], v[72:75]
	v_mfma_f32_16x16x32_bf16 v[64:67], v[174:177], v[212:215], v[64:67]
	v_mfma_f32_16x16x32_bf16 v[120:123], v[170:173], v[186:189], v[120:123]
	v_mfma_f32_16x16x32_bf16 v[112:115], v[178:181], v[186:189], v[112:115]
	v_mfma_f32_16x16x32_bf16 v[104:107], v[170:173], v[194:197], v[104:107]
	v_mfma_f32_16x16x32_bf16 v[96:99], v[178:181], v[194:197], v[96:99]
	v_mfma_f32_16x16x32_bf16 v[88:91], v[170:173], v[202:205], v[88:91]
	v_mfma_f32_16x16x32_bf16 v[80:83], v[178:181], v[202:205], v[80:83]
	v_mfma_f32_16x16x32_bf16 v[72:75], v[170:173], v[216:219], v[72:75]
	v_mfma_f32_16x16x32_bf16 v[64:67], v[178:181], v[216:219], v[64:67]
	s_barrier
; #define PG8_STAGE(bufoff, gbase, voff) do { _Pragma("unroll") for (int _i = 0; _i < 2; ++_i) \
;         __builtin_amdgcn_global_load_lds((const unsigned*)((const char*)(gbase) + (voff)[_i]), (PG8_LAS unsigned*)(lds + (bufoff) + ldsw + _i * 8192), 16, 0, 0); } while (0)
; #define PG8_LDA(dst, b, h) do { _Pragma("unroll") for (int m = 0; m < 4; ++m) _Pragma("unroll") for (int k = 0; k < 2; ++k) dst[m][k] = *(const PG8_LAS bf16x8*)(lds + PG8_SA(b, h) + aoff + m * 2048 + k * 1024); } while (0)
; #define PG8_WAIT_V(n) asm volatile("s_waitcnt vmcnt(" #n ")" ::: "memory")
; #define PG8_WAIT_L(n) asm volatile("s_waitcnt lgkmcnt(" #n ")" ::: "memory")
; #define PG8_BAR __builtin_amdgcn_s_barrier()
; template <class Epi, class Sched, bool ALIGN_EPI = false, bool SP2 = false>
; __device__ __forceinline__ void gemm_phase(PG8_LAS unsigned char* lds, const Gemm g, const Sched& S, const Epi& E, const int wid) {
;     ...
;         for (int t = 0; t < nt; t += 2) {
;             const bool last = (t == nt - 2);
;             const char* a1 = cA + (size_t)(t + 1) * kstep;
;             const char* a2 = last ? nA : cA + (size_t)(t + 2) * kstep; const char* b2 = last ? nB : cB + (size_t)(t + 2) * kstep;
;             const char* a3 = a2 + kstep; const char* b3 = b2 + kstep;
;             if (last && has_next) S.a_ready(nxt);
;             if constexpr (SP2) {
;             PG8_LDB(B0, 0, 0); PG8_LDB(B1, 0, 1); PG8_SCHED; PG8_LDA(At, 0, 0); PG8_STAGE(PG8_SA(1, 1), a1 + hstep, voffA);
;             PG8_WAIT_V(8); PG8_WAIT_L(0); PG8_BAR; PG8_MMA(0, 0, At, B0); PG8_MMA(0, 1, At, B1); PG8_BAR; PG8_SCHED;
;             PG8_LDA(At, 0, 1); PG8_STAGE(PG8_SB(0, 0), b2, voffB); PG8_STAGE(PG8_SB(0, 1), b2 + hstep, voffB); PG8_STAGE(PG8_SA(0, 0), a2, voffA);
;             PG8_WAIT_V(8); PG8_WAIT_L(0); PG8_BAR; PG8_MMA(1, 0, At, B0); PG8_MMA(1, 1, At, B1); PG8_BAR; PG8_SCHED;
;             PG8_LDB(B0, 1, 0); PG8_LDB(B1, 1, 1); PG8_SCHED; PG8_LDA(At, 1, 0); PG8_STAGE(PG8_SA(0, 1), a2 + hstep, voffA);
;             PG8_WAIT_V(8); PG8_WAIT_L(0); PG8_BAR; PG8_MMA(0, 0, At, B0); PG8_MMA(0, 1, At, B1); PG8_BAR; PG8_SCHED;
;             PG8_LDA(At, 1, 1); PG8_STAGE(PG8_SB(1, 0), b3, voffB); PG8_STAGE(PG8_SB(1, 1), b3 + hstep, voffB); PG8_STAGE(PG8_SA(1, 0), a3, voffA);
;             PG8_WAIT_V(8); PG8_WAIT_L(0); PG8_BAR; PG8_MMA(1, 0, At, B0); PG8_MMA(1, 1, At, B1); PG8_BAR; PG8_SCHED;
	s_add_i32 s26, s49, s9
	v_lshl_add_u64 v[206:207], v[206:207], 0, s[6:7]
	s_mov_b32 m0, s26
	ds_read_b128 v[182:185], v153 offset:49152
	ds_read_b128 v[186:189], v153 offset:50176
	ds_read_b128 v[190:193], v153 offset:51200
	ds_read_b128 v[194:197], v153 offset:52224
	ds_read_b128 v[198:201], v153 offset:53248
	ds_read_b128 v[202:205], v153 offset:54272
	ds_read_b128 v[212:215], v153 offset:55296
	ds_read_b128 v[216:219], v153 offset:56320
	global_load_lds_dwordx4 v[206:207], off
	s_add_i32 m0, s26, 0x2000
	s_add_u32 s24, s24, 0x40080
	v_lshl_add_u64 v[206:207], v[220:221], 0, s[6:7]
	s_addc_u32 s25, s25, 0
	s_add_i32 s26, s50, s9
	global_load_lds_dwordx4 v[206:207], off
	v_lshl_add_u64 v[206:207], s[24:25], 0, v[132:133]
	s_mov_b32 m0, s26
	s_nop 0
	global_load_lds_dwordx4 v[206:207], off
	v_lshl_add_u64 v[206:207], s[24:25], 0, v[128:129]
	s_add_i32 m0, s26, 0x2000
	s_nop 0
	global_load_lds_dwordx4 v[206:207], off
	v_lshl_add_u64 v[206:207], v[222:223], 0, s[6:7]
	s_mov_b32 m0, s38
	s_nop 0
	global_load_lds_dwordx4 v[206:207], off
	v_lshl_add_u64 v[206:207], v[224:225], 0, s[6:7]
	s_mov_b32 m0, s39
	s_nop 0
	global_load_lds_dwordx4 v[206:207], off
	s_waitcnt vmcnt(8)
	s_waitcnt lgkmcnt(0)
	s_barrier
	v_mfma_f32_16x16x32_bf16 v[60:63], v[144:147], v[182:185], v[60:63]
	v_mfma_f32_16x16x32_bf16 v[52:55], v[158:161], v[182:185], v[52:55]
	v_mfma_f32_16x16x32_bf16 v[44:47], v[144:147], v[190:193], v[44:47]
	v_mfma_f32_16x16x32_bf16 v[36:39], v[158:161], v[190:193], v[36:39]
	v_mfma_f32_16x16x32_bf16 v[28:31], v[144:147], v[198:201], v[28:31]
	v_mfma_f32_16x16x32_bf16 v[20:23], v[158:161], v[198:201], v[20:23]
	v_mfma_f32_16x16x32_bf16 v[12:15], v[144:147], v[212:215], v[12:15]
	v_mfma_f32_16x16x32_bf16 v[4:7], v[158:161], v[212:215], v[4:7]
	v_mfma_f32_16x16x32_bf16 v[60:63], v[154:157], v[186:189], v[60:63]
	v_mfma_f32_16x16x32_bf16 v[52:55], v[162:165], v[186:189], v[52:55]
	v_mfma_f32_16x16x32_bf16 v[44:47], v[154:157], v[194:197], v[44:47]
	v_mfma_f32_16x16x32_bf16 v[36:39], v[162:165], v[194:197], v[36:39]
	v_mfma_f32_16x16x32_bf16 v[28:31], v[154:157], v[202:205], v[28:31]
	v_mfma_f32_16x16x32_bf16 v[20:23], v[162:165], v[202:205], v[20:23]
	v_mfma_f32_16x16x32_bf16 v[12:15], v[154:157], v[216:219], v[12:15]
	v_mfma_f32_16x16x32_bf16 v[4:7], v[162:165], v[216:219], v[4:7]
	v_mfma_f32_16x16x32_bf16 v[56:59], v[166:169], v[182:185], v[56:59]
	v_mfma_f32_16x16x32_bf16 v[48:51], v[174:177], v[182:185], v[48:51]
	v_mfma_f32_16x16x32_bf16 v[40:43], v[166:169], v[190:193], v[40:43]
	v_mfma_f32_16x16x32_bf16 v[32:35], v[174:177], v[190:193], v[32:35]
	v_mfma_f32_16x16x32_bf16 v[24:27], v[166:169], v[198:201], v[24:27]
	v_mfma_f32_16x16x32_bf16 v[16:19], v[174:177], v[198:201], v[16:19]
	v_mfma_f32_16x16x32_bf16 v[8:11], v[166:169], v[212:215], v[8:11]
	v_mfma_f32_16x16x32_bf16 v[0:3], v[174:177], v[212:215], v[0:3]
	v_mfma_f32_16x16x32_bf16 v[56:59], v[170:173], v[186:189], v[56:59]
	v_mfma_f32_16x16x32_bf16 v[48:51], v[178:181], v[186:189], v[48:51]
	v_mfma_f32_16x16x32_bf16 v[40:43], v[170:173], v[194:197], v[40:43]
	v_mfma_f32_16x16x32_bf16 v[32:35], v[178:181], v[194:197], v[32:35]
	v_mfma_f32_16x16x32_bf16 v[24:27], v[170:173], v[202:205], v[24:27]
	v_mfma_f32_16x16x32_bf16 v[16:19], v[178:181], v[202:205], v[16:19]
	v_mfma_f32_16x16x32_bf16 v[8:11], v[170:173], v[216:219], v[8:11]
	v_mfma_f32_16x16x32_bf16 v[0:3], v[178:181], v[216:219], v[0:3]
	s_barrier
	s_add_i32 s48, s48, 2
	s_add_u32 s22, s22, 0x100
	s_addc_u32 s23, s23, 0
	s_add_u32 s46, s46, 0x100
	s_addc_u32 s47, s47, 0
	s_cmp_gt_u32 s48, 13
	s_cbranch_scc0 .LBB0_269

; #define PG8_STAGE(bufoff, gbase, voff) do { _Pragma("unroll") for (int _i = 0; _i < 2; ++_i) \
;         __builtin_amdgcn_global_load_lds((const unsigned*)((const char*)(gbase) + (voff)[_i]), (PG8_LAS unsigned*)(lds + (bufoff) + ldsw + _i * 8192), 16, 0, 0); } while (0)
; #define PG8_LDA(dst, b, h) do { _Pragma("unroll") for (int m = 0; m < 4; ++m) _Pragma("unroll") for (int k = 0; k < 2; ++k) dst[m][k] = *(const PG8_LAS bf16x8*)(lds + PG8_SA(b, h) + aoff + m * 2048 + k * 1024); } while (0)
; #define PG8_LDB(dst, b, h) do { _Pragma("unroll") for (int n = 0; n < 2; ++n) _Pragma("unroll") for (int k = 0; k < 2; ++k) dst[n][k] = *(const PG8_LAS bf16x8*)(lds + PG8_SB(b, h) + boff + n * 2048 + k * 1024); } while (0)
; #define PG8_MMA(ai, bj, At, Bt) do { __builtin_amdgcn_s_setprio(1); _Pragma("unroll") for (int m = 0; m < 4; ++m) _Pragma("unroll") for (int n = 0; n < 2; ++n) _Pragma("unroll") for (int k = 0; k < 2; ++k) \
;         acc[ai][bj][m][n] = __builtin_amdgcn_mfma_f32_16x16x32_bf16(Bt[n][k], At[m][k], acc[ai][bj][m][n], 0, 0, 0); __builtin_amdgcn_s_setprio(0); } while (0)
; #define PG8_WAIT_V(n) asm volatile("s_waitcnt vmcnt(" #n ")" ::: "memory")
; #define PG8_WAIT_L(n) asm volatile("s_waitcnt lgkmcnt(" #n ")" ::: "memory")
; #define PG8_BAR __builtin_amdgcn_s_barrier()
; #define PG8_SCHED __builtin_amdgcn_sched_barrier(0)
; template <class Epi, class Sched, bool ALIGN_EPI = false, bool SP2 = false>
; __device__ __forceinline__ void gemm_phase(PG8_LAS unsigned char* lds, const Gemm g, const Sched& S, const Epi& E, const int wid) {
;     ...
;             PG8_LDB(B0, 0, 0); PG8_LDB(B1, 0, 1); PG8_SCHED; PG8_LDA(At, 0, 0); PG8_STAGE(PG8_SA(1, 1), a1 + hstep, voffA);
;             PG8_WAIT_V(8); PG8_WAIT_L(0); PG8_BAR; PG8_MMA(0, 0, At, B0); PG8_MMA(0, 1, At, B1); PG8_BAR; PG8_SCHED;
;             PG8_LDA(At, 0, 1); PG8_STAGE(PG8_SB(0, 0), b2, voffB); PG8_STAGE(PG8_SB(0, 1), b2 + hstep, voffB); PG8_STAGE(PG8_SA(0, 0), a2, voffA);
;             PG8_WAIT_V(8); PG8_WAIT_L(0); PG8_BAR; PG8_MMA(1, 0, At, B0); PG8_MMA(1, 1, At, B1); PG8_BAR; PG8_SCHED;
.LBB0_756:
	v_add_u32_e32 v151, s35, v149
	ds_read_b128 v[152:155], v151
	ds_read_b128 v[156:159], v151 offset:1024
	ds_read_b128 v[160:163], v151 offset:2048
	ds_read_b128 v[164:167], v151 offset:3072
	v_add_u32_e32 v151, s38, v149
	s_add_u32 s16, s2, s14
	ds_read_b128 v[168:171], v151
	ds_read_b128 v[172:175], v151 offset:1024
	ds_read_b128 v[176:179], v151 offset:2048
	ds_read_b128 v[180:183], v151 offset:3072
	s_addc_u32 s17, s3, s15
	s_add_u32 s16, s16, 0x100
	s_addc_u32 s17, s17, 0
	s_add_u32 s45, s42, s14
	s_addc_u32 s46, s43, s15
	s_cmpk_eq_i32 s14, 0x1500
	s_cselect_b32 s19, s13, s17
	s_cselect_b32 s18, s12, s16
	s_cselect_b32 s17, s9, s46
	s_cselect_b32 s16, s8, s45
	v_lshl_add_u64 v[206:207], v[144:145], 0, s[14:15]
	s_add_i32 m0, s25, 0xc000
	ds_read_b128 v[184:187], v150
	ds_read_b128 v[188:191], v150 offset:1024
	ds_read_b128 v[194:197], v150 offset:2048
	ds_read_b128 v[198:201], v150 offset:3072
	ds_read_b128 v[202:205], v150 offset:4096
	ds_read_b128 v[212:215], v150 offset:5120
	ds_read_b128 v[216:219], v150 offset:6144
	ds_read_b128 v[220:223], v150 offset:7168
	global_load_lds_dwordx4 v[206:207], off
	v_lshl_add_u64 v[206:207], v[146:147], 0, s[14:15]
	s_add_i32 m0, s25, 0xe000
	s_nop 0
	global_load_lds_dwordx4 v[206:207], off
	s_waitcnt vmcnt(8)
	s_waitcnt lgkmcnt(0)
	s_barrier
	v_mfma_f32_16x16x32_bf16 v[120:123], v[152:155], v[184:187], v[120:123]
	v_mfma_f32_16x16x32_bf16 v[124:127], v[160:163], v[184:187], v[124:127]
	v_mfma_f32_16x16x32_bf16 v[108:111], v[152:155], v[194:197], v[108:111]
	v_mfma_f32_16x16x32_bf16 v[116:119], v[160:163], v[194:197], v[116:119]
	v_mfma_f32_16x16x32_bf16 v[92:95], v[152:155], v[202:205], v[92:95]
	v_mfma_f32_16x16x32_bf16 v[112:115], v[160:163], v[202:205], v[112:115]
	v_mfma_f32_16x16x32_bf16 v[72:75], v[152:155], v[216:219], v[72:75]
	v_mfma_f32_16x16x32_bf16 v[100:103], v[160:163], v[216:219], v[100:103]
	v_mfma_f32_16x16x32_bf16 v[120:123], v[156:159], v[188:191], v[120:123]
	v_mfma_f32_16x16x32_bf16 v[124:127], v[164:167], v[188:191], v[124:127]
	v_mfma_f32_16x16x32_bf16 v[108:111], v[156:159], v[198:201], v[108:111]
	v_mfma_f32_16x16x32_bf16 v[116:119], v[164:167], v[198:201], v[116:119]
	v_mfma_f32_16x16x32_bf16 v[92:95], v[156:159], v[212:215], v[92:95]
	v_mfma_f32_16x16x32_bf16 v[112:115], v[164:167], v[212:215], v[112:115]
	v_mfma_f32_16x16x32_bf16 v[72:75], v[156:159], v[220:223], v[72:75]
	v_mfma_f32_16x16x32_bf16 v[100:103], v[164:167], v[220:223], v[100:103]
	v_mfma_f32_16x16x32_bf16 v[104:107], v[168:171], v[184:187], v[104:107]
	v_mfma_f32_16x16x32_bf16 v[88:91], v[176:179], v[184:187], v[88:91]
	v_mfma_f32_16x16x32_bf16 v[96:99], v[168:171], v[194:197], v[96:99]
	v_mfma_f32_16x16x32_bf16 v[76:79], v[176:179], v[194:197], v[76:79]
	v_mfma_f32_16x16x32_bf16 v[84:87], v[168:171], v[202:205], v[84:87]
	v_mfma_f32_16x16x32_bf16 v[68:71], v[176:179], v[202:205], v[68:71]
	v_mfma_f32_16x16x32_bf16 v[80:83], v[168:171], v[216:219], v[80:83]
	v_mfma_f32_16x16x32_bf16 v[64:67], v[176:179], v[216:219], v[64:67]
	v_mfma_f32_16x16x32_bf16 v[104:107], v[172:175], v[188:191], v[104:107]
	v_mfma_f32_16x16x32_bf16 v[88:91], v[180:183], v[188:191], v[88:91]
	v_mfma_f32_16x16x32_bf16 v[96:99], v[172:175], v[198:201], v[96:99]
	v_mfma_f32_16x16x32_bf16 v[76:79], v[180:183], v[198:201], v[76:79]
	v_mfma_f32_16x16x32_bf16 v[84:87], v[172:175], v[212:215], v[84:87]
	v_mfma_f32_16x16x32_bf16 v[68:71], v[180:183], v[212:215], v[68:71]
	v_mfma_f32_16x16x32_bf16 v[80:83], v[172:175], v[220:223], v[80:83]
	v_mfma_f32_16x16x32_bf16 v[64:67], v[180:183], v[220:223], v[64:67]
	s_barrier
	s_add_i32 s45, s35, s23
	v_lshl_add_u64 v[206:207], s[16:17], 0, v[132:133]
	s_mov_b32 m0, s45
	ds_read_b128 v[184:187], v150 offset:16384
	ds_read_b128 v[188:191], v150 offset:17408
	ds_read_b128 v[194:197], v150 offset:18432
	ds_read_b128 v[198:201], v150 offset:19456
	ds_read_b128 v[202:205], v150 offset:20480
	ds_read_b128 v[212:215], v150 offset:21504
	ds_read_b128 v[216:219], v150 offset:22528
	ds_read_b128 v[220:223], v150 offset:23552
	global_load_lds_dwordx4 v[206:207], off
	s_add_i32 m0, s45, 0x2000
	s_add_u32 s46, s16, 0xb0000
	v_lshl_add_u64 v[224:225], s[16:17], 0, v[128:129]
	s_addc_u32 s47, s17, 0
	s_add_i32 s45, s38, s23
	global_load_lds_dwordx4 v[224:225], off
	v_lshl_add_u64 v[226:227], s[46:47], 0, v[132:133]
	s_mov_b32 m0, s45
	v_lshl_add_u64 v[228:229], s[18:19], 0, v[130:131]
	global_load_lds_dwordx4 v[226:227], off
	v_lshl_add_u64 v[226:227], s[46:47], 0, v[128:129]
	s_add_i32 m0, s45, 0x2000
	s_nop 0
	global_load_lds_dwordx4 v[226:227], off
	v_lshl_add_u64 v[226:227], s[18:19], 0, v[134:135]
	s_mov_b32 m0, s25
	s_nop 0
	global_load_lds_dwordx4 v[226:227], off
	s_mov_b32 m0, s27
	s_nop 0
	global_load_lds_dwordx4 v[228:229], off
	s_waitcnt vmcnt(8)
	s_waitcnt lgkmcnt(0)
	s_barrier
; #define PG8_STAGE(bufoff, gbase, voff) do { _Pragma("unroll") for (int _i = 0; _i < 2; ++_i) \
;         __builtin_amdgcn_global_load_lds((const unsigned*)((const char*)(gbase) + (voff)[_i]), (PG8_LAS unsigned*)(lds + (bufoff) + ldsw + _i * 8192), 16, 0, 0); } while (0)
; #define PG8_LDA(dst, b, h) do { _Pragma("unroll") for (int m = 0; m < 4; ++m) _Pragma("unroll") for (int k = 0; k < 2; ++k) dst[m][k] = *(const PG8_LAS bf16x8*)(lds + PG8_SA(b, h) + aoff + m * 2048 + k * 1024); } while (0)
; #define PG8_LDB(dst, b, h) do { _Pragma("unroll") for (int n = 0; n < 2; ++n) _Pragma("unroll") for (int k = 0; k < 2; ++k) dst[n][k] = *(const PG8_LAS bf16x8*)(lds + PG8_SB(b, h) + boff + n * 2048 + k * 1024); } while (0)
; #define PG8_MMA(ai, bj, At, Bt) do { __builtin_amdgcn_s_setprio(1); _Pragma("unroll") for (int m = 0; m < 4; ++m) _Pragma("unroll") for (int n = 0; n < 2; ++n) _Pragma("unroll") for (int k = 0; k < 2; ++k) \
;         acc[ai][bj][m][n] = __builtin_amdgcn_mfma_f32_16x16x32_bf16(Bt[n][k], At[m][k], acc[ai][bj][m][n], 0, 0, 0); __builtin_amdgcn_s_setprio(0); } while (0)
; #define PG8_WAIT_V(n) asm volatile("s_waitcnt vmcnt(" #n ")" ::: "memory")
; #define PG8_WAIT_L(n) asm volatile("s_waitcnt lgkmcnt(" #n ")" ::: "memory")
; #define PG8_BAR __builtin_amdgcn_s_barrier()
; #define PG8_SCHED __builtin_amdgcn_sched_barrier(0)
; template <class Epi, class Sched, bool ALIGN_EPI = false, bool SP2 = false>
; __device__ __forceinline__ void gemm_phase(PG8_LAS unsigned char* lds, const Gemm g, const Sched& S, const Epi& E, const int wid) {
;     ...
;             PG8_WAIT_V(8); PG8_WAIT_L(0); PG8_BAR; PG8_MMA(1, 0, At, B0); PG8_MMA(1, 1, At, B1); PG8_BAR; PG8_SCHED;
;             PG8_LDB(B0, 1, 0); PG8_LDB(B1, 1, 1); PG8_SCHED; PG8_LDA(At, 1, 0); PG8_STAGE(PG8_SA(0, 1), a2 + hstep, voffA);
;             PG8_WAIT_V(8); PG8_WAIT_L(0); PG8_BAR; PG8_MMA(0, 0, At, B0); PG8_MMA(0, 1, At, B1); PG8_BAR; PG8_SCHED;
	v_mfma_f32_16x16x32_bf16 v[60:63], v[152:155], v[184:187], v[60:63]
	v_mfma_f32_16x16x32_bf16 v[56:59], v[160:163], v[184:187], v[56:59]
	v_mfma_f32_16x16x32_bf16 v[44:47], v[152:155], v[194:197], v[44:47]
	v_mfma_f32_16x16x32_bf16 v[40:43], v[160:163], v[194:197], v[40:43]
	v_mfma_f32_16x16x32_bf16 v[28:31], v[152:155], v[202:205], v[28:31]
	v_mfma_f32_16x16x32_bf16 v[24:27], v[160:163], v[202:205], v[24:27]
	v_mfma_f32_16x16x32_bf16 v[4:7], v[152:155], v[216:219], v[4:7]
	v_mfma_f32_16x16x32_bf16 v[12:15], v[160:163], v[216:219], v[12:15]
	v_mfma_f32_16x16x32_bf16 v[60:63], v[156:159], v[188:191], v[60:63]
	v_mfma_f32_16x16x32_bf16 v[56:59], v[164:167], v[188:191], v[56:59]
	v_mfma_f32_16x16x32_bf16 v[44:47], v[156:159], v[198:201], v[44:47]
	v_mfma_f32_16x16x32_bf16 v[40:43], v[164:167], v[198:201], v[40:43]
	v_mfma_f32_16x16x32_bf16 v[28:31], v[156:159], v[212:215], v[28:31]
	v_mfma_f32_16x16x32_bf16 v[24:27], v[164:167], v[212:215], v[24:27]
	v_mfma_f32_16x16x32_bf16 v[4:7], v[156:159], v[220:223], v[4:7]
	v_mfma_f32_16x16x32_bf16 v[12:15], v[164:167], v[220:223], v[12:15]
	v_mfma_f32_16x16x32_bf16 v[52:55], v[168:171], v[184:187], v[52:55]
	v_mfma_f32_16x16x32_bf16 v[48:51], v[176:179], v[184:187], v[48:51]
	v_mfma_f32_16x16x32_bf16 v[36:39], v[168:171], v[194:197], v[36:39]
	v_mfma_f32_16x16x32_bf16 v[32:35], v[176:179], v[194:197], v[32:35]
	v_mfma_f32_16x16x32_bf16 v[20:23], v[168:171], v[202:205], v[20:23]
	v_mfma_f32_16x16x32_bf16 v[16:19], v[176:179], v[202:205], v[16:19]
	v_mfma_f32_16x16x32_bf16 v[8:11], v[168:171], v[216:219], v[8:11]
	v_mfma_f32_16x16x32_bf16 v[0:3], v[176:179], v[216:219], v[0:3]
	v_mfma_f32_16x16x32_bf16 v[52:55], v[172:175], v[188:191], v[52:55]
	v_mfma_f32_16x16x32_bf16 v[48:51], v[180:183], v[188:191], v[48:51]
	v_mfma_f32_16x16x32_bf16 v[36:39], v[172:175], v[198:201], v[36:39]
	v_mfma_f32_16x16x32_bf16 v[32:35], v[180:183], v[198:201], v[32:35]
	v_mfma_f32_16x16x32_bf16 v[20:23], v[172:175], v[212:215], v[20:23]
	v_mfma_f32_16x16x32_bf16 v[16:19], v[180:183], v[212:215], v[16:19]
	v_mfma_f32_16x16x32_bf16 v[8:11], v[172:175], v[220:223], v[8:11]
	v_mfma_f32_16x16x32_bf16 v[0:3], v[180:183], v[220:223], v[0:3]
	s_barrier
	s_add_i32 s45, 0, 0x18000
	v_add_u32_e32 v151, s45, v149
	s_add_i32 s46, 0, 0x1c000
	ds_read_b128 v[152:155], v151
	ds_read_b128 v[156:159], v151 offset:1024
	ds_read_b128 v[160:163], v151 offset:2048
	ds_read_b128 v[164:167], v151 offset:3072
	v_add_u32_e32 v151, s46, v149
	ds_read_b128 v[168:171], v151
	ds_read_b128 v[172:175], v151 offset:1024
	ds_read_b128 v[176:179], v151 offset:2048
	ds_read_b128 v[180:183], v151 offset:3072
	s_add_u32 s18, s18, 0xb0000
	s_addc_u32 s19, s19, 0
	s_mov_b32 m0, s28
	v_lshl_add_u64 v[230:231], s[18:19], 0, v[134:135]
	ds_read_b128 v[184:187], v150 offset:32768
	ds_read_b128 v[188:191], v150 offset:33792
	ds_read_b128 v[194:197], v150 offset:34816
	ds_read_b128 v[198:201], v150 offset:35840
	ds_read_b128 v[202:205], v150 offset:36864
	ds_read_b128 v[212:215], v150 offset:37888
	ds_read_b128 v[216:219], v150 offset:38912
	ds_read_b128 v[220:223], v150 offset:39936
	global_load_lds_dwordx4 v[230:231], off
	v_lshl_add_u64 v[230:231], s[18:19], 0, v[130:131]
	s_mov_b32 m0, s29
	s_nop 0
	global_load_lds_dwordx4 v[230:231], off
	s_waitcnt vmcnt(8)
	s_waitcnt lgkmcnt(0)
	s_barrier
	v_mfma_f32_16x16x32_bf16 v[120:123], v[152:155], v[184:187], v[120:123]
	v_mfma_f32_16x16x32_bf16 v[124:127], v[160:163], v[184:187], v[124:127]
	v_mfma_f32_16x16x32_bf16 v[108:111], v[152:155], v[194:197], v[108:111]
	v_mfma_f32_16x16x32_bf16 v[116:119], v[160:163], v[194:197], v[116:119]
	v_mfma_f32_16x16x32_bf16 v[92:95], v[152:155], v[202:205], v[92:95]
	v_mfma_f32_16x16x32_bf16 v[112:115], v[160:163], v[202:205], v[112:115]
	v_mfma_f32_16x16x32_bf16 v[72:75], v[152:155], v[216:219], v[72:75]
	v_mfma_f32_16x16x32_bf16 v[100:103], v[160:163], v[216:219], v[100:103]
	v_mfma_f32_16x16x32_bf16 v[120:123], v[156:159], v[188:191], v[120:123]
	v_mfma_f32_16x16x32_bf16 v[124:127], v[164:167], v[188:191], v[124:127]
	v_mfma_f32_16x16x32_bf16 v[108:111], v[156:159], v[198:201], v[108:111]
	v_mfma_f32_16x16x32_bf16 v[116:119], v[164:167], v[198:201], v[116:119]
	v_mfma_f32_16x16x32_bf16 v[92:95], v[156:159], v[212:215], v[92:95]
	v_mfma_f32_16x16x32_bf16 v[112:115], v[164:167], v[212:215], v[112:115]
	v_mfma_f32_16x16x32_bf16 v[72:75], v[156:159], v[220:223], v[72:75]
	v_mfma_f32_16x16x32_bf16 v[100:103], v[164:167], v[220:223], v[100:103]
	v_mfma_f32_16x16x32_bf16 v[104:107], v[168:171], v[184:187], v[104:107]
	v_mfma_f32_16x16x32_bf16 v[88:91], v[176:179], v[184:187], v[88:91]
	v_mfma_f32_16x16x32_bf16 v[96:99], v[168:171], v[194:197], v[96:99]
	v_mfma_f32_16x16x32_bf16 v[76:79], v[176:179], v[194:197], v[76:79]
	v_mfma_f32_16x16x32_bf16 v[84:87], v[168:171], v[202:205], v[84:87]
	v_mfma_f32_16x16x32_bf16 v[68:71], v[176:179], v[202:205], v[68:71]
	v_mfma_f32_16x16x32_bf16 v[80:83], v[168:171], v[216:219], v[80:83]
	v_mfma_f32_16x16x32_bf16 v[64:67], v[176:179], v[216:219], v[64:67]
	v_mfma_f32_16x16x32_bf16 v[104:107], v[172:175], v[188:191], v[104:107]
	v_mfma_f32_16x16x32_bf16 v[88:91], v[180:183], v[188:191], v[88:91]
	v_mfma_f32_16x16x32_bf16 v[96:99], v[172:175], v[198:201], v[96:99]
	v_mfma_f32_16x16x32_bf16 v[76:79], v[180:183], v[198:201], v[76:79]
	v_mfma_f32_16x16x32_bf16 v[84:87], v[172:175], v[212:215], v[84:87]
	v_mfma_f32_16x16x32_bf16 v[68:71], v[180:183], v[212:215], v[68:71]
	v_mfma_f32_16x16x32_bf16 v[80:83], v[172:175], v[220:223], v[80:83]
	v_mfma_f32_16x16x32_bf16 v[64:67], v[180:183], v[220:223], v[64:67]
	s_barrier
; #define PG8_STAGE(bufoff, gbase, voff) do { _Pragma("unroll") for (int _i = 0; _i < 2; ++_i) \
;         __builtin_amdgcn_global_load_lds((const unsigned*)((const char*)(gbase) + (voff)[_i]), (PG8_LAS unsigned*)(lds + (bufoff) + ldsw + _i * 8192), 16, 0, 0); } while (0)
; #define PG8_LDA(dst, b, h) do { _Pragma("unroll") for (int m = 0; m < 4; ++m) _Pragma("unroll") for (int k = 0; k < 2; ++k) dst[m][k] = *(const PG8_LAS bf16x8*)(lds + PG8_SA(b, h) + aoff + m * 2048 + k * 1024); } while (0)
; #define PG8_MMA(ai, bj, At, Bt) do { __builtin_amdgcn_s_setprio(1); _Pragma("unroll") for (int m = 0; m < 4; ++m) _Pragma("unroll") for (int n = 0; n < 2; ++n) _Pragma("unroll") for (int k = 0; k < 2; ++k) \
;         acc[ai][bj][m][n] = __builtin_amdgcn_mfma_f32_16x16x32_bf16(Bt[n][k], At[m][k], acc[ai][bj][m][n], 0, 0, 0); __builtin_amdgcn_s_setprio(0); } while (0)
; #define PG8_WAIT_V(n) asm volatile("s_waitcnt vmcnt(" #n ")" ::: "memory")
; #define PG8_WAIT_L(n) asm volatile("s_waitcnt lgkmcnt(" #n ")" ::: "memory")
; #define PG8_BAR __builtin_amdgcn_s_barrier()
; #define PG8_SCHED __builtin_amdgcn_sched_barrier(0)
; template <class Epi, class Sched, bool ALIGN_EPI = false, bool SP2 = false>
; __device__ __forceinline__ void gemm_phase(PG8_LAS unsigned char* lds, const Gemm g, const Sched& S, const Epi& E, const int wid) {
;     ...
;             PG8_LDA(At, 1, 1); PG8_STAGE(PG8_SB(1, 0), b3, voffB); PG8_STAGE(PG8_SB(1, 1), b3 + hstep, voffB); PG8_STAGE(PG8_SA(1, 0), a3, voffA);
;             PG8_WAIT_V(8); PG8_WAIT_L(0); PG8_BAR; PG8_MMA(1, 0, At, B0); PG8_MMA(1, 1, At, B1); PG8_BAR; PG8_SCHED;
;     ...
;         if (!has_next) break;
; #pragma unroll
;         for (int a = 0; a < 2; ++a)
; #pragma unroll
;             for (int b = 0; b < 2; ++b)
; #pragma unroll
;                 for (int m = 0; m < 4; ++m)
; #pragma unroll
;                     for (int n = 0; n < 2; ++n) acc[a][b][m][n] = (f32x4){0.f, 0.f, 0.f, 0.f};
;         cur = nxt; cA = nA; cB = nB; ++ui;
	s_add_i32 s18, s45, s23
	v_lshl_add_u64 v[206:207], v[206:207], 0, s[10:11]
	s_mov_b32 m0, s18
	ds_read_b128 v[184:187], v150 offset:49152
	ds_read_b128 v[188:191], v150 offset:50176
	ds_read_b128 v[194:197], v150 offset:51200
	ds_read_b128 v[198:201], v150 offset:52224
	ds_read_b128 v[202:205], v150 offset:53248
	ds_read_b128 v[212:215], v150 offset:54272
	ds_read_b128 v[216:219], v150 offset:55296
	ds_read_b128 v[220:223], v150 offset:56320
	global_load_lds_dwordx4 v[206:207], off
	s_add_i32 m0, s18, 0x2000
	s_add_u32 s16, s16, 0xb0080
	v_lshl_add_u64 v[206:207], v[224:225], 0, s[10:11]
	s_addc_u32 s17, s17, 0
	s_add_i32 s18, s46, s23
	global_load_lds_dwordx4 v[206:207], off
	v_lshl_add_u64 v[206:207], s[16:17], 0, v[132:133]
	s_mov_b32 m0, s18
	s_nop 0
	global_load_lds_dwordx4 v[206:207], off
	v_lshl_add_u64 v[206:207], s[16:17], 0, v[128:129]
	s_add_i32 m0, s18, 0x2000
	s_nop 0
	global_load_lds_dwordx4 v[206:207], off
	v_lshl_add_u64 v[206:207], v[226:227], 0, s[10:11]
	s_mov_b32 m0, s31
	s_nop 0
	global_load_lds_dwordx4 v[206:207], off
	v_lshl_add_u64 v[206:207], v[228:229], 0, s[10:11]
	s_mov_b32 m0, s33
	s_nop 0
	global_load_lds_dwordx4 v[206:207], off
	s_waitcnt vmcnt(8)
	s_waitcnt lgkmcnt(0)
	s_barrier
	v_mfma_f32_16x16x32_bf16 v[60:63], v[152:155], v[184:187], v[60:63]
	v_mfma_f32_16x16x32_bf16 v[56:59], v[160:163], v[184:187], v[56:59]
	v_mfma_f32_16x16x32_bf16 v[44:47], v[152:155], v[194:197], v[44:47]
	v_mfma_f32_16x16x32_bf16 v[40:43], v[160:163], v[194:197], v[40:43]
	v_mfma_f32_16x16x32_bf16 v[28:31], v[152:155], v[202:205], v[28:31]
	v_mfma_f32_16x16x32_bf16 v[24:27], v[160:163], v[202:205], v[24:27]
	v_mfma_f32_16x16x32_bf16 v[4:7], v[152:155], v[216:219], v[4:7]
	v_mfma_f32_16x16x32_bf16 v[12:15], v[160:163], v[216:219], v[12:15]
	v_mfma_f32_16x16x32_bf16 v[60:63], v[156:159], v[188:191], v[60:63]
	v_mfma_f32_16x16x32_bf16 v[56:59], v[164:167], v[188:191], v[56:59]
	v_mfma_f32_16x16x32_bf16 v[44:47], v[156:159], v[198:201], v[44:47]
	v_mfma_f32_16x16x32_bf16 v[40:43], v[164:167], v[198:201], v[40:43]
	v_mfma_f32_16x16x32_bf16 v[28:31], v[156:159], v[212:215], v[28:31]
	v_mfma_f32_16x16x32_bf16 v[24:27], v[164:167], v[212:215], v[24:27]
	v_mfma_f32_16x16x32_bf16 v[4:7], v[156:159], v[220:223], v[4:7]
	v_mfma_f32_16x16x32_bf16 v[12:15], v[164:167], v[220:223], v[12:15]
	v_mfma_f32_16x16x32_bf16 v[52:55], v[168:171], v[184:187], v[52:55]
	v_mfma_f32_16x16x32_bf16 v[48:51], v[176:179], v[184:187], v[48:51]
	v_mfma_f32_16x16x32_bf16 v[36:39], v[168:171], v[194:197], v[36:39]
	v_mfma_f32_16x16x32_bf16 v[32:35], v[176:179], v[194:197], v[32:35]
	v_mfma_f32_16x16x32_bf16 v[20:23], v[168:171], v[202:205], v[20:23]
	v_mfma_f32_16x16x32_bf16 v[16:19], v[176:179], v[202:205], v[16:19]
	v_mfma_f32_16x16x32_bf16 v[8:11], v[168:171], v[216:219], v[8:11]
	v_mfma_f32_16x16x32_bf16 v[0:3], v[176:179], v[216:219], v[0:3]
	v_mfma_f32_16x16x32_bf16 v[52:55], v[172:175], v[188:191], v[52:55]
	v_mfma_f32_16x16x32_bf16 v[48:51], v[180:183], v[188:191], v[48:51]
	v_mfma_f32_16x16x32_bf16 v[36:39], v[172:175], v[198:201], v[36:39]
	v_mfma_f32_16x16x32_bf16 v[32:35], v[180:183], v[198:201], v[32:35]
	v_mfma_f32_16x16x32_bf16 v[20:23], v[172:175], v[212:215], v[20:23]
	v_mfma_f32_16x16x32_bf16 v[16:19], v[180:183], v[212:215], v[16:19]
	v_mfma_f32_16x16x32_bf16 v[8:11], v[172:175], v[220:223], v[8:11]
	v_mfma_f32_16x16x32_bf16 v[0:3], v[180:183], v[220:223], v[0:3]
	s_barrier
	s_add_i32 s44, s44, 2
	s_add_u32 s14, s14, 0x100
	s_addc_u32 s15, s15, 0
	s_cmp_gt_u32 s44, 41
	s_cbranch_scc0 .LBB0_756
	s_add_u32 s14, s42, 0xffffff00
	s_addc_u32 s15, s43, -1
	s_and_b64 vcc, exec, s[6:7]
	s_cbranch_vccnz .LBB0_743
	v_mov_b32_e32 v0, 0
	s_mov_b32 s0, s39
	s_mov_b32 s20, s40
	s_mov_b64 s[2:3], s[12:13]
	s_mov_b32 s34, s41
	v_mov_b32_e32 v1, v0
	v_mov_b32_e32 v2, v0
	v_mov_b32_e32 v3, v0
	v_mov_b32_e32 v8, v0
	v_mov_b32_e32 v9, v0
	v_mov_b32_e32 v10, v0
	v_mov_b32_e32 v11, v0
	v_mov_b32_e32 v16, v0
	v_mov_b32_e32 v17, v0
	v_mov_b32_e32 v18, v0
	v_mov_b32_e32 v19, v0
	v_mov_b32_e32 v20, v0
	v_mov_b32_e32 v21, v0
	v_mov_b32_e32 v22, v0
	v_mov_b32_e32 v23, v0
	v_mov_b32_e32 v32, v0
	v_mov_b32_e32 v33, v0
	v_mov_b32_e32 v34, v0
	v_mov_b32_e32 v35, v0
	v_mov_b32_e32 v36, v0
	v_mov_b32_e32 v37, v0
	v_mov_b32_e32 v38, v0
	v_mov_b32_e32 v39, v0
	v_mov_b32_e32 v48, v0
	v_mov_b32_e32 v49, v0
	v_mov_b32_e32 v50, v0
	v_mov_b32_e32 v51, v0
	v_mov_b32_e32 v52, v0
	v_mov_b32_e32 v53, v0
	v_mov_b32_e32 v54, v0
	v_mov_b32_e32 v55, v0
	v_mov_b32_e32 v12, v0
	v_mov_b32_e32 v13, v0
	v_mov_b32_e32 v14, v0
	v_mov_b32_e32 v15, v0
	v_mov_b32_e32 v4, v0
	v_mov_b32_e32 v5, v0
	v_mov_b32_e32 v6, v0
	v_mov_b32_e32 v7, v0
	v_mov_b32_e32 v24, v0
	v_mov_b32_e32 v25, v0
	v_mov_b32_e32 v26, v0
	v_mov_b32_e32 v27, v0
	v_mov_b32_e32 v28, v0
	v_mov_b32_e32 v29, v0
	v_mov_b32_e32 v30, v0
	v_mov_b32_e32 v31, v0
	v_mov_b32_e32 v40, v0
	v_mov_b32_e32 v41, v0
	v_mov_b32_e32 v42, v0
	v_mov_b32_e32 v43, v0
	v_mov_b32_e32 v44, v0
	v_mov_b32_e32 v45, v0
	v_mov_b32_e32 v46, v0
	v_mov_b32_e32 v47, v0
	v_mov_b32_e32 v56, v0
	v_mov_b32_e32 v57, v0
	v_mov_b32_e32 v58, v0
	v_mov_b32_e32 v59, v0
	v_mov_b32_e32 v60, v0
	v_mov_b32_e32 v61, v0
	v_mov_b32_e32 v62, v0
	v_mov_b32_e32 v63, v0
	v_mov_b32_e32 v64, v0
	v_mov_b32_e32 v65, v0
	v_mov_b32_e32 v66, v0
	v_mov_b32_e32 v67, v0
	v_mov_b32_e32 v80, v0
	v_mov_b32_e32 v81, v0
	v_mov_b32_e32 v82, v0
	v_mov_b32_e32 v83, v0
	v_mov_b32_e32 v68, v0
	v_mov_b32_e32 v69, v0
	v_mov_b32_e32 v70, v0
	v_mov_b32_e32 v71, v0
	v_mov_b32_e32 v84, v0
	v_mov_b32_e32 v85, v0
	v_mov_b32_e32 v86, v0
	v_mov_b32_e32 v87, v0
	v_mov_b32_e32 v76, v0
	v_mov_b32_e32 v77, v0
	v_mov_b32_e32 v78, v0
	v_mov_b32_e32 v79, v0
	v_mov_b32_e32 v96, v0
	v_mov_b32_e32 v97, v0
	v_mov_b32_e32 v98, v0
	v_mov_b32_e32 v99, v0
	v_mov_b32_e32 v88, v0
	v_mov_b32_e32 v89, v0
	v_mov_b32_e32 v90, v0
	v_mov_b32_e32 v91, v0
	v_mov_b32_e32 v104, v0
	v_mov_b32_e32 v105, v0
	v_mov_b32_e32 v106, v0
	v_mov_b32_e32 v107, v0
	v_mov_b32_e32 v100, v0
	v_mov_b32_e32 v101, v0
	v_mov_b32_e32 v102, v0
	v_mov_b32_e32 v103, v0
	v_mov_b32_e32 v72, v0
	v_mov_b32_e32 v73, v0
	v_mov_b32_e32 v74, v0
	v_mov_b32_e32 v75, v0
	v_mov_b32_e32 v112, v0
	v_mov_b32_e32 v113, v0
	v_mov_b32_e32 v114, v0
	v_mov_b32_e32 v115, v0
	v_mov_b32_e32 v92, v0
	v_mov_b32_e32 v93, v0
	v_mov_b32_e32 v94, v0
	v_mov_b32_e32 v95, v0
	v_mov_b32_e32 v116, v0
	v_mov_b32_e32 v117, v0
	v_mov_b32_e32 v118, v0
	v_mov_b32_e32 v119, v0
	v_mov_b32_e32 v108, v0
	v_mov_b32_e32 v109, v0
	v_mov_b32_e32 v110, v0
	v_mov_b32_e32 v111, v0
	v_mov_b32_e32 v124, v0
	v_mov_b32_e32 v125, v0
	v_mov_b32_e32 v126, v0
	v_mov_b32_e32 v127, v0
	v_mov_b32_e32 v120, v0
	v_mov_b32_e32 v121, v0
	v_mov_b32_e32 v122, v0
	v_mov_b32_e32 v123, v0
	s_andn2_b64 vcc, exec, s[4:5]
	s_cbranch_vccnz .LBB0_744

; template <class Epi, class Sched, bool ALIGN_EPI = false, bool SP2 = false>
; __device__ __forceinline__ void gemm_phase(PG8_LAS unsigned char* lds, const Gemm g, const Sched& S, const Epi& E, const int wid) {
;     ...
;         const bool has_next = S.next(ui + 1, nxt);
;         const char* nA = has_next ? (const char*)g.A + (size_t)nxt.pm * tstep : cA; const char* nB = has_next ? (const char*)g.Bt + (size_t)nxt.pn * tstep : cB;
;         for (int t = 0; t < nt; t += 2) {
;             const bool last = (t == nt - 2);
;             const char* a1 = cA + (size_t)(t + 1) * kstep;
;             const char* a2 = last ? nA : cA + (size_t)(t + 2) * kstep; const char* b2 = last ? nB : cB + (size_t)(t + 2) * kstep;
;             const char* a3 = a2 + kstep; const char* b3 = b2 + kstep;
.LBB0_881:
	s_ashr_i32 s13, s12, 31
	s_lshl_b64 s[14:15], s[12:13], 19
	s_add_u32 s14, s80, s14
	s_addc_u32 s15, s81, s15
	s_and_b64 s[18:19], s[4:5], exec
	s_cselect_b32 s13, s15, s21
	s_cselect_b32 s43, s14, s20
	s_ashr_i32 s9, s8, 31
	s_lshl_b64 s[18:19], s[8:9], 19
	s_add_u32 s18, s10, s18
	s_addc_u32 s19, s11, s19
	s_and_b64 s[24:25], s[4:5], exec
	s_cselect_b32 s9, s19, s23
	s_cselect_b32 s44, s18, s22
	s_add_u32 s20, s20, 0x40080
	s_addc_u32 s21, s21, 0
	s_add_u32 s45, s22, 0x100

; template <class Epi, class Sched, bool ALIGN_EPI = false, bool SP2 = false>
; __device__ __forceinline__ void gemm_phase(PG8_LAS unsigned char* lds, const Gemm g, const Sched& S, const Epi& E, const int wid) {
;     ...
;         for (int t = 0; t < nt; t += 2) {
;             const bool last = (t == nt - 2);
;             const char* a1 = cA + (size_t)(t + 1) * kstep;
;             const char* a2 = last ? nA : cA + (size_t)(t + 2) * kstep; const char* b2 = last ? nB : cB + (size_t)(t + 2) * kstep;
;             const char* a3 = a2 + kstep; const char* b3 = b2 + kstep;
	s_addc_u32 s46, s23, 0
	s_mov_b32 s47, -2


; #define PG8_STAGE(bufoff, gbase, voff) do { _Pragma("unroll") for (int _i = 0; _i < 2; ++_i) \
;         __builtin_amdgcn_global_load_lds((const unsigned*)((const char*)(gbase) + (voff)[_i]), (PG8_LAS unsigned*)(lds + (bufoff) + ldsw + _i * 8192), 16, 0, 0); } while (0)
; #define PG8_LDA(dst, b, h) do { _Pragma("unroll") for (int m = 0; m < 4; ++m) _Pragma("unroll") for (int k = 0; k < 2; ++k) dst[m][k] = *(const PG8_LAS bf16x8*)(lds + PG8_SA(b, h) + aoff + m * 2048 + k * 1024); } while (0)
; #define PG8_LDB(dst, b, h) do { _Pragma("unroll") for (int n = 0; n < 2; ++n) _Pragma("unroll") for (int k = 0; k < 2; ++k) dst[n][k] = *(const PG8_LAS bf16x8*)(lds + PG8_SB(b, h) + boff + n * 2048 + k * 1024); } while (0)
; #define PG8_MMA(ai, bj, At, Bt) do { __builtin_amdgcn_s_setprio(1); _Pragma("unroll") for (int m = 0; m < 4; ++m) _Pragma("unroll") for (int n = 0; n < 2; ++n) _Pragma("unroll") for (int k = 0; k < 2; ++k) \
;         acc[ai][bj][m][n] = __builtin_amdgcn_mfma_f32_16x16x32_bf16(Bt[n][k], At[m][k], acc[ai][bj][m][n], 0, 0, 0); __builtin_amdgcn_s_setprio(0); } while (0)
; #define PG8_WAIT_V(n) asm volatile("s_waitcnt vmcnt(" #n ")" ::: "memory")
; #define PG8_WAIT_L(n) asm volatile("s_waitcnt lgkmcnt(" #n ")" ::: "memory")
; #define PG8_BAR __builtin_amdgcn_s_barrier()
; #define PG8_SCHED __builtin_amdgcn_sched_barrier(0)
; template <class Epi, class Sched, bool ALIGN_EPI = false, bool SP2 = false>
; __device__ __forceinline__ void gemm_phase(PG8_LAS unsigned char* lds, const Gemm g, const Sched& S, const Epi& E, const int wid) {
;     ...
;             PG8_LDB(B0, 0, 0); PG8_LDB(B1, 0, 1); PG8_SCHED; PG8_LDA(At, 0, 0); PG8_STAGE(PG8_SA(1, 1), a1 + hstep, voffA);
;             PG8_WAIT_V(8); PG8_WAIT_L(0); PG8_BAR; PG8_MMA(0, 0, At, B0); PG8_MMA(0, 1, At, B1); PG8_BAR; PG8_SCHED;
;             PG8_LDA(At, 0, 1); PG8_STAGE(PG8_SB(0, 0), b2, voffB); PG8_STAGE(PG8_SB(0, 1), b2 + hstep, voffB); PG8_STAGE(PG8_SA(0, 0), a2, voffA);
;             PG8_WAIT_V(8); PG8_WAIT_L(0); PG8_BAR; PG8_MMA(1, 0, At, B0); PG8_MMA(1, 1, At, B1); PG8_BAR; PG8_SCHED;
	ds_read_b128 v[152:155], v149
	ds_read_b128 v[156:159], v149 offset:1024
	ds_read_b128 v[160:163], v149 offset:2048
	ds_read_b128 v[164:167], v149 offset:3072
	ds_read_b128 v[168:171], v150
	ds_read_b128 v[172:175], v150 offset:1024
	ds_read_b128 v[176:179], v150 offset:2048
	ds_read_b128 v[180:183], v150 offset:3072
	s_add_u32 s22, s20, 0xfffc0080
	s_addc_u32 s23, s21, -1
	s_cmp_eq_u32 s47, 12
	s_cselect_b32 s25, s13, s23
	s_cselect_b32 s24, s43, s22
	s_cselect_b32 s23, s9, s46
	s_cselect_b32 s22, s44, s45
	v_lshl_add_u64 v[144:145], s[20:21], 0, v[136:137]
	s_add_i32 m0, s17, 0xc000
	ds_read_b128 v[184:187], v151
	ds_read_b128 v[188:191], v151 offset:1024
	ds_read_b128 v[192:195], v151 offset:2048
	ds_read_b128 v[196:199], v151 offset:3072
	ds_read_b128 v[200:203], v151 offset:4096
	ds_read_b128 v[204:207], v151 offset:5120
	ds_read_b128 v[212:215], v151 offset:6144
	ds_read_b128 v[216:219], v151 offset:7168
	global_load_lds_dwordx4 v[144:145], off
	v_lshl_add_u64 v[144:145], s[20:21], 0, v[138:139]
	s_add_i32 m0, s17, 0xe000
	s_nop 0
	global_load_lds_dwordx4 v[144:145], off
	s_waitcnt vmcnt(8)
	s_waitcnt lgkmcnt(0)
	s_barrier
	v_mfma_f32_16x16x32_bf16 v[124:127], v[152:155], v[184:187], 0
	v_mfma_f32_16x16x32_bf16 v[120:123], v[160:163], v[184:187], 0
	v_mfma_f32_16x16x32_bf16 v[116:119], v[152:155], v[192:195], 0
	v_mfma_f32_16x16x32_bf16 v[108:111], v[160:163], v[192:195], 0
	v_mfma_f32_16x16x32_bf16 v[100:103], v[152:155], v[200:203], 0
	v_mfma_f32_16x16x32_bf16 v[92:95], v[160:163], v[200:203], 0
	v_mfma_f32_16x16x32_bf16 v[84:87], v[152:155], v[212:215], 0
	v_mfma_f32_16x16x32_bf16 v[76:79], v[160:163], v[212:215], 0
	v_mfma_f32_16x16x32_bf16 v[124:127], v[156:159], v[188:191], v[124:127]
	v_mfma_f32_16x16x32_bf16 v[120:123], v[164:167], v[188:191], v[120:123]
	v_mfma_f32_16x16x32_bf16 v[116:119], v[156:159], v[196:199], v[116:119]
	v_mfma_f32_16x16x32_bf16 v[108:111], v[164:167], v[196:199], v[108:111]
	v_mfma_f32_16x16x32_bf16 v[100:103], v[156:159], v[204:207], v[100:103]
	v_mfma_f32_16x16x32_bf16 v[92:95], v[164:167], v[204:207], v[92:95]
	v_mfma_f32_16x16x32_bf16 v[84:87], v[156:159], v[216:219], v[84:87]
	v_mfma_f32_16x16x32_bf16 v[76:79], v[164:167], v[216:219], v[76:79]
	v_mfma_f32_16x16x32_bf16 v[112:115], v[168:171], v[184:187], 0
	v_mfma_f32_16x16x32_bf16 v[104:107], v[176:179], v[184:187], 0
	v_mfma_f32_16x16x32_bf16 v[96:99], v[168:171], v[192:195], 0
	v_mfma_f32_16x16x32_bf16 v[88:91], v[176:179], v[192:195], 0
	v_mfma_f32_16x16x32_bf16 v[80:83], v[168:171], v[200:203], 0
	v_mfma_f32_16x16x32_bf16 v[72:75], v[176:179], v[200:203], 0
	v_mfma_f32_16x16x32_bf16 v[68:71], v[168:171], v[212:215], 0
	v_mfma_f32_16x16x32_bf16 v[64:67], v[176:179], v[212:215], 0
	v_mfma_f32_16x16x32_bf16 v[112:115], v[172:175], v[188:191], v[112:115]
	v_mfma_f32_16x16x32_bf16 v[104:107], v[180:183], v[188:191], v[104:107]
	v_mfma_f32_16x16x32_bf16 v[96:99], v[172:175], v[196:199], v[96:99]
	v_mfma_f32_16x16x32_bf16 v[88:91], v[180:183], v[196:199], v[88:91]
	v_mfma_f32_16x16x32_bf16 v[80:83], v[172:175], v[204:207], v[80:83]
	v_mfma_f32_16x16x32_bf16 v[72:75], v[180:183], v[204:207], v[72:75]
	v_mfma_f32_16x16x32_bf16 v[68:71], v[172:175], v[216:219], v[68:71]
	v_mfma_f32_16x16x32_bf16 v[64:67], v[180:183], v[216:219], v[64:67]
	s_barrier
	s_add_i32 s48, s39, s26
	v_lshl_add_u64 v[144:145], s[22:23], 0, v[132:133]
	s_mov_b32 m0, s48
	ds_read_b128 v[184:187], v151 offset:16384
	ds_read_b128 v[188:191], v151 offset:17408
	ds_read_b128 v[192:195], v151 offset:18432
	ds_read_b128 v[196:199], v151 offset:19456
	ds_read_b128 v[200:203], v151 offset:20480
	ds_read_b128 v[204:207], v151 offset:21504
	ds_read_b128 v[212:215], v151 offset:22528
	ds_read_b128 v[216:219], v151 offset:23552
	global_load_lds_dwordx4 v[144:145], off
	s_add_i32 m0, s48, 0x2000
	s_add_u32 s48, s22, 0x40000
	v_lshl_add_u64 v[220:221], s[22:23], 0, v[128:129]
	s_addc_u32 s49, s23, 0
	s_add_i32 s50, s40, s26
	global_load_lds_dwordx4 v[220:221], off
	v_lshl_add_u64 v[222:223], s[48:49], 0, v[132:133]
	s_mov_b32 m0, s50
	v_lshl_add_u64 v[224:225], s[24:25], 0, v[130:131]
	global_load_lds_dwordx4 v[222:223], off
	v_lshl_add_u64 v[222:223], s[48:49], 0, v[128:129]
	s_add_i32 m0, s50, 0x2000
	s_nop 0
	global_load_lds_dwordx4 v[222:223], off
	v_lshl_add_u64 v[222:223], s[24:25], 0, v[134:135]
	s_mov_b32 m0, s17
	s_nop 0
	global_load_lds_dwordx4 v[222:223], off
	s_mov_b32 m0, s29
	s_nop 0
	global_load_lds_dwordx4 v[224:225], off
	s_waitcnt vmcnt(8)
	s_waitcnt lgkmcnt(0)
	s_barrier
	v_mfma_f32_16x16x32_bf16 v[60:63], v[152:155], v[184:187], 0
	v_mfma_f32_16x16x32_bf16 v[56:59], v[160:163], v[184:187], 0
	v_mfma_f32_16x16x32_bf16 v[52:55], v[152:155], v[192:195], 0
	v_mfma_f32_16x16x32_bf16 v[44:47], v[160:163], v[192:195], 0
	v_mfma_f32_16x16x32_bf16 v[36:39], v[152:155], v[200:203], 0
	v_mfma_f32_16x16x32_bf16 v[28:31], v[160:163], v[200:203], 0
	v_mfma_f32_16x16x32_bf16 v[20:23], v[152:155], v[212:215], 0
	v_mfma_f32_16x16x32_bf16 v[12:15], v[160:163], v[212:215], 0
	v_mfma_f32_16x16x32_bf16 v[60:63], v[156:159], v[188:191], v[60:63]
	v_mfma_f32_16x16x32_bf16 v[56:59], v[164:167], v[188:191], v[56:59]
	v_mfma_f32_16x16x32_bf16 v[52:55], v[156:159], v[196:199], v[52:55]
	v_mfma_f32_16x16x32_bf16 v[44:47], v[164:167], v[196:199], v[44:47]
	v_mfma_f32_16x16x32_bf16 v[36:39], v[156:159], v[204:207], v[36:39]
	v_mfma_f32_16x16x32_bf16 v[28:31], v[164:167], v[204:207], v[28:31]
	v_mfma_f32_16x16x32_bf16 v[20:23], v[156:159], v[216:219], v[20:23]
	v_mfma_f32_16x16x32_bf16 v[12:15], v[164:167], v[216:219], v[12:15]
	v_mfma_f32_16x16x32_bf16 v[48:51], v[168:171], v[184:187], 0
	v_mfma_f32_16x16x32_bf16 v[40:43], v[176:179], v[184:187], 0
	v_mfma_f32_16x16x32_bf16 v[32:35], v[168:171], v[192:195], 0
	v_mfma_f32_16x16x32_bf16 v[24:27], v[176:179], v[192:195], 0
	v_mfma_f32_16x16x32_bf16 v[16:19], v[168:171], v[200:203], 0
	v_mfma_f32_16x16x32_bf16 v[8:11], v[176:179], v[200:203], 0
	v_mfma_f32_16x16x32_bf16 v[4:7], v[168:171], v[212:215], 0
	v_mfma_f32_16x16x32_bf16 v[0:3], v[176:179], v[212:215], 0
	v_mfma_f32_16x16x32_bf16 v[48:51], v[172:175], v[188:191], v[48:51]
	v_mfma_f32_16x16x32_bf16 v[40:43], v[180:183], v[188:191], v[40:43]
	v_mfma_f32_16x16x32_bf16 v[32:35], v[172:175], v[196:199], v[32:35]
	v_mfma_f32_16x16x32_bf16 v[24:27], v[180:183], v[196:199], v[24:27]
	v_mfma_f32_16x16x32_bf16 v[16:19], v[172:175], v[204:207], v[16:19]
	v_mfma_f32_16x16x32_bf16 v[8:11], v[180:183], v[204:207], v[8:11]
	v_mfma_f32_16x16x32_bf16 v[4:7], v[172:175], v[216:219], v[4:7]
	v_mfma_f32_16x16x32_bf16 v[0:3], v[180:183], v[216:219], v[0:3]
	s_barrier
; #define PG8_STAGE(bufoff, gbase, voff) do { _Pragma("unroll") for (int _i = 0; _i < 2; ++_i) \
;         __builtin_amdgcn_global_load_lds((const unsigned*)((const char*)(gbase) + (voff)[_i]), (PG8_LAS unsigned*)(lds + (bufoff) + ldsw + _i * 8192), 16, 0, 0); } while (0)
; #define PG8_LDA(dst, b, h) do { _Pragma("unroll") for (int m = 0; m < 4; ++m) _Pragma("unroll") for (int k = 0; k < 2; ++k) dst[m][k] = *(const PG8_LAS bf16x8*)(lds + PG8_SA(b, h) + aoff + m * 2048 + k * 1024); } while (0)
; #define PG8_LDB(dst, b, h) do { _Pragma("unroll") for (int n = 0; n < 2; ++n) _Pragma("unroll") for (int k = 0; k < 2; ++k) dst[n][k] = *(const PG8_LAS bf16x8*)(lds + PG8_SB(b, h) + boff + n * 2048 + k * 1024); } while (0)
; #define PG8_MMA(ai, bj, At, Bt) do { __builtin_amdgcn_s_setprio(1); _Pragma("unroll") for (int m = 0; m < 4; ++m) _Pragma("unroll") for (int n = 0; n < 2; ++n) _Pragma("unroll") for (int k = 0; k < 2; ++k) \
;         acc[ai][bj][m][n] = __builtin_amdgcn_mfma_f32_16x16x32_bf16(Bt[n][k], At[m][k], acc[ai][bj][m][n], 0, 0, 0); __builtin_amdgcn_s_setprio(0); } while (0)
; #define PG8_WAIT_V(n) asm volatile("s_waitcnt vmcnt(" #n ")" ::: "memory")
; #define PG8_WAIT_L(n) asm volatile("s_waitcnt lgkmcnt(" #n ")" ::: "memory")
; #define PG8_BAR __builtin_amdgcn_s_barrier()
; #define PG8_SCHED __builtin_amdgcn_sched_barrier(0)
; template <class Epi, class Sched, bool ALIGN_EPI = false, bool SP2 = false>
; __device__ __forceinline__ void gemm_phase(PG8_LAS unsigned char* lds, const Gemm g, const Sched& S, const Epi& E, const int wid) {
;     ...
;             PG8_LDB(B0, 1, 0); PG8_LDB(B1, 1, 1); PG8_SCHED; PG8_LDA(At, 1, 0); PG8_STAGE(PG8_SA(0, 1), a2 + hstep, voffA);
;             PG8_WAIT_V(8); PG8_WAIT_L(0); PG8_BAR; PG8_MMA(0, 0, At, B0); PG8_MMA(0, 1, At, B1); PG8_BAR; PG8_SCHED;
;             PG8_LDA(At, 1, 1); PG8_STAGE(PG8_SB(1, 0), b3, voffB); PG8_STAGE(PG8_SB(1, 1), b3 + hstep, voffB); PG8_STAGE(PG8_SA(1, 0), a3, voffA);
;             PG8_WAIT_V(8); PG8_WAIT_L(0); PG8_BAR; PG8_MMA(1, 0, At, B0); PG8_MMA(1, 1, At, B1); PG8_BAR; PG8_SCHED;
	s_add_i32 s48, 0, 0x18000
	s_add_i32 s49, 0, 0x1c000
	v_add_u32_e32 v164, s48, v147
	v_add_u32_e32 v180, s49, v147
	ds_read_b128 v[152:155], v164
	ds_read_b128 v[156:159], v164 offset:1024
	ds_read_b128 v[160:163], v164 offset:2048
	ds_read_b128 v[164:167], v164 offset:3072
	ds_read_b128 v[168:171], v180
	ds_read_b128 v[172:175], v180 offset:1024
	ds_read_b128 v[176:179], v180 offset:2048
	ds_read_b128 v[180:183], v180 offset:3072
	s_add_u32 s24, s24, 0x40000
	s_addc_u32 s25, s25, 0
	s_mov_b32 m0, s30
	v_lshl_add_u64 v[226:227], s[24:25], 0, v[134:135]
	ds_read_b128 v[184:187], v151 offset:32768
	ds_read_b128 v[188:191], v151 offset:33792
	ds_read_b128 v[192:195], v151 offset:34816
	ds_read_b128 v[196:199], v151 offset:35840
	ds_read_b128 v[200:203], v151 offset:36864
	ds_read_b128 v[204:207], v151 offset:37888
	ds_read_b128 v[212:215], v151 offset:38912
	ds_read_b128 v[216:219], v151 offset:39936
	global_load_lds_dwordx4 v[226:227], off
	v_lshl_add_u64 v[226:227], s[24:25], 0, v[130:131]
	s_mov_b32 m0, s31
	s_nop 0
	global_load_lds_dwordx4 v[226:227], off
	s_waitcnt vmcnt(8)
	s_waitcnt lgkmcnt(0)
	s_barrier
	v_mfma_f32_16x16x32_bf16 v[124:127], v[152:155], v[184:187], v[124:127]
	v_mfma_f32_16x16x32_bf16 v[120:123], v[160:163], v[184:187], v[120:123]
	v_mfma_f32_16x16x32_bf16 v[116:119], v[152:155], v[192:195], v[116:119]
	v_mfma_f32_16x16x32_bf16 v[108:111], v[160:163], v[192:195], v[108:111]
	v_mfma_f32_16x16x32_bf16 v[100:103], v[152:155], v[200:203], v[100:103]
	v_mfma_f32_16x16x32_bf16 v[92:95], v[160:163], v[200:203], v[92:95]
	v_mfma_f32_16x16x32_bf16 v[84:87], v[152:155], v[212:215], v[84:87]
	v_mfma_f32_16x16x32_bf16 v[76:79], v[160:163], v[212:215], v[76:79]
	v_mfma_f32_16x16x32_bf16 v[124:127], v[156:159], v[188:191], v[124:127]
	v_mfma_f32_16x16x32_bf16 v[120:123], v[164:167], v[188:191], v[120:123]
	v_mfma_f32_16x16x32_bf16 v[116:119], v[156:159], v[196:199], v[116:119]
	v_mfma_f32_16x16x32_bf16 v[108:111], v[164:167], v[196:199], v[108:111]
	v_mfma_f32_16x16x32_bf16 v[100:103], v[156:159], v[204:207], v[100:103]
	v_mfma_f32_16x16x32_bf16 v[92:95], v[164:167], v[204:207], v[92:95]
	v_mfma_f32_16x16x32_bf16 v[84:87], v[156:159], v[216:219], v[84:87]
	v_mfma_f32_16x16x32_bf16 v[76:79], v[164:167], v[216:219], v[76:79]
	v_mfma_f32_16x16x32_bf16 v[112:115], v[168:171], v[184:187], v[112:115]
	v_mfma_f32_16x16x32_bf16 v[104:107], v[176:179], v[184:187], v[104:107]
	v_mfma_f32_16x16x32_bf16 v[96:99], v[168:171], v[192:195], v[96:99]
	v_mfma_f32_16x16x32_bf16 v[88:91], v[176:179], v[192:195], v[88:91]
	v_mfma_f32_16x16x32_bf16 v[80:83], v[168:171], v[200:203], v[80:83]
	v_mfma_f32_16x16x32_bf16 v[72:75], v[176:179], v[200:203], v[72:75]
	v_mfma_f32_16x16x32_bf16 v[68:71], v[168:171], v[212:215], v[68:71]
	v_mfma_f32_16x16x32_bf16 v[64:67], v[176:179], v[212:215], v[64:67]
	v_mfma_f32_16x16x32_bf16 v[112:115], v[172:175], v[188:191], v[112:115]
	v_mfma_f32_16x16x32_bf16 v[104:107], v[180:183], v[188:191], v[104:107]
	v_mfma_f32_16x16x32_bf16 v[96:99], v[172:175], v[196:199], v[96:99]
	v_mfma_f32_16x16x32_bf16 v[88:91], v[180:183], v[196:199], v[88:91]
	v_mfma_f32_16x16x32_bf16 v[80:83], v[172:175], v[204:207], v[80:83]
	v_mfma_f32_16x16x32_bf16 v[72:75], v[180:183], v[204:207], v[72:75]
	v_mfma_f32_16x16x32_bf16 v[68:71], v[172:175], v[216:219], v[68:71]
	v_mfma_f32_16x16x32_bf16 v[64:67], v[180:183], v[216:219], v[64:67]
	s_barrier
	s_add_i32 s24, s48, s26
	v_lshl_add_u64 v[144:145], v[144:145], 0, s[6:7]
	s_mov_b32 m0, s24
	ds_read_b128 v[184:187], v151 offset:49152
	ds_read_b128 v[188:191], v151 offset:50176
	ds_read_b128 v[192:195], v151 offset:51200
	ds_read_b128 v[196:199], v151 offset:52224
	ds_read_b128 v[200:203], v151 offset:53248
	ds_read_b128 v[204:207], v151 offset:54272
	ds_read_b128 v[212:215], v151 offset:55296
	ds_read_b128 v[216:219], v151 offset:56320
	global_load_lds_dwordx4 v[144:145], off
	s_add_i32 m0, s24, 0x2000
	s_add_u32 s22, s22, 0x40080
	v_lshl_add_u64 v[144:145], v[220:221], 0, s[6:7]
	s_addc_u32 s23, s23, 0
	s_add_i32 s24, s49, s26
	global_load_lds_dwordx4 v[144:145], off
	v_lshl_add_u64 v[144:145], s[22:23], 0, v[132:133]
	s_mov_b32 m0, s24
	s_nop 0
	global_load_lds_dwordx4 v[144:145], off
	v_lshl_add_u64 v[144:145], s[22:23], 0, v[128:129]
	s_add_i32 m0, s24, 0x2000
	s_nop 0
	global_load_lds_dwordx4 v[144:145], off
	v_lshl_add_u64 v[144:145], v[222:223], 0, s[6:7]
	s_mov_b32 m0, s37
	s_nop 0
	global_load_lds_dwordx4 v[144:145], off
	v_lshl_add_u64 v[144:145], v[224:225], 0, s[6:7]
	s_mov_b32 m0, s38
	s_nop 0
	global_load_lds_dwordx4 v[144:145], off
	s_waitcnt vmcnt(8)
	s_waitcnt lgkmcnt(0)
	s_barrier
	v_mfma_f32_16x16x32_bf16 v[60:63], v[152:155], v[184:187], v[60:63]
	v_mfma_f32_16x16x32_bf16 v[56:59], v[160:163], v[184:187], v[56:59]
	v_mfma_f32_16x16x32_bf16 v[52:55], v[152:155], v[192:195], v[52:55]
	v_mfma_f32_16x16x32_bf16 v[44:47], v[160:163], v[192:195], v[44:47]
	v_mfma_f32_16x16x32_bf16 v[36:39], v[152:155], v[200:203], v[36:39]
	v_mfma_f32_16x16x32_bf16 v[28:31], v[160:163], v[200:203], v[28:31]
	v_mfma_f32_16x16x32_bf16 v[20:23], v[152:155], v[212:215], v[20:23]
	v_mfma_f32_16x16x32_bf16 v[12:15], v[160:163], v[212:215], v[12:15]
	v_mfma_f32_16x16x32_bf16 v[60:63], v[156:159], v[188:191], v[60:63]
	v_mfma_f32_16x16x32_bf16 v[56:59], v[164:167], v[188:191], v[56:59]
	v_mfma_f32_16x16x32_bf16 v[52:55], v[156:159], v[196:199], v[52:55]
	v_mfma_f32_16x16x32_bf16 v[44:47], v[164:167], v[196:199], v[44:47]
	v_mfma_f32_16x16x32_bf16 v[36:39], v[156:159], v[204:207], v[36:39]
	v_mfma_f32_16x16x32_bf16 v[28:31], v[164:167], v[204:207], v[28:31]
	v_mfma_f32_16x16x32_bf16 v[20:23], v[156:159], v[216:219], v[20:23]
	v_mfma_f32_16x16x32_bf16 v[12:15], v[164:167], v[216:219], v[12:15]
	v_mfma_f32_16x16x32_bf16 v[48:51], v[168:171], v[184:187], v[48:51]
	v_mfma_f32_16x16x32_bf16 v[40:43], v[176:179], v[184:187], v[40:43]
	v_mfma_f32_16x16x32_bf16 v[32:35], v[168:171], v[192:195], v[32:35]
	v_mfma_f32_16x16x32_bf16 v[24:27], v[176:179], v[192:195], v[24:27]
	v_mfma_f32_16x16x32_bf16 v[16:19], v[168:171], v[200:203], v[16:19]
	v_mfma_f32_16x16x32_bf16 v[8:11], v[176:179], v[200:203], v[8:11]
	v_mfma_f32_16x16x32_bf16 v[4:7], v[168:171], v[212:215], v[4:7]
	v_mfma_f32_16x16x32_bf16 v[0:3], v[176:179], v[212:215], v[0:3]
	v_mfma_f32_16x16x32_bf16 v[48:51], v[172:175], v[188:191], v[48:51]
	v_mfma_f32_16x16x32_bf16 v[40:43], v[180:183], v[188:191], v[40:43]
	v_mfma_f32_16x16x32_bf16 v[32:35], v[172:175], v[196:199], v[32:35]
	v_mfma_f32_16x16x32_bf16 v[24:27], v[180:183], v[196:199], v[24:27]
	v_mfma_f32_16x16x32_bf16 v[16:19], v[172:175], v[204:207], v[16:19]
	v_mfma_f32_16x16x32_bf16 v[8:11], v[180:183], v[204:207], v[8:11]
	v_mfma_f32_16x16x32_bf16 v[4:7], v[172:175], v[216:219], v[4:7]
	v_mfma_f32_16x16x32_bf16 v[0:3], v[180:183], v[216:219], v[0:3]
	s_barrier
	s_add_i32 s47, s47, 2
	s_add_u32 s20, s20, 0x100
	s_addc_u32 s21, s21, 0
	s_add_u32 s45, s45, 0x100
	s_addc_u32 s46, s46, 0
	s_cmp_gt_u32 s47, 13
	s_cbranch_scc0 .LBB0_882
	s_branch .Lkp_exit_2
; #define PG8_STAGE(bufoff, gbase, voff) do { _Pragma("unroll") for (int _i = 0; _i < 2; ++_i) \
;         __builtin_amdgcn_global_load_lds((const unsigned*)((const char*)(gbase) + (voff)[_i]), (PG8_LAS unsigned*)(lds + (bufoff) + ldsw + _i * 8192), 16, 0, 0); } while (0)
; #define PG8_LDA(dst, b, h) do { _Pragma("unroll") for (int m = 0; m < 4; ++m) _Pragma("unroll") for (int k = 0; k < 2; ++k) dst[m][k] = *(const PG8_LAS bf16x8*)(lds + PG8_SA(b, h) + aoff + m * 2048 + k * 1024); } while (0)
; #define PG8_LDB(dst, b, h) do { _Pragma("unroll") for (int n = 0; n < 2; ++n) _Pragma("unroll") for (int k = 0; k < 2; ++k) dst[n][k] = *(const PG8_LAS bf16x8*)(lds + PG8_SB(b, h) + boff + n * 2048 + k * 1024); } while (0)
; #define PG8_MMA(ai, bj, At, Bt) do { __builtin_amdgcn_s_setprio(1); _Pragma("unroll") for (int m = 0; m < 4; ++m) _Pragma("unroll") for (int n = 0; n < 2; ++n) _Pragma("unroll") for (int k = 0; k < 2; ++k) \
;         acc[ai][bj][m][n] = __builtin_amdgcn_mfma_f32_16x16x32_bf16(Bt[n][k], At[m][k], acc[ai][bj][m][n], 0, 0, 0); __builtin_amdgcn_s_setprio(0); } while (0)
; #define PG8_WAIT_V(n) asm volatile("s_waitcnt vmcnt(" #n ")" ::: "memory")
; #define PG8_WAIT_L(n) asm volatile("s_waitcnt lgkmcnt(" #n ")" ::: "memory")
; #define PG8_BAR __builtin_amdgcn_s_barrier()
; #define PG8_SCHED __builtin_amdgcn_sched_barrier(0)
; template <class Epi, class Sched, bool ALIGN_EPI = false, bool SP2 = false>
; __device__ __forceinline__ void gemm_phase(PG8_LAS unsigned char* lds, const Gemm g, const Sched& S, const Epi& E, const int wid) {
;     ...
;             PG8_LDB(B0, 0, 0); PG8_LDB(B1, 0, 1); PG8_SCHED; PG8_LDA(At, 0, 0); PG8_STAGE(PG8_SA(1, 1), a1 + hstep, voffA);
;             PG8_WAIT_V(8); PG8_WAIT_L(0); PG8_BAR; PG8_MMA(0, 0, At, B0); PG8_MMA(0, 1, At, B1); PG8_BAR; PG8_SCHED;
;             PG8_LDA(At, 0, 1); PG8_STAGE(PG8_SB(0, 0), b2, voffB); PG8_STAGE(PG8_SB(0, 1), b2 + hstep, voffB); PG8_STAGE(PG8_SA(0, 0), a2, voffA);
;             PG8_WAIT_V(8); PG8_WAIT_L(0); PG8_BAR; PG8_MMA(1, 0, At, B0); PG8_MMA(1, 1, At, B1); PG8_BAR; PG8_SCHED;
.LBB0_882:
	ds_read_b128 v[152:155], v149
	ds_read_b128 v[156:159], v149 offset:1024
	ds_read_b128 v[160:163], v149 offset:2048
	ds_read_b128 v[164:167], v149 offset:3072
	ds_read_b128 v[168:171], v150
	ds_read_b128 v[172:175], v150 offset:1024
	ds_read_b128 v[176:179], v150 offset:2048
	ds_read_b128 v[180:183], v150 offset:3072
	s_add_u32 s22, s20, 0xfffc0080
	s_addc_u32 s23, s21, -1
	s_cmp_eq_u32 s47, 12
	s_cselect_b32 s25, s13, s23
	s_cselect_b32 s24, s43, s22
	s_cselect_b32 s23, s9, s46
	s_cselect_b32 s22, s44, s45
	v_lshl_add_u64 v[144:145], s[20:21], 0, v[136:137]
	s_add_i32 m0, s17, 0xc000
	ds_read_b128 v[184:187], v151
	ds_read_b128 v[188:191], v151 offset:1024
	ds_read_b128 v[192:195], v151 offset:2048
	ds_read_b128 v[196:199], v151 offset:3072
	ds_read_b128 v[200:203], v151 offset:4096
	ds_read_b128 v[204:207], v151 offset:5120
	ds_read_b128 v[212:215], v151 offset:6144
	ds_read_b128 v[216:219], v151 offset:7168
	global_load_lds_dwordx4 v[144:145], off
	v_lshl_add_u64 v[144:145], s[20:21], 0, v[138:139]
	s_add_i32 m0, s17, 0xe000
	s_nop 0
	global_load_lds_dwordx4 v[144:145], off
	s_waitcnt vmcnt(8)
	s_waitcnt lgkmcnt(0)
	s_barrier
	v_mfma_f32_16x16x32_bf16 v[124:127], v[152:155], v[184:187], v[124:127]
	v_mfma_f32_16x16x32_bf16 v[120:123], v[160:163], v[184:187], v[120:123]
	v_mfma_f32_16x16x32_bf16 v[116:119], v[152:155], v[192:195], v[116:119]
	v_mfma_f32_16x16x32_bf16 v[108:111], v[160:163], v[192:195], v[108:111]
	v_mfma_f32_16x16x32_bf16 v[100:103], v[152:155], v[200:203], v[100:103]
	v_mfma_f32_16x16x32_bf16 v[92:95], v[160:163], v[200:203], v[92:95]
	v_mfma_f32_16x16x32_bf16 v[84:87], v[152:155], v[212:215], v[84:87]
	v_mfma_f32_16x16x32_bf16 v[76:79], v[160:163], v[212:215], v[76:79]
	v_mfma_f32_16x16x32_bf16 v[124:127], v[156:159], v[188:191], v[124:127]
	v_mfma_f32_16x16x32_bf16 v[120:123], v[164:167], v[188:191], v[120:123]
	v_mfma_f32_16x16x32_bf16 v[116:119], v[156:159], v[196:199], v[116:119]
	v_mfma_f32_16x16x32_bf16 v[108:111], v[164:167], v[196:199], v[108:111]
	v_mfma_f32_16x16x32_bf16 v[100:103], v[156:159], v[204:207], v[100:103]
	v_mfma_f32_16x16x32_bf16 v[92:95], v[164:167], v[204:207], v[92:95]
	v_mfma_f32_16x16x32_bf16 v[84:87], v[156:159], v[216:219], v[84:87]
	v_mfma_f32_16x16x32_bf16 v[76:79], v[164:167], v[216:219], v[76:79]
	v_mfma_f32_16x16x32_bf16 v[112:115], v[168:171], v[184:187], v[112:115]
	v_mfma_f32_16x16x32_bf16 v[104:107], v[176:179], v[184:187], v[104:107]
	v_mfma_f32_16x16x32_bf16 v[96:99], v[168:171], v[192:195], v[96:99]
	v_mfma_f32_16x16x32_bf16 v[88:91], v[176:179], v[192:195], v[88:91]
	v_mfma_f32_16x16x32_bf16 v[80:83], v[168:171], v[200:203], v[80:83]
	v_mfma_f32_16x16x32_bf16 v[72:75], v[176:179], v[200:203], v[72:75]
	v_mfma_f32_16x16x32_bf16 v[68:71], v[168:171], v[212:215], v[68:71]
	v_mfma_f32_16x16x32_bf16 v[64:67], v[176:179], v[212:215], v[64:67]
	v_mfma_f32_16x16x32_bf16 v[112:115], v[172:175], v[188:191], v[112:115]
	v_mfma_f32_16x16x32_bf16 v[104:107], v[180:183], v[188:191], v[104:107]
	v_mfma_f32_16x16x32_bf16 v[96:99], v[172:175], v[196:199], v[96:99]
	v_mfma_f32_16x16x32_bf16 v[88:91], v[180:183], v[196:199], v[88:91]
	v_mfma_f32_16x16x32_bf16 v[80:83], v[172:175], v[204:207], v[80:83]
	v_mfma_f32_16x16x32_bf16 v[72:75], v[180:183], v[204:207], v[72:75]
	v_mfma_f32_16x16x32_bf16 v[68:71], v[172:175], v[216:219], v[68:71]
	v_mfma_f32_16x16x32_bf16 v[64:67], v[180:183], v[216:219], v[64:67]
	s_barrier
	s_add_i32 s48, s39, s26
	v_lshl_add_u64 v[144:145], s[22:23], 0, v[132:133]
	s_mov_b32 m0, s48
	ds_read_b128 v[184:187], v151 offset:16384
	ds_read_b128 v[188:191], v151 offset:17408
	ds_read_b128 v[192:195], v151 offset:18432
	ds_read_b128 v[196:199], v151 offset:19456
	ds_read_b128 v[200:203], v151 offset:20480
	ds_read_b128 v[204:207], v151 offset:21504
	ds_read_b128 v[212:215], v151 offset:22528
	ds_read_b128 v[216:219], v151 offset:23552
	global_load_lds_dwordx4 v[144:145], off
	s_add_i32 m0, s48, 0x2000
	s_add_u32 s48, s22, 0x40000
	v_lshl_add_u64 v[220:221], s[22:23], 0, v[128:129]
	s_addc_u32 s49, s23, 0
	s_add_i32 s50, s40, s26
	global_load_lds_dwordx4 v[220:221], off
	v_lshl_add_u64 v[222:223], s[48:49], 0, v[132:133]
	s_mov_b32 m0, s50
	v_lshl_add_u64 v[224:225], s[24:25], 0, v[130:131]
	global_load_lds_dwordx4 v[222:223], off
	v_lshl_add_u64 v[222:223], s[48:49], 0, v[128:129]
	s_add_i32 m0, s50, 0x2000
	s_nop 0
	global_load_lds_dwordx4 v[222:223], off
	v_lshl_add_u64 v[222:223], s[24:25], 0, v[134:135]
	s_mov_b32 m0, s17
	s_nop 0
	global_load_lds_dwordx4 v[222:223], off
	s_mov_b32 m0, s29
	s_nop 0
	global_load_lds_dwordx4 v[224:225], off
	s_waitcnt vmcnt(8)
	s_waitcnt lgkmcnt(0)
	s_barrier
; #define PG8_STAGE(bufoff, gbase, voff) do { _Pragma("unroll") for (int _i = 0; _i < 2; ++_i) \
;         __builtin_amdgcn_global_load_lds((const unsigned*)((const char*)(gbase) + (voff)[_i]), (PG8_LAS unsigned*)(lds + (bufoff) + ldsw + _i * 8192), 16, 0, 0); } while (0)
; #define PG8_LDA(dst, b, h) do { _Pragma("unroll") for (int m = 0; m < 4; ++m) _Pragma("unroll") for (int k = 0; k < 2; ++k) dst[m][k] = *(const PG8_LAS bf16x8*)(lds + PG8_SA(b, h) + aoff + m * 2048 + k * 1024); } while (0)
; #define PG8_LDB(dst, b, h) do { _Pragma("unroll") for (int n = 0; n < 2; ++n) _Pragma("unroll") for (int k = 0; k < 2; ++k) dst[n][k] = *(const PG8_LAS bf16x8*)(lds + PG8_SB(b, h) + boff + n * 2048 + k * 1024); } while (0)
; #define PG8_MMA(ai, bj, At, Bt) do { __builtin_amdgcn_s_setprio(1); _Pragma("unroll") for (int m = 0; m < 4; ++m) _Pragma("unroll") for (int n = 0; n < 2; ++n) _Pragma("unroll") for (int k = 0; k < 2; ++k) \
;         acc[ai][bj][m][n] = __builtin_amdgcn_mfma_f32_16x16x32_bf16(Bt[n][k], At[m][k], acc[ai][bj][m][n], 0, 0, 0); __builtin_amdgcn_s_setprio(0); } while (0)
; #define PG8_WAIT_V(n) asm volatile("s_waitcnt vmcnt(" #n ")" ::: "memory")
; #define PG8_WAIT_L(n) asm volatile("s_waitcnt lgkmcnt(" #n ")" ::: "memory")
; #define PG8_BAR __builtin_amdgcn_s_barrier()
; #define PG8_SCHED __builtin_amdgcn_sched_barrier(0)
; template <class Epi, class Sched, bool ALIGN_EPI = false, bool SP2 = false>
; __device__ __forceinline__ void gemm_phase(PG8_LAS unsigned char* lds, const Gemm g, const Sched& S, const Epi& E, const int wid) {
;     ...
;             PG8_WAIT_V(8); PG8_WAIT_L(0); PG8_BAR; PG8_MMA(1, 0, At, B0); PG8_MMA(1, 1, At, B1); PG8_BAR; PG8_SCHED;
;             PG8_LDB(B0, 1, 0); PG8_LDB(B1, 1, 1); PG8_SCHED; PG8_LDA(At, 1, 0); PG8_STAGE(PG8_SA(0, 1), a2 + hstep, voffA);
;             PG8_WAIT_V(8); PG8_WAIT_L(0); PG8_BAR; PG8_MMA(0, 0, At, B0); PG8_MMA(0, 1, At, B1); PG8_BAR; PG8_SCHED;
	v_mfma_f32_16x16x32_bf16 v[60:63], v[152:155], v[184:187], v[60:63]
	v_mfma_f32_16x16x32_bf16 v[56:59], v[160:163], v[184:187], v[56:59]
	v_mfma_f32_16x16x32_bf16 v[52:55], v[152:155], v[192:195], v[52:55]
	v_mfma_f32_16x16x32_bf16 v[44:47], v[160:163], v[192:195], v[44:47]
	v_mfma_f32_16x16x32_bf16 v[36:39], v[152:155], v[200:203], v[36:39]
	v_mfma_f32_16x16x32_bf16 v[28:31], v[160:163], v[200:203], v[28:31]
	v_mfma_f32_16x16x32_bf16 v[20:23], v[152:155], v[212:215], v[20:23]
	v_mfma_f32_16x16x32_bf16 v[12:15], v[160:163], v[212:215], v[12:15]
	v_mfma_f32_16x16x32_bf16 v[60:63], v[156:159], v[188:191], v[60:63]
	v_mfma_f32_16x16x32_bf16 v[56:59], v[164:167], v[188:191], v[56:59]
	v_mfma_f32_16x16x32_bf16 v[52:55], v[156:159], v[196:199], v[52:55]
	v_mfma_f32_16x16x32_bf16 v[44:47], v[164:167], v[196:199], v[44:47]
	v_mfma_f32_16x16x32_bf16 v[36:39], v[156:159], v[204:207], v[36:39]
	v_mfma_f32_16x16x32_bf16 v[28:31], v[164:167], v[204:207], v[28:31]
	v_mfma_f32_16x16x32_bf16 v[20:23], v[156:159], v[216:219], v[20:23]
	v_mfma_f32_16x16x32_bf16 v[12:15], v[164:167], v[216:219], v[12:15]
	v_mfma_f32_16x16x32_bf16 v[48:51], v[168:171], v[184:187], v[48:51]
	v_mfma_f32_16x16x32_bf16 v[40:43], v[176:179], v[184:187], v[40:43]
	v_mfma_f32_16x16x32_bf16 v[32:35], v[168:171], v[192:195], v[32:35]
	v_mfma_f32_16x16x32_bf16 v[24:27], v[176:179], v[192:195], v[24:27]
	v_mfma_f32_16x16x32_bf16 v[16:19], v[168:171], v[200:203], v[16:19]
	v_mfma_f32_16x16x32_bf16 v[8:11], v[176:179], v[200:203], v[8:11]
	v_mfma_f32_16x16x32_bf16 v[4:7], v[168:171], v[212:215], v[4:7]
	v_mfma_f32_16x16x32_bf16 v[0:3], v[176:179], v[212:215], v[0:3]
	v_mfma_f32_16x16x32_bf16 v[48:51], v[172:175], v[188:191], v[48:51]
	v_mfma_f32_16x16x32_bf16 v[40:43], v[180:183], v[188:191], v[40:43]
	v_mfma_f32_16x16x32_bf16 v[32:35], v[172:175], v[196:199], v[32:35]
	v_mfma_f32_16x16x32_bf16 v[24:27], v[180:183], v[196:199], v[24:27]
	v_mfma_f32_16x16x32_bf16 v[16:19], v[172:175], v[204:207], v[16:19]
	v_mfma_f32_16x16x32_bf16 v[8:11], v[180:183], v[204:207], v[8:11]
	v_mfma_f32_16x16x32_bf16 v[4:7], v[172:175], v[216:219], v[4:7]
	v_mfma_f32_16x16x32_bf16 v[0:3], v[180:183], v[216:219], v[0:3]
	s_barrier
	s_add_i32 s48, 0, 0x18000
	s_add_i32 s49, 0, 0x1c000
	v_add_u32_e32 v164, s48, v147
	v_add_u32_e32 v180, s49, v147
	ds_read_b128 v[152:155], v164
	ds_read_b128 v[156:159], v164 offset:1024
	ds_read_b128 v[160:163], v164 offset:2048
	ds_read_b128 v[164:167], v164 offset:3072
	ds_read_b128 v[168:171], v180
	ds_read_b128 v[172:175], v180 offset:1024
	ds_read_b128 v[176:179], v180 offset:2048
	ds_read_b128 v[180:183], v180 offset:3072
	s_add_u32 s24, s24, 0x40000
	s_addc_u32 s25, s25, 0
	s_mov_b32 m0, s30
	v_lshl_add_u64 v[226:227], s[24:25], 0, v[134:135]
	ds_read_b128 v[184:187], v151 offset:32768
	ds_read_b128 v[188:191], v151 offset:33792
	ds_read_b128 v[192:195], v151 offset:34816
	ds_read_b128 v[196:199], v151 offset:35840
	ds_read_b128 v[200:203], v151 offset:36864
	ds_read_b128 v[204:207], v151 offset:37888
	ds_read_b128 v[212:215], v151 offset:38912
	ds_read_b128 v[216:219], v151 offset:39936
	global_load_lds_dwordx4 v[226:227], off
	v_lshl_add_u64 v[226:227], s[24:25], 0, v[130:131]
	s_mov_b32 m0, s31
	s_nop 0
	global_load_lds_dwordx4 v[226:227], off
	s_waitcnt vmcnt(8)
	s_waitcnt lgkmcnt(0)
	s_barrier
	v_mfma_f32_16x16x32_bf16 v[124:127], v[152:155], v[184:187], v[124:127]
	v_mfma_f32_16x16x32_bf16 v[120:123], v[160:163], v[184:187], v[120:123]
	v_mfma_f32_16x16x32_bf16 v[116:119], v[152:155], v[192:195], v[116:119]
	v_mfma_f32_16x16x32_bf16 v[108:111], v[160:163], v[192:195], v[108:111]
	v_mfma_f32_16x16x32_bf16 v[100:103], v[152:155], v[200:203], v[100:103]
	v_mfma_f32_16x16x32_bf16 v[92:95], v[160:163], v[200:203], v[92:95]
	v_mfma_f32_16x16x32_bf16 v[84:87], v[152:155], v[212:215], v[84:87]
	v_mfma_f32_16x16x32_bf16 v[76:79], v[160:163], v[212:215], v[76:79]
	v_mfma_f32_16x16x32_bf16 v[124:127], v[156:159], v[188:191], v[124:127]
	v_mfma_f32_16x16x32_bf16 v[120:123], v[164:167], v[188:191], v[120:123]
	v_mfma_f32_16x16x32_bf16 v[116:119], v[156:159], v[196:199], v[116:119]
	v_mfma_f32_16x16x32_bf16 v[108:111], v[164:167], v[196:199], v[108:111]
	v_mfma_f32_16x16x32_bf16 v[100:103], v[156:159], v[204:207], v[100:103]
	v_mfma_f32_16x16x32_bf16 v[92:95], v[164:167], v[204:207], v[92:95]
	v_mfma_f32_16x16x32_bf16 v[84:87], v[156:159], v[216:219], v[84:87]
	v_mfma_f32_16x16x32_bf16 v[76:79], v[164:167], v[216:219], v[76:79]
	v_mfma_f32_16x16x32_bf16 v[112:115], v[168:171], v[184:187], v[112:115]
	v_mfma_f32_16x16x32_bf16 v[104:107], v[176:179], v[184:187], v[104:107]
	v_mfma_f32_16x16x32_bf16 v[96:99], v[168:171], v[192:195], v[96:99]
	v_mfma_f32_16x16x32_bf16 v[88:91], v[176:179], v[192:195], v[88:91]
	v_mfma_f32_16x16x32_bf16 v[80:83], v[168:171], v[200:203], v[80:83]
	v_mfma_f32_16x16x32_bf16 v[72:75], v[176:179], v[200:203], v[72:75]
	v_mfma_f32_16x16x32_bf16 v[68:71], v[168:171], v[212:215], v[68:71]
	v_mfma_f32_16x16x32_bf16 v[64:67], v[176:179], v[212:215], v[64:67]
	v_mfma_f32_16x16x32_bf16 v[112:115], v[172:175], v[188:191], v[112:115]
	v_mfma_f32_16x16x32_bf16 v[104:107], v[180:183], v[188:191], v[104:107]
	v_mfma_f32_16x16x32_bf16 v[96:99], v[172:175], v[196:199], v[96:99]
	v_mfma_f32_16x16x32_bf16 v[88:91], v[180:183], v[196:199], v[88:91]
	v_mfma_f32_16x16x32_bf16 v[80:83], v[172:175], v[204:207], v[80:83]
	v_mfma_f32_16x16x32_bf16 v[72:75], v[180:183], v[204:207], v[72:75]
	v_mfma_f32_16x16x32_bf16 v[68:71], v[172:175], v[216:219], v[68:71]
	v_mfma_f32_16x16x32_bf16 v[64:67], v[180:183], v[216:219], v[64:67]
	s_barrier
; #define PG8_STAGE(bufoff, gbase, voff) do { _Pragma("unroll") for (int _i = 0; _i < 2; ++_i) \
;         __builtin_amdgcn_global_load_lds((const unsigned*)((const char*)(gbase) + (voff)[_i]), (PG8_LAS unsigned*)(lds + (bufoff) + ldsw + _i * 8192), 16, 0, 0); } while (0)
; #define PG8_LDA(dst, b, h) do { _Pragma("unroll") for (int m = 0; m < 4; ++m) _Pragma("unroll") for (int k = 0; k < 2; ++k) dst[m][k] = *(const PG8_LAS bf16x8*)(lds + PG8_SA(b, h) + aoff + m * 2048 + k * 1024); } while (0)
; #define PG8_MMA(ai, bj, At, Bt) do { __builtin_amdgcn_s_setprio(1); _Pragma("unroll") for (int m = 0; m < 4; ++m) _Pragma("unroll") for (int n = 0; n < 2; ++n) _Pragma("unroll") for (int k = 0; k < 2; ++k) \
;         acc[ai][bj][m][n] = __builtin_amdgcn_mfma_f32_16x16x32_bf16(Bt[n][k], At[m][k], acc[ai][bj][m][n], 0, 0, 0); __builtin_amdgcn_s_setprio(0); } while (0)
; #define PG8_WAIT_V(n) asm volatile("s_waitcnt vmcnt(" #n ")" ::: "memory")
; #define PG8_WAIT_L(n) asm volatile("s_waitcnt lgkmcnt(" #n ")" ::: "memory")
; #define PG8_BAR __builtin_amdgcn_s_barrier()
; #define PG8_SCHED __builtin_amdgcn_sched_barrier(0)
; template <class Epi, class Sched, bool ALIGN_EPI = false, bool SP2 = false>
; __device__ __forceinline__ void gemm_phase(PG8_LAS unsigned char* lds, const Gemm g, const Sched& S, const Epi& E, const int wid) {
;     ...
;             PG8_LDA(At, 1, 1); PG8_STAGE(PG8_SB(1, 0), b3, voffB); PG8_STAGE(PG8_SB(1, 1), b3 + hstep, voffB); PG8_STAGE(PG8_SA(1, 0), a3, voffA);
;             PG8_WAIT_V(8); PG8_WAIT_L(0); PG8_BAR; PG8_MMA(1, 0, At, B0); PG8_MMA(1, 1, At, B1); PG8_BAR; PG8_SCHED;
	s_add_i32 s24, s48, s26
	v_lshl_add_u64 v[144:145], v[144:145], 0, s[6:7]
	s_mov_b32 m0, s24
	ds_read_b128 v[184:187], v151 offset:49152
	ds_read_b128 v[188:191], v151 offset:50176
	ds_read_b128 v[192:195], v151 offset:51200
	ds_read_b128 v[196:199], v151 offset:52224
	ds_read_b128 v[200:203], v151 offset:53248
	ds_read_b128 v[204:207], v151 offset:54272
	ds_read_b128 v[212:215], v151 offset:55296
	ds_read_b128 v[216:219], v151 offset:56320
	global_load_lds_dwordx4 v[144:145], off
	s_add_i32 m0, s24, 0x2000
	s_add_u32 s22, s22, 0x40080
	v_lshl_add_u64 v[144:145], v[220:221], 0, s[6:7]
	s_addc_u32 s23, s23, 0
	s_add_i32 s24, s49, s26
	global_load_lds_dwordx4 v[144:145], off
	v_lshl_add_u64 v[144:145], s[22:23], 0, v[132:133]
	s_mov_b32 m0, s24
	s_nop 0
	global_load_lds_dwordx4 v[144:145], off
	v_lshl_add_u64 v[144:145], s[22:23], 0, v[128:129]
	s_add_i32 m0, s24, 0x2000
	s_nop 0
	global_load_lds_dwordx4 v[144:145], off
	v_lshl_add_u64 v[144:145], v[222:223], 0, s[6:7]
	s_mov_b32 m0, s37
	s_nop 0
	global_load_lds_dwordx4 v[144:145], off
	v_lshl_add_u64 v[144:145], v[224:225], 0, s[6:7]
	s_mov_b32 m0, s38
	s_nop 0
	global_load_lds_dwordx4 v[144:145], off
	s_waitcnt vmcnt(8)
	s_waitcnt lgkmcnt(0)
	s_barrier
	v_mfma_f32_16x16x32_bf16 v[60:63], v[152:155], v[184:187], v[60:63]
	v_mfma_f32_16x16x32_bf16 v[56:59], v[160:163], v[184:187], v[56:59]
	v_mfma_f32_16x16x32_bf16 v[52:55], v[152:155], v[192:195], v[52:55]
	v_mfma_f32_16x16x32_bf16 v[44:47], v[160:163], v[192:195], v[44:47]
	v_mfma_f32_16x16x32_bf16 v[36:39], v[152:155], v[200:203], v[36:39]
	v_mfma_f32_16x16x32_bf16 v[28:31], v[160:163], v[200:203], v[28:31]
	v_mfma_f32_16x16x32_bf16 v[20:23], v[152:155], v[212:215], v[20:23]
	v_mfma_f32_16x16x32_bf16 v[12:15], v[160:163], v[212:215], v[12:15]
	v_mfma_f32_16x16x32_bf16 v[60:63], v[156:159], v[188:191], v[60:63]
	v_mfma_f32_16x16x32_bf16 v[56:59], v[164:167], v[188:191], v[56:59]
	v_mfma_f32_16x16x32_bf16 v[52:55], v[156:159], v[196:199], v[52:55]
	v_mfma_f32_16x16x32_bf16 v[44:47], v[164:167], v[196:199], v[44:47]
	v_mfma_f32_16x16x32_bf16 v[36:39], v[156:159], v[204:207], v[36:39]
	v_mfma_f32_16x16x32_bf16 v[28:31], v[164:167], v[204:207], v[28:31]
	v_mfma_f32_16x16x32_bf16 v[20:23], v[156:159], v[216:219], v[20:23]
	v_mfma_f32_16x16x32_bf16 v[12:15], v[164:167], v[216:219], v[12:15]
	v_mfma_f32_16x16x32_bf16 v[48:51], v[168:171], v[184:187], v[48:51]
	v_mfma_f32_16x16x32_bf16 v[40:43], v[176:179], v[184:187], v[40:43]
	v_mfma_f32_16x16x32_bf16 v[32:35], v[168:171], v[192:195], v[32:35]
	v_mfma_f32_16x16x32_bf16 v[24:27], v[176:179], v[192:195], v[24:27]
	v_mfma_f32_16x16x32_bf16 v[16:19], v[168:171], v[200:203], v[16:19]
	v_mfma_f32_16x16x32_bf16 v[8:11], v[176:179], v[200:203], v[8:11]
	v_mfma_f32_16x16x32_bf16 v[4:7], v[168:171], v[212:215], v[4:7]
	v_mfma_f32_16x16x32_bf16 v[0:3], v[176:179], v[212:215], v[0:3]
	v_mfma_f32_16x16x32_bf16 v[48:51], v[172:175], v[188:191], v[48:51]
	v_mfma_f32_16x16x32_bf16 v[40:43], v[180:183], v[188:191], v[40:43]
	v_mfma_f32_16x16x32_bf16 v[32:35], v[172:175], v[196:199], v[32:35]
	v_mfma_f32_16x16x32_bf16 v[24:27], v[180:183], v[196:199], v[24:27]
	v_mfma_f32_16x16x32_bf16 v[16:19], v[172:175], v[204:207], v[16:19]
	v_mfma_f32_16x16x32_bf16 v[8:11], v[180:183], v[204:207], v[8:11]
	v_mfma_f32_16x16x32_bf16 v[4:7], v[172:175], v[216:219], v[4:7]
	v_mfma_f32_16x16x32_bf16 v[0:3], v[180:183], v[216:219], v[0:3]
	s_barrier
	s_add_i32 s47, s47, 2
	s_add_u32 s20, s20, 0x100
	s_addc_u32 s21, s21, 0
	s_add_u32 s45, s45, 0x100
	s_addc_u32 s46, s46, 0
	s_cmp_gt_u32 s47, 13
	s_cbranch_scc0 .LBB0_882

; #define PG8_STAGE(bufoff, gbase, voff) do { _Pragma("unroll") for (int _i = 0; _i < 2; ++_i) \
;         __builtin_amdgcn_global_load_lds((const unsigned*)((const char*)(gbase) + (voff)[_i]), (PG8_LAS unsigned*)(lds + (bufoff) + ldsw + _i * 8192), 16, 0, 0); } while (0)
; #define PG8_LDA(dst, b, h) do { _Pragma("unroll") for (int m = 0; m < 4; ++m) _Pragma("unroll") for (int k = 0; k < 2; ++k) dst[m][k] = *(const PG8_LAS bf16x8*)(lds + PG8_SA(b, h) + aoff + m * 2048 + k * 1024); } while (0)
; #define PG8_LDB(dst, b, h) do { _Pragma("unroll") for (int n = 0; n < 2; ++n) _Pragma("unroll") for (int k = 0; k < 2; ++k) dst[n][k] = *(const PG8_LAS bf16x8*)(lds + PG8_SB(b, h) + boff + n * 2048 + k * 1024); } while (0)
; #define PG8_MMA(ai, bj, At, Bt) do { __builtin_amdgcn_s_setprio(1); _Pragma("unroll") for (int m = 0; m < 4; ++m) _Pragma("unroll") for (int n = 0; n < 2; ++n) _Pragma("unroll") for (int k = 0; k < 2; ++k) \
;         acc[ai][bj][m][n] = __builtin_amdgcn_mfma_f32_16x16x32_bf16(Bt[n][k], At[m][k], acc[ai][bj][m][n], 0, 0, 0); __builtin_amdgcn_s_setprio(0); } while (0)
; #define PG8_WAIT_V(n) asm volatile("s_waitcnt vmcnt(" #n ")" ::: "memory")
; #define PG8_WAIT_L(n) asm volatile("s_waitcnt lgkmcnt(" #n ")" ::: "memory")
; #define PG8_BAR __builtin_amdgcn_s_barrier()
; #define PG8_SCHED __builtin_amdgcn_sched_barrier(0)
; template <class Epi, class Sched, bool ALIGN_EPI = false, bool SP2 = false>
; __device__ __forceinline__ void gemm_phase(PG8_LAS unsigned char* lds, const Gemm g, const Sched& S, const Epi& E, const int wid) {
;     ...
;             PG8_LDB(B0, 0, 0); PG8_LDB(B1, 0, 1); PG8_SCHED; PG8_LDA(At, 0, 0); PG8_STAGE(PG8_SA(1, 1), a1 + hstep, voffA);
;             PG8_WAIT_V(8); PG8_WAIT_L(0); PG8_BAR; PG8_MMA(0, 0, At, B0); PG8_MMA(0, 1, At, B1); PG8_BAR; PG8_SCHED;
;             PG8_LDA(At, 0, 1); PG8_STAGE(PG8_SB(0, 0), b2, voffB); PG8_STAGE(PG8_SB(0, 1), b2 + hstep, voffB); PG8_STAGE(PG8_SA(0, 0), a2, voffA);
;             PG8_WAIT_V(8); PG8_WAIT_L(0); PG8_BAR; PG8_MMA(1, 0, At, B0); PG8_MMA(1, 1, At, B1); PG8_BAR; PG8_SCHED;
.LBB0_1786:
	v_add_u32_e32 v164, s41, v150
	v_add_u32_e32 v180, s42, v150
	s_add_u32 s22, s8, s20
	ds_read_b128 v[152:155], v164
	ds_read_b128 v[156:159], v164 offset:1024
	ds_read_b128 v[160:163], v164 offset:2048
	ds_read_b128 v[164:167], v164 offset:3072
	ds_read_b128 v[168:171], v180
	ds_read_b128 v[172:175], v180 offset:1024
	ds_read_b128 v[176:179], v180 offset:2048
	ds_read_b128 v[180:183], v180 offset:3072
	s_addc_u32 s23, s9, s21
	s_add_u32 s22, s22, 0x100
	s_addc_u32 s23, s23, 0
	s_add_u32 s49, s44, s20
	s_addc_u32 s50, s45, s21
	s_cmpk_eq_i32 s20, 0x700
	s_cselect_b32 s25, s15, s23
	s_cselect_b32 s24, s46, s22
	s_cselect_b32 s23, s13, s50
	s_cselect_b32 s22, s47, s49
	v_lshl_add_u64 v[206:207], v[144:145], 0, s[20:21]
	s_add_i32 m0, s33, 0xc000
	ds_read_b128 v[186:189], v151
	ds_read_b128 v[190:193], v151 offset:1024
	ds_read_b128 v[194:197], v151 offset:2048
	ds_read_b128 v[198:201], v151 offset:3072
	ds_read_b128 v[202:205], v151 offset:4096
	ds_read_b128 v[210:213], v151 offset:5120
	ds_read_b128 v[214:217], v151 offset:6144
	ds_read_b128 v[218:221], v151 offset:7168
	global_load_lds_dwordx4 v[206:207], off
	v_lshl_add_u64 v[206:207], v[146:147], 0, s[20:21]
	s_add_i32 m0, s33, 0xe000
	s_nop 0
	global_load_lds_dwordx4 v[206:207], off
	s_waitcnt vmcnt(8)
	s_waitcnt lgkmcnt(0)
	s_barrier
	v_mfma_f32_16x16x32_bf16 v[124:127], v[152:155], v[186:189], v[124:127]
	v_mfma_f32_16x16x32_bf16 v[120:123], v[160:163], v[186:189], v[120:123]
	v_mfma_f32_16x16x32_bf16 v[112:115], v[152:155], v[194:197], v[112:115]
	v_mfma_f32_16x16x32_bf16 v[104:107], v[160:163], v[194:197], v[104:107]
	v_mfma_f32_16x16x32_bf16 v[96:99], v[152:155], v[202:205], v[96:99]
	v_mfma_f32_16x16x32_bf16 v[88:91], v[160:163], v[202:205], v[88:91]
	v_mfma_f32_16x16x32_bf16 v[80:83], v[152:155], v[214:217], v[80:83]
	v_mfma_f32_16x16x32_bf16 v[72:75], v[160:163], v[214:217], v[72:75]
	v_mfma_f32_16x16x32_bf16 v[124:127], v[156:159], v[190:193], v[124:127]
	v_mfma_f32_16x16x32_bf16 v[120:123], v[164:167], v[190:193], v[120:123]
	v_mfma_f32_16x16x32_bf16 v[112:115], v[156:159], v[198:201], v[112:115]
	v_mfma_f32_16x16x32_bf16 v[104:107], v[164:167], v[198:201], v[104:107]
	v_mfma_f32_16x16x32_bf16 v[96:99], v[156:159], v[210:213], v[96:99]
	v_mfma_f32_16x16x32_bf16 v[88:91], v[164:167], v[210:213], v[88:91]
	v_mfma_f32_16x16x32_bf16 v[80:83], v[156:159], v[218:221], v[80:83]
	v_mfma_f32_16x16x32_bf16 v[72:75], v[164:167], v[218:221], v[72:75]
	v_mfma_f32_16x16x32_bf16 v[116:119], v[168:171], v[186:189], v[116:119]
	v_mfma_f32_16x16x32_bf16 v[108:111], v[176:179], v[186:189], v[108:111]
	v_mfma_f32_16x16x32_bf16 v[100:103], v[168:171], v[194:197], v[100:103]
	v_mfma_f32_16x16x32_bf16 v[92:95], v[176:179], v[194:197], v[92:95]
	v_mfma_f32_16x16x32_bf16 v[84:87], v[168:171], v[202:205], v[84:87]
	v_mfma_f32_16x16x32_bf16 v[76:79], v[176:179], v[202:205], v[76:79]
	v_mfma_f32_16x16x32_bf16 v[68:71], v[168:171], v[214:217], v[68:71]
	v_mfma_f32_16x16x32_bf16 v[64:67], v[176:179], v[214:217], v[64:67]
	v_mfma_f32_16x16x32_bf16 v[116:119], v[172:175], v[190:193], v[116:119]
	v_mfma_f32_16x16x32_bf16 v[108:111], v[180:183], v[190:193], v[108:111]
	v_mfma_f32_16x16x32_bf16 v[100:103], v[172:175], v[198:201], v[100:103]
	v_mfma_f32_16x16x32_bf16 v[92:95], v[180:183], v[198:201], v[92:95]
	v_mfma_f32_16x16x32_bf16 v[84:87], v[172:175], v[210:213], v[84:87]
	v_mfma_f32_16x16x32_bf16 v[76:79], v[180:183], v[210:213], v[76:79]
	v_mfma_f32_16x16x32_bf16 v[68:71], v[172:175], v[218:221], v[68:71]
	v_mfma_f32_16x16x32_bf16 v[64:67], v[180:183], v[218:221], v[64:67]
	s_barrier
	s_add_i32 s49, s41, s31
	v_lshl_add_u64 v[206:207], s[22:23], 0, v[130:131]
	s_mov_b32 m0, s49
	ds_read_b128 v[186:189], v151 offset:16384
	ds_read_b128 v[190:193], v151 offset:17408
	ds_read_b128 v[194:197], v151 offset:18432
	ds_read_b128 v[198:201], v151 offset:19456
	ds_read_b128 v[202:205], v151 offset:20480
	ds_read_b128 v[210:213], v151 offset:21504
	ds_read_b128 v[214:217], v151 offset:22528
	ds_read_b128 v[218:221], v151 offset:23552
	global_load_lds_dwordx4 v[206:207], off
	s_add_i32 m0, s49, 0x2000
	s_add_u32 s50, s22, 0x40000
	v_lshl_add_u64 v[222:223], s[22:23], 0, v[134:135]
	s_addc_u32 s51, s23, 0
	s_add_i32 s49, s42, s31
	global_load_lds_dwordx4 v[222:223], off
	v_lshl_add_u64 v[224:225], s[50:51], 0, v[130:131]
	s_mov_b32 m0, s49
	v_lshl_add_u64 v[226:227], s[24:25], 0, v[132:133]
	global_load_lds_dwordx4 v[224:225], off
	v_lshl_add_u64 v[224:225], s[50:51], 0, v[134:135]
	s_add_i32 m0, s49, 0x2000
	s_nop 0
	global_load_lds_dwordx4 v[224:225], off
	v_lshl_add_u64 v[224:225], s[24:25], 0, v[128:129]
	s_mov_b32 m0, s33
	s_nop 0
	global_load_lds_dwordx4 v[224:225], off
	s_mov_b32 m0, s34
	s_nop 0
	global_load_lds_dwordx4 v[226:227], off
	s_waitcnt vmcnt(8)
	s_waitcnt lgkmcnt(0)
	s_barrier
; #define PG8_STAGE(bufoff, gbase, voff) do { _Pragma("unroll") for (int _i = 0; _i < 2; ++_i) \
;         __builtin_amdgcn_global_load_lds((const unsigned*)((const char*)(gbase) + (voff)[_i]), (PG8_LAS unsigned*)(lds + (bufoff) + ldsw + _i * 8192), 16, 0, 0); } while (0)
; #define PG8_LDA(dst, b, h) do { _Pragma("unroll") for (int m = 0; m < 4; ++m) _Pragma("unroll") for (int k = 0; k < 2; ++k) dst[m][k] = *(const PG8_LAS bf16x8*)(lds + PG8_SA(b, h) + aoff + m * 2048 + k * 1024); } while (0)
; #define PG8_LDB(dst, b, h) do { _Pragma("unroll") for (int n = 0; n < 2; ++n) _Pragma("unroll") for (int k = 0; k < 2; ++k) dst[n][k] = *(const PG8_LAS bf16x8*)(lds + PG8_SB(b, h) + boff + n * 2048 + k * 1024); } while (0)
; #define PG8_MMA(ai, bj, At, Bt) do { __builtin_amdgcn_s_setprio(1); _Pragma("unroll") for (int m = 0; m < 4; ++m) _Pragma("unroll") for (int n = 0; n < 2; ++n) _Pragma("unroll") for (int k = 0; k < 2; ++k) \
;         acc[ai][bj][m][n] = __builtin_amdgcn_mfma_f32_16x16x32_bf16(Bt[n][k], At[m][k], acc[ai][bj][m][n], 0, 0, 0); __builtin_amdgcn_s_setprio(0); } while (0)
; #define PG8_WAIT_V(n) asm volatile("s_waitcnt vmcnt(" #n ")" ::: "memory")
; #define PG8_WAIT_L(n) asm volatile("s_waitcnt lgkmcnt(" #n ")" ::: "memory")
; #define PG8_BAR __builtin_amdgcn_s_barrier()
; #define PG8_SCHED __builtin_amdgcn_sched_barrier(0)
; template <class Epi, class Sched, bool ALIGN_EPI = false, bool SP2 = false>
; __device__ __forceinline__ void gemm_phase(PG8_LAS unsigned char* lds, const Gemm g, const Sched& S, const Epi& E, const int wid) {
;     ...
;             PG8_WAIT_V(8); PG8_WAIT_L(0); PG8_BAR; PG8_MMA(1, 0, At, B0); PG8_MMA(1, 1, At, B1); PG8_BAR; PG8_SCHED;
;             PG8_LDB(B0, 1, 0); PG8_LDB(B1, 1, 1); PG8_SCHED; PG8_LDA(At, 1, 0); PG8_STAGE(PG8_SA(0, 1), a2 + hstep, voffA);
;             PG8_WAIT_V(8); PG8_WAIT_L(0); PG8_BAR; PG8_MMA(0, 0, At, B0); PG8_MMA(0, 1, At, B1); PG8_BAR; PG8_SCHED;
	v_mfma_f32_16x16x32_bf16 v[60:63], v[152:155], v[186:189], v[60:63]
	v_mfma_f32_16x16x32_bf16 v[56:59], v[160:163], v[186:189], v[56:59]
	v_mfma_f32_16x16x32_bf16 v[44:47], v[152:155], v[194:197], v[44:47]
	v_mfma_f32_16x16x32_bf16 v[40:43], v[160:163], v[194:197], v[40:43]
	v_mfma_f32_16x16x32_bf16 v[28:31], v[152:155], v[202:205], v[28:31]
	v_mfma_f32_16x16x32_bf16 v[24:27], v[160:163], v[202:205], v[24:27]
	v_mfma_f32_16x16x32_bf16 v[12:15], v[152:155], v[214:217], v[12:15]
	v_mfma_f32_16x16x32_bf16 v[8:11], v[160:163], v[214:217], v[8:11]
	v_mfma_f32_16x16x32_bf16 v[60:63], v[156:159], v[190:193], v[60:63]
	v_mfma_f32_16x16x32_bf16 v[56:59], v[164:167], v[190:193], v[56:59]
	v_mfma_f32_16x16x32_bf16 v[44:47], v[156:159], v[198:201], v[44:47]
	v_mfma_f32_16x16x32_bf16 v[40:43], v[164:167], v[198:201], v[40:43]
	v_mfma_f32_16x16x32_bf16 v[28:31], v[156:159], v[210:213], v[28:31]
	v_mfma_f32_16x16x32_bf16 v[24:27], v[164:167], v[210:213], v[24:27]
	v_mfma_f32_16x16x32_bf16 v[12:15], v[156:159], v[218:221], v[12:15]
	v_mfma_f32_16x16x32_bf16 v[8:11], v[164:167], v[218:221], v[8:11]
	v_mfma_f32_16x16x32_bf16 v[52:55], v[168:171], v[186:189], v[52:55]
	v_mfma_f32_16x16x32_bf16 v[48:51], v[176:179], v[186:189], v[48:51]
	v_mfma_f32_16x16x32_bf16 v[36:39], v[168:171], v[194:197], v[36:39]
	v_mfma_f32_16x16x32_bf16 v[32:35], v[176:179], v[194:197], v[32:35]
	v_mfma_f32_16x16x32_bf16 v[20:23], v[168:171], v[202:205], v[20:23]
	v_mfma_f32_16x16x32_bf16 v[16:19], v[176:179], v[202:205], v[16:19]
	v_mfma_f32_16x16x32_bf16 v[4:7], v[168:171], v[214:217], v[4:7]
	v_mfma_f32_16x16x32_bf16 v[0:3], v[176:179], v[214:217], v[0:3]
	v_mfma_f32_16x16x32_bf16 v[52:55], v[172:175], v[190:193], v[52:55]
	v_mfma_f32_16x16x32_bf16 v[48:51], v[180:183], v[190:193], v[48:51]
	v_mfma_f32_16x16x32_bf16 v[36:39], v[172:175], v[198:201], v[36:39]
	v_mfma_f32_16x16x32_bf16 v[32:35], v[180:183], v[198:201], v[32:35]
	v_mfma_f32_16x16x32_bf16 v[20:23], v[172:175], v[210:213], v[20:23]
	v_mfma_f32_16x16x32_bf16 v[16:19], v[180:183], v[210:213], v[16:19]
	v_mfma_f32_16x16x32_bf16 v[4:7], v[172:175], v[218:221], v[4:7]
	v_mfma_f32_16x16x32_bf16 v[0:3], v[180:183], v[218:221], v[0:3]
	s_barrier
	s_add_i32 s49, 0, 0x18000
	s_add_i32 s50, 0, 0x1c000
	v_add_u32_e32 v164, s49, v150
	v_add_u32_e32 v180, s50, v150
	ds_read_b128 v[152:155], v164
	ds_read_b128 v[156:159], v164 offset:1024
	ds_read_b128 v[160:163], v164 offset:2048
	ds_read_b128 v[164:167], v164 offset:3072
	ds_read_b128 v[168:171], v180
	ds_read_b128 v[172:175], v180 offset:1024
	ds_read_b128 v[176:179], v180 offset:2048
	ds_read_b128 v[180:183], v180 offset:3072
	s_add_u32 s24, s24, 0x40000
	s_addc_u32 s25, s25, 0
	s_mov_b32 m0, s35
	v_lshl_add_u64 v[228:229], s[24:25], 0, v[128:129]
	ds_read_b128 v[186:189], v151 offset:32768
	ds_read_b128 v[190:193], v151 offset:33792
	ds_read_b128 v[194:197], v151 offset:34816
	ds_read_b128 v[198:201], v151 offset:35840
	ds_read_b128 v[202:205], v151 offset:36864
	ds_read_b128 v[210:213], v151 offset:37888
	ds_read_b128 v[214:217], v151 offset:38912
	ds_read_b128 v[218:221], v151 offset:39936
	global_load_lds_dwordx4 v[228:229], off
	v_lshl_add_u64 v[228:229], s[24:25], 0, v[132:133]
	s_mov_b32 m0, s36
	s_nop 0
	global_load_lds_dwordx4 v[228:229], off
	s_waitcnt vmcnt(8)
	s_waitcnt lgkmcnt(0)
	s_barrier
	v_mfma_f32_16x16x32_bf16 v[124:127], v[152:155], v[186:189], v[124:127]
	v_mfma_f32_16x16x32_bf16 v[120:123], v[160:163], v[186:189], v[120:123]
	v_mfma_f32_16x16x32_bf16 v[112:115], v[152:155], v[194:197], v[112:115]
	v_mfma_f32_16x16x32_bf16 v[104:107], v[160:163], v[194:197], v[104:107]
	v_mfma_f32_16x16x32_bf16 v[96:99], v[152:155], v[202:205], v[96:99]
	v_mfma_f32_16x16x32_bf16 v[88:91], v[160:163], v[202:205], v[88:91]
	v_mfma_f32_16x16x32_bf16 v[80:83], v[152:155], v[214:217], v[80:83]
	v_mfma_f32_16x16x32_bf16 v[72:75], v[160:163], v[214:217], v[72:75]
	v_mfma_f32_16x16x32_bf16 v[124:127], v[156:159], v[190:193], v[124:127]
	v_mfma_f32_16x16x32_bf16 v[120:123], v[164:167], v[190:193], v[120:123]
	v_mfma_f32_16x16x32_bf16 v[112:115], v[156:159], v[198:201], v[112:115]
	v_mfma_f32_16x16x32_bf16 v[104:107], v[164:167], v[198:201], v[104:107]
	v_mfma_f32_16x16x32_bf16 v[96:99], v[156:159], v[210:213], v[96:99]
	v_mfma_f32_16x16x32_bf16 v[88:91], v[164:167], v[210:213], v[88:91]
	v_mfma_f32_16x16x32_bf16 v[80:83], v[156:159], v[218:221], v[80:83]
	v_mfma_f32_16x16x32_bf16 v[72:75], v[164:167], v[218:221], v[72:75]
	v_mfma_f32_16x16x32_bf16 v[116:119], v[168:171], v[186:189], v[116:119]
	v_mfma_f32_16x16x32_bf16 v[108:111], v[176:179], v[186:189], v[108:111]
	v_mfma_f32_16x16x32_bf16 v[100:103], v[168:171], v[194:197], v[100:103]
	v_mfma_f32_16x16x32_bf16 v[92:95], v[176:179], v[194:197], v[92:95]
	v_mfma_f32_16x16x32_bf16 v[84:87], v[168:171], v[202:205], v[84:87]
	v_mfma_f32_16x16x32_bf16 v[76:79], v[176:179], v[202:205], v[76:79]
	v_mfma_f32_16x16x32_bf16 v[68:71], v[168:171], v[214:217], v[68:71]
	v_mfma_f32_16x16x32_bf16 v[64:67], v[176:179], v[214:217], v[64:67]
	v_mfma_f32_16x16x32_bf16 v[116:119], v[172:175], v[190:193], v[116:119]
	v_mfma_f32_16x16x32_bf16 v[108:111], v[180:183], v[190:193], v[108:111]
	v_mfma_f32_16x16x32_bf16 v[100:103], v[172:175], v[198:201], v[100:103]
	v_mfma_f32_16x16x32_bf16 v[92:95], v[180:183], v[198:201], v[92:95]
	v_mfma_f32_16x16x32_bf16 v[84:87], v[172:175], v[210:213], v[84:87]
	v_mfma_f32_16x16x32_bf16 v[76:79], v[180:183], v[210:213], v[76:79]
	v_mfma_f32_16x16x32_bf16 v[68:71], v[172:175], v[218:221], v[68:71]
	v_mfma_f32_16x16x32_bf16 v[64:67], v[180:183], v[218:221], v[64:67]
	s_barrier
; #define PG8_STAGE(bufoff, gbase, voff) do { _Pragma("unroll") for (int _i = 0; _i < 2; ++_i) \
;         __builtin_amdgcn_global_load_lds((const unsigned*)((const char*)(gbase) + (voff)[_i]), (PG8_LAS unsigned*)(lds + (bufoff) + ldsw + _i * 8192), 16, 0, 0); } while (0)
; #define PG8_LDA(dst, b, h) do { _Pragma("unroll") for (int m = 0; m < 4; ++m) _Pragma("unroll") for (int k = 0; k < 2; ++k) dst[m][k] = *(const PG8_LAS bf16x8*)(lds + PG8_SA(b, h) + aoff + m * 2048 + k * 1024); } while (0)
; #define PG8_MMA(ai, bj, At, Bt) do { __builtin_amdgcn_s_setprio(1); _Pragma("unroll") for (int m = 0; m < 4; ++m) _Pragma("unroll") for (int n = 0; n < 2; ++n) _Pragma("unroll") for (int k = 0; k < 2; ++k) \
;         acc[ai][bj][m][n] = __builtin_amdgcn_mfma_f32_16x16x32_bf16(Bt[n][k], At[m][k], acc[ai][bj][m][n], 0, 0, 0); __builtin_amdgcn_s_setprio(0); } while (0)
; #define PG8_WAIT_V(n) asm volatile("s_waitcnt vmcnt(" #n ")" ::: "memory")
; #define PG8_WAIT_L(n) asm volatile("s_waitcnt lgkmcnt(" #n ")" ::: "memory")
; #define PG8_BAR __builtin_amdgcn_s_barrier()
; #define PG8_SCHED __builtin_amdgcn_sched_barrier(0)
; template <class Epi, class Sched, bool ALIGN_EPI = false, bool SP2 = false>
; __device__ __forceinline__ void gemm_phase(PG8_LAS unsigned char* lds, const Gemm g, const Sched& S, const Epi& E, const int wid) {
;     ...
;             PG8_LDA(At, 1, 1); PG8_STAGE(PG8_SB(1, 0), b3, voffB); PG8_STAGE(PG8_SB(1, 1), b3 + hstep, voffB); PG8_STAGE(PG8_SA(1, 0), a3, voffA);
;             PG8_WAIT_V(8); PG8_WAIT_L(0); PG8_BAR; PG8_MMA(1, 0, At, B0); PG8_MMA(1, 1, At, B1); PG8_BAR; PG8_SCHED;
;     ...
;         if (!has_next) break;
; #pragma unroll
;         for (int a = 0; a < 2; ++a)
; #pragma unroll
;             for (int b = 0; b < 2; ++b)
; #pragma unroll
;                 for (int m = 0; m < 4; ++m)
; #pragma unroll
;                     for (int n = 0; n < 2; ++n) acc[a][b][m][n] = (f32x4){0.f, 0.f, 0.f, 0.f};
;         cur = nxt; cA = nA; cB = nB; ++ui;
	s_add_i32 s24, s49, s31
	v_lshl_add_u64 v[206:207], v[206:207], 0, s[10:11]
	s_mov_b32 m0, s24
	ds_read_b128 v[186:189], v151 offset:49152
	ds_read_b128 v[190:193], v151 offset:50176
	ds_read_b128 v[194:197], v151 offset:51200
	ds_read_b128 v[198:201], v151 offset:52224
	ds_read_b128 v[202:205], v151 offset:53248
	ds_read_b128 v[210:213], v151 offset:54272
	ds_read_b128 v[214:217], v151 offset:55296
	ds_read_b128 v[218:221], v151 offset:56320
	global_load_lds_dwordx4 v[206:207], off
	s_add_i32 m0, s24, 0x2000
	s_add_u32 s22, s22, 0x40080
	v_lshl_add_u64 v[206:207], v[222:223], 0, s[10:11]
	s_addc_u32 s23, s23, 0
	s_add_i32 s24, s50, s31
	global_load_lds_dwordx4 v[206:207], off
	v_lshl_add_u64 v[206:207], s[22:23], 0, v[130:131]
	s_mov_b32 m0, s24
	s_nop 0
	global_load_lds_dwordx4 v[206:207], off
	v_lshl_add_u64 v[206:207], s[22:23], 0, v[134:135]
	s_add_i32 m0, s24, 0x2000
	s_nop 0
	global_load_lds_dwordx4 v[206:207], off
	v_lshl_add_u64 v[206:207], v[224:225], 0, s[10:11]
	s_mov_b32 m0, s38
	s_nop 0
	global_load_lds_dwordx4 v[206:207], off
	v_lshl_add_u64 v[206:207], v[226:227], 0, s[10:11]
	s_mov_b32 m0, s39
	s_nop 0
	global_load_lds_dwordx4 v[206:207], off
	s_waitcnt vmcnt(8)
	s_waitcnt lgkmcnt(0)
	s_barrier
	v_mfma_f32_16x16x32_bf16 v[60:63], v[152:155], v[186:189], v[60:63]
	v_mfma_f32_16x16x32_bf16 v[56:59], v[160:163], v[186:189], v[56:59]
	v_mfma_f32_16x16x32_bf16 v[44:47], v[152:155], v[194:197], v[44:47]
	v_mfma_f32_16x16x32_bf16 v[40:43], v[160:163], v[194:197], v[40:43]
	v_mfma_f32_16x16x32_bf16 v[28:31], v[152:155], v[202:205], v[28:31]
	v_mfma_f32_16x16x32_bf16 v[24:27], v[160:163], v[202:205], v[24:27]
	v_mfma_f32_16x16x32_bf16 v[12:15], v[152:155], v[214:217], v[12:15]
	v_mfma_f32_16x16x32_bf16 v[8:11], v[160:163], v[214:217], v[8:11]
	v_mfma_f32_16x16x32_bf16 v[60:63], v[156:159], v[190:193], v[60:63]
	v_mfma_f32_16x16x32_bf16 v[56:59], v[164:167], v[190:193], v[56:59]
	v_mfma_f32_16x16x32_bf16 v[44:47], v[156:159], v[198:201], v[44:47]
	v_mfma_f32_16x16x32_bf16 v[40:43], v[164:167], v[198:201], v[40:43]
	v_mfma_f32_16x16x32_bf16 v[28:31], v[156:159], v[210:213], v[28:31]
	v_mfma_f32_16x16x32_bf16 v[24:27], v[164:167], v[210:213], v[24:27]
	v_mfma_f32_16x16x32_bf16 v[12:15], v[156:159], v[218:221], v[12:15]
	v_mfma_f32_16x16x32_bf16 v[8:11], v[164:167], v[218:221], v[8:11]
	v_mfma_f32_16x16x32_bf16 v[52:55], v[168:171], v[186:189], v[52:55]
	v_mfma_f32_16x16x32_bf16 v[48:51], v[176:179], v[186:189], v[48:51]
	v_mfma_f32_16x16x32_bf16 v[36:39], v[168:171], v[194:197], v[36:39]
	v_mfma_f32_16x16x32_bf16 v[32:35], v[176:179], v[194:197], v[32:35]
	v_mfma_f32_16x16x32_bf16 v[20:23], v[168:171], v[202:205], v[20:23]
	v_mfma_f32_16x16x32_bf16 v[16:19], v[176:179], v[202:205], v[16:19]
	v_mfma_f32_16x16x32_bf16 v[4:7], v[168:171], v[214:217], v[4:7]
	v_mfma_f32_16x16x32_bf16 v[0:3], v[176:179], v[214:217], v[0:3]
	v_mfma_f32_16x16x32_bf16 v[52:55], v[172:175], v[190:193], v[52:55]
	v_mfma_f32_16x16x32_bf16 v[48:51], v[180:183], v[190:193], v[48:51]
	v_mfma_f32_16x16x32_bf16 v[36:39], v[172:175], v[198:201], v[36:39]
	v_mfma_f32_16x16x32_bf16 v[32:35], v[180:183], v[198:201], v[32:35]
	v_mfma_f32_16x16x32_bf16 v[20:23], v[172:175], v[210:213], v[20:23]
	v_mfma_f32_16x16x32_bf16 v[16:19], v[180:183], v[210:213], v[16:19]
	v_mfma_f32_16x16x32_bf16 v[4:7], v[172:175], v[218:221], v[4:7]
	v_mfma_f32_16x16x32_bf16 v[0:3], v[180:183], v[218:221], v[0:3]
	s_barrier
	s_add_i32 s48, s48, 2
	s_add_u32 s20, s20, 0x100
	s_addc_u32 s21, s21, 0
	s_cmp_gt_u32 s48, 13
	s_cbranch_scc0 .LBB0_1786
	s_add_u32 s20, s44, 0xffffff00
	s_addc_u32 s21, s45, -1
	s_andn2_b64 vcc, exec, s[6:7]
	s_cbranch_vccnz .LBB0_1777
	v_mov_b32_e32 v0, 0
	s_mov_b32 s2, s12
	s_mov_b32 s0, s14
	s_mov_b64 s[8:9], s[18:19]
	s_mov_b32 s40, s43
	v_mov_b32_e32 v1, v0
	v_mov_b32_e32 v2, v0
	v_mov_b32_e32 v3, v0
	v_mov_b32_e32 v4, v0
	v_mov_b32_e32 v5, v0
	v_mov_b32_e32 v6, v0
	v_mov_b32_e32 v7, v0
	v_mov_b32_e32 v16, v0
	v_mov_b32_e32 v17, v0
	v_mov_b32_e32 v18, v0
	v_mov_b32_e32 v19, v0
	v_mov_b32_e32 v20, v0
	v_mov_b32_e32 v21, v0
	v_mov_b32_e32 v22, v0
	v_mov_b32_e32 v23, v0
	v_mov_b32_e32 v32, v0
	v_mov_b32_e32 v33, v0
	v_mov_b32_e32 v34, v0
	v_mov_b32_e32 v35, v0
	v_mov_b32_e32 v36, v0
	v_mov_b32_e32 v37, v0
	v_mov_b32_e32 v38, v0
	v_mov_b32_e32 v39, v0
	v_mov_b32_e32 v48, v0
	v_mov_b32_e32 v49, v0
	v_mov_b32_e32 v50, v0
	v_mov_b32_e32 v51, v0
	v_mov_b32_e32 v52, v0
	v_mov_b32_e32 v53, v0
	v_mov_b32_e32 v54, v0
	v_mov_b32_e32 v55, v0
	v_mov_b32_e32 v8, v0
	v_mov_b32_e32 v9, v0
	v_mov_b32_e32 v10, v0
	v_mov_b32_e32 v11, v0
	v_mov_b32_e32 v12, v0
	v_mov_b32_e32 v13, v0
	v_mov_b32_e32 v14, v0
	v_mov_b32_e32 v15, v0
	v_mov_b32_e32 v24, v0
	v_mov_b32_e32 v25, v0
	v_mov_b32_e32 v26, v0
	v_mov_b32_e32 v27, v0
	v_mov_b32_e32 v28, v0
	v_mov_b32_e32 v29, v0
	v_mov_b32_e32 v30, v0
	v_mov_b32_e32 v31, v0
	v_mov_b32_e32 v40, v0
	v_mov_b32_e32 v41, v0
	v_mov_b32_e32 v42, v0
	v_mov_b32_e32 v43, v0
	v_mov_b32_e32 v44, v0
	v_mov_b32_e32 v45, v0
	v_mov_b32_e32 v46, v0
	v_mov_b32_e32 v47, v0
	v_mov_b32_e32 v56, v0
	v_mov_b32_e32 v57, v0
	v_mov_b32_e32 v58, v0
	v_mov_b32_e32 v59, v0
	v_mov_b32_e32 v60, v0
	v_mov_b32_e32 v61, v0
	v_mov_b32_e32 v62, v0
	v_mov_b32_e32 v63, v0
	v_mov_b32_e32 v64, v0
	v_mov_b32_e32 v65, v0
	v_mov_b32_e32 v66, v0
	v_mov_b32_e32 v67, v0
	v_mov_b32_e32 v68, v0
	v_mov_b32_e32 v69, v0
	v_mov_b32_e32 v70, v0
	v_mov_b32_e32 v71, v0
	v_mov_b32_e32 v76, v0
	v_mov_b32_e32 v77, v0
	v_mov_b32_e32 v78, v0
	v_mov_b32_e32 v79, v0
	v_mov_b32_e32 v84, v0
	v_mov_b32_e32 v85, v0
	v_mov_b32_e32 v86, v0
	v_mov_b32_e32 v87, v0
	v_mov_b32_e32 v92, v0
	v_mov_b32_e32 v93, v0
	v_mov_b32_e32 v94, v0
	v_mov_b32_e32 v95, v0
	v_mov_b32_e32 v100, v0
	v_mov_b32_e32 v101, v0
	v_mov_b32_e32 v102, v0
	v_mov_b32_e32 v103, v0
	v_mov_b32_e32 v108, v0
	v_mov_b32_e32 v109, v0
	v_mov_b32_e32 v110, v0
	v_mov_b32_e32 v111, v0
	v_mov_b32_e32 v116, v0
	v_mov_b32_e32 v117, v0
	v_mov_b32_e32 v118, v0
	v_mov_b32_e32 v119, v0
	v_mov_b32_e32 v72, v0
	v_mov_b32_e32 v73, v0
	v_mov_b32_e32 v74, v0
	v_mov_b32_e32 v75, v0
	v_mov_b32_e32 v80, v0
	v_mov_b32_e32 v81, v0
	v_mov_b32_e32 v82, v0
	v_mov_b32_e32 v83, v0
	v_mov_b32_e32 v88, v0
	v_mov_b32_e32 v89, v0
	v_mov_b32_e32 v90, v0
	v_mov_b32_e32 v91, v0
	v_mov_b32_e32 v96, v0
	v_mov_b32_e32 v97, v0
	v_mov_b32_e32 v98, v0
	v_mov_b32_e32 v99, v0
	v_mov_b32_e32 v104, v0
	v_mov_b32_e32 v105, v0
	v_mov_b32_e32 v106, v0
	v_mov_b32_e32 v107, v0
	v_mov_b32_e32 v112, v0
	v_mov_b32_e32 v113, v0
	v_mov_b32_e32 v114, v0
	v_mov_b32_e32 v115, v0
	v_mov_b32_e32 v120, v0
	v_mov_b32_e32 v121, v0
	v_mov_b32_e32 v122, v0
	v_mov_b32_e32 v123, v0
	v_mov_b32_e32 v124, v0
	v_mov_b32_e32 v125, v0
	v_mov_b32_e32 v126, v0
	v_mov_b32_e32 v127, v0
	s_andn2_b64 vcc, exec, s[4:5]
	s_cbranch_vccnz .LBB0_1778

; template <class Epi, class Sched, bool ALIGN_EPI = false, bool SP2 = false>
; __device__ __forceinline__ void gemm_phase(PG8_LAS unsigned char* lds, const Gemm g, const Sched& S, const Epi& E, const int wid) {
;     ...
;         const bool has_next = S.next(ui + 1, nxt);
;         const char* nA = has_next ? (const char*)g.A + (size_t)nxt.pm * tstep : cA; const char* nB = has_next ? (const char*)g.Bt + (size_t)nxt.pn * tstep : cB;
;         for (int t = 0; t < nt; t += 2) {
;             const bool last = (t == nt - 2);
;             const char* a1 = cA + (size_t)(t + 1) * kstep;
;             const char* a2 = last ? nA : cA + (size_t)(t + 2) * kstep; const char* b2 = last ? nB : cB + (size_t)(t + 2) * kstep;
;             const char* a3 = a2 + kstep; const char* b3 = b2 + kstep;
.LBB0_1911:
	s_ashr_i32 s15, s14, 31
	s_lshl_b64 s[16:17], s[14:15], 19
	s_add_u32 s16, s80, s16
	s_addc_u32 s17, s81, s17
	s_and_b64 s[18:19], s[4:5], exec
	s_cselect_b32 s15, s17, s23
	s_cselect_b32 s42, s16, s22
	s_ashr_i32 s13, s12, 31
	s_lshl_b64 s[18:19], s[12:13], 19
	s_add_u32 s18, s10, s18
	s_addc_u32 s19, s11, s19
	s_and_b64 s[26:27], s[4:5], exec
	s_cselect_b32 s13, s19, s25
	s_cselect_b32 s43, s18, s24
	s_add_u32 s22, s22, 0x40080
	s_addc_u32 s23, s23, 0
	s_add_u32 s44, s24, 0x100

; template <class Epi, class Sched, bool ALIGN_EPI = false, bool SP2 = false>
; __device__ __forceinline__ void gemm_phase(PG8_LAS unsigned char* lds, const Gemm g, const Sched& S, const Epi& E, const int wid) {
;     ...
;         for (int t = 0; t < nt; t += 2) {
;             const bool last = (t == nt - 2);
;             const char* a1 = cA + (size_t)(t + 1) * kstep;
;             const char* a2 = last ? nA : cA + (size_t)(t + 2) * kstep; const char* b2 = last ? nB : cB + (size_t)(t + 2) * kstep;
;             const char* a3 = a2 + kstep; const char* b3 = b2 + kstep;
	s_addc_u32 s45, s25, 0
	s_mov_b32 s46, -2


; #define PG8_STAGE(bufoff, gbase, voff) do { _Pragma("unroll") for (int _i = 0; _i < 2; ++_i) \
;         __builtin_amdgcn_global_load_lds((const unsigned*)((const char*)(gbase) + (voff)[_i]), (PG8_LAS unsigned*)(lds + (bufoff) + ldsw + _i * 8192), 16, 0, 0); } while (0)
; #define PG8_LDA(dst, b, h) do { _Pragma("unroll") for (int m = 0; m < 4; ++m) _Pragma("unroll") for (int k = 0; k < 2; ++k) dst[m][k] = *(const PG8_LAS bf16x8*)(lds + PG8_SA(b, h) + aoff + m * 2048 + k * 1024); } while (0)
; #define PG8_LDB(dst, b, h) do { _Pragma("unroll") for (int n = 0; n < 2; ++n) _Pragma("unroll") for (int k = 0; k < 2; ++k) dst[n][k] = *(const PG8_LAS bf16x8*)(lds + PG8_SB(b, h) + boff + n * 2048 + k * 1024); } while (0)
; #define PG8_MMA(ai, bj, At, Bt) do { __builtin_amdgcn_s_setprio(1); _Pragma("unroll") for (int m = 0; m < 4; ++m) _Pragma("unroll") for (int n = 0; n < 2; ++n) _Pragma("unroll") for (int k = 0; k < 2; ++k) \
;         acc[ai][bj][m][n] = __builtin_amdgcn_mfma_f32_16x16x32_bf16(Bt[n][k], At[m][k], acc[ai][bj][m][n], 0, 0, 0); __builtin_amdgcn_s_setprio(0); } while (0)
; #define PG8_WAIT_V(n) asm volatile("s_waitcnt vmcnt(" #n ")" ::: "memory")
; #define PG8_WAIT_L(n) asm volatile("s_waitcnt lgkmcnt(" #n ")" ::: "memory")
; #define PG8_BAR __builtin_amdgcn_s_barrier()
; #define PG8_SCHED __builtin_amdgcn_sched_barrier(0)
; template <class Epi, class Sched, bool ALIGN_EPI = false, bool SP2 = false>
; __device__ __forceinline__ void gemm_phase(PG8_LAS unsigned char* lds, const Gemm g, const Sched& S, const Epi& E, const int wid) {
;     ...
;             PG8_LDB(B0, 0, 0); PG8_LDB(B1, 0, 1); PG8_SCHED; PG8_LDA(At, 0, 0); PG8_STAGE(PG8_SA(1, 1), a1 + hstep, voffA);
;             PG8_WAIT_V(8); PG8_WAIT_L(0); PG8_BAR; PG8_MMA(0, 0, At, B0); PG8_MMA(0, 1, At, B1); PG8_BAR; PG8_SCHED;
;             PG8_LDA(At, 0, 1); PG8_STAGE(PG8_SB(0, 0), b2, voffB); PG8_STAGE(PG8_SB(0, 1), b2 + hstep, voffB); PG8_STAGE(PG8_SA(0, 0), a2, voffA);
;             PG8_WAIT_V(8); PG8_WAIT_L(0); PG8_BAR; PG8_MMA(1, 0, At, B0); PG8_MMA(1, 1, At, B1); PG8_BAR; PG8_SCHED;
	ds_read_b128 v[144:147], v151
	ds_read_b128 v[154:157], v151 offset:1024
	ds_read_b128 v[158:161], v151 offset:2048
	ds_read_b128 v[162:165], v151 offset:3072
	ds_read_b128 v[166:169], v152
	ds_read_b128 v[170:173], v152 offset:1024
	ds_read_b128 v[174:177], v152 offset:2048
	ds_read_b128 v[178:181], v152 offset:3072
	s_add_u32 s24, s22, 0xfffc0080
	s_addc_u32 s25, s23, -1
	s_cmp_eq_u32 s46, 12
	s_cselect_b32 s27, s15, s25
	s_cselect_b32 s26, s42, s24
	s_cselect_b32 s25, s13, s45
	s_cselect_b32 s24, s43, s44
	v_lshl_add_u64 v[206:207], s[22:23], 0, v[136:137]
	s_add_i32 m0, s21, 0xc000
	ds_read_b128 v[182:185], v153
	ds_read_b128 v[186:189], v153 offset:1024
	ds_read_b128 v[190:193], v153 offset:2048
	ds_read_b128 v[194:197], v153 offset:3072
	ds_read_b128 v[198:201], v153 offset:4096
	ds_read_b128 v[202:205], v153 offset:5120
	ds_read_b128 v[210:213], v153 offset:6144
	ds_read_b128 v[214:217], v153 offset:7168
	global_load_lds_dwordx4 v[206:207], off
	v_lshl_add_u64 v[206:207], s[22:23], 0, v[138:139]
	s_add_i32 m0, s21, 0xe000
	s_nop 0
	global_load_lds_dwordx4 v[206:207], off
	s_waitcnt vmcnt(8)
	s_waitcnt lgkmcnt(0)
	s_barrier
	v_mfma_f32_16x16x32_bf16 v[124:127], v[144:147], v[182:185], 0
	v_mfma_f32_16x16x32_bf16 v[116:119], v[158:161], v[182:185], 0
	v_mfma_f32_16x16x32_bf16 v[108:111], v[144:147], v[190:193], 0
	v_mfma_f32_16x16x32_bf16 v[100:103], v[158:161], v[190:193], 0
	v_mfma_f32_16x16x32_bf16 v[92:95], v[144:147], v[198:201], 0
	v_mfma_f32_16x16x32_bf16 v[84:87], v[158:161], v[198:201], 0
	v_mfma_f32_16x16x32_bf16 v[76:79], v[144:147], v[210:213], 0
	v_mfma_f32_16x16x32_bf16 v[68:71], v[158:161], v[210:213], 0
	v_mfma_f32_16x16x32_bf16 v[124:127], v[154:157], v[186:189], v[124:127]
	v_mfma_f32_16x16x32_bf16 v[116:119], v[162:165], v[186:189], v[116:119]
	v_mfma_f32_16x16x32_bf16 v[108:111], v[154:157], v[194:197], v[108:111]
	v_mfma_f32_16x16x32_bf16 v[100:103], v[162:165], v[194:197], v[100:103]
	v_mfma_f32_16x16x32_bf16 v[92:95], v[154:157], v[202:205], v[92:95]
	v_mfma_f32_16x16x32_bf16 v[84:87], v[162:165], v[202:205], v[84:87]
	v_mfma_f32_16x16x32_bf16 v[76:79], v[154:157], v[214:217], v[76:79]
	v_mfma_f32_16x16x32_bf16 v[68:71], v[162:165], v[214:217], v[68:71]
	v_mfma_f32_16x16x32_bf16 v[120:123], v[166:169], v[182:185], 0
	v_mfma_f32_16x16x32_bf16 v[112:115], v[174:177], v[182:185], 0
	v_mfma_f32_16x16x32_bf16 v[104:107], v[166:169], v[190:193], 0
	v_mfma_f32_16x16x32_bf16 v[96:99], v[174:177], v[190:193], 0
	v_mfma_f32_16x16x32_bf16 v[88:91], v[166:169], v[198:201], 0
	v_mfma_f32_16x16x32_bf16 v[80:83], v[174:177], v[198:201], 0
	v_mfma_f32_16x16x32_bf16 v[72:75], v[166:169], v[210:213], 0
	v_mfma_f32_16x16x32_bf16 v[64:67], v[174:177], v[210:213], 0
	v_mfma_f32_16x16x32_bf16 v[120:123], v[170:173], v[186:189], v[120:123]
	v_mfma_f32_16x16x32_bf16 v[112:115], v[178:181], v[186:189], v[112:115]
	v_mfma_f32_16x16x32_bf16 v[104:107], v[170:173], v[194:197], v[104:107]
	v_mfma_f32_16x16x32_bf16 v[96:99], v[178:181], v[194:197], v[96:99]
	v_mfma_f32_16x16x32_bf16 v[88:91], v[170:173], v[202:205], v[88:91]
	v_mfma_f32_16x16x32_bf16 v[80:83], v[178:181], v[202:205], v[80:83]
	v_mfma_f32_16x16x32_bf16 v[72:75], v[170:173], v[214:217], v[72:75]
	v_mfma_f32_16x16x32_bf16 v[64:67], v[178:181], v[214:217], v[64:67]
	s_barrier
	s_add_i32 s47, s38, s9
	v_lshl_add_u64 v[206:207], s[24:25], 0, v[132:133]
	s_mov_b32 m0, s47
	ds_read_b128 v[182:185], v153 offset:16384
	ds_read_b128 v[186:189], v153 offset:17408
	ds_read_b128 v[190:193], v153 offset:18432
	ds_read_b128 v[194:197], v153 offset:19456
	ds_read_b128 v[198:201], v153 offset:20480
	ds_read_b128 v[202:205], v153 offset:21504
	ds_read_b128 v[210:213], v153 offset:22528
	ds_read_b128 v[214:217], v153 offset:23552
	global_load_lds_dwordx4 v[206:207], off
	s_add_i32 m0, s47, 0x2000
	s_add_u32 s48, s24, 0x40000
	v_lshl_add_u64 v[218:219], s[24:25], 0, v[128:129]
	s_addc_u32 s49, s25, 0
	s_add_i32 s47, s39, s9
	global_load_lds_dwordx4 v[218:219], off
	v_lshl_add_u64 v[220:221], s[48:49], 0, v[132:133]
	s_mov_b32 m0, s47
	v_lshl_add_u64 v[222:223], s[26:27], 0, v[130:131]
	global_load_lds_dwordx4 v[220:221], off
	v_lshl_add_u64 v[220:221], s[48:49], 0, v[128:129]
	s_add_i32 m0, s47, 0x2000
	s_nop 0
	global_load_lds_dwordx4 v[220:221], off
	v_lshl_add_u64 v[220:221], s[26:27], 0, v[134:135]
	s_mov_b32 m0, s21
	s_nop 0
	global_load_lds_dwordx4 v[220:221], off
	s_mov_b32 m0, s30
	s_nop 0
	global_load_lds_dwordx4 v[222:223], off
	s_waitcnt vmcnt(8)
	s_waitcnt lgkmcnt(0)
	s_barrier
	v_mfma_f32_16x16x32_bf16 v[60:63], v[144:147], v[182:185], 0
	v_mfma_f32_16x16x32_bf16 v[52:55], v[158:161], v[182:185], 0
	v_mfma_f32_16x16x32_bf16 v[44:47], v[144:147], v[190:193], 0
	v_mfma_f32_16x16x32_bf16 v[36:39], v[158:161], v[190:193], 0
	v_mfma_f32_16x16x32_bf16 v[28:31], v[144:147], v[198:201], 0
	v_mfma_f32_16x16x32_bf16 v[20:23], v[158:161], v[198:201], 0
	v_mfma_f32_16x16x32_bf16 v[12:15], v[144:147], v[210:213], 0
	v_mfma_f32_16x16x32_bf16 v[4:7], v[158:161], v[210:213], 0
	v_mfma_f32_16x16x32_bf16 v[60:63], v[154:157], v[186:189], v[60:63]
	v_mfma_f32_16x16x32_bf16 v[52:55], v[162:165], v[186:189], v[52:55]
	v_mfma_f32_16x16x32_bf16 v[44:47], v[154:157], v[194:197], v[44:47]
	v_mfma_f32_16x16x32_bf16 v[36:39], v[162:165], v[194:197], v[36:39]
	v_mfma_f32_16x16x32_bf16 v[28:31], v[154:157], v[202:205], v[28:31]
	v_mfma_f32_16x16x32_bf16 v[20:23], v[162:165], v[202:205], v[20:23]
	v_mfma_f32_16x16x32_bf16 v[12:15], v[154:157], v[214:217], v[12:15]
	v_mfma_f32_16x16x32_bf16 v[4:7], v[162:165], v[214:217], v[4:7]
	v_mfma_f32_16x16x32_bf16 v[56:59], v[166:169], v[182:185], 0
	v_mfma_f32_16x16x32_bf16 v[48:51], v[174:177], v[182:185], 0
	v_mfma_f32_16x16x32_bf16 v[40:43], v[166:169], v[190:193], 0
	v_mfma_f32_16x16x32_bf16 v[32:35], v[174:177], v[190:193], 0
	v_mfma_f32_16x16x32_bf16 v[24:27], v[166:169], v[198:201], 0
	v_mfma_f32_16x16x32_bf16 v[16:19], v[174:177], v[198:201], 0
	v_mfma_f32_16x16x32_bf16 v[8:11], v[166:169], v[210:213], 0
	v_mfma_f32_16x16x32_bf16 v[0:3], v[174:177], v[210:213], 0
	v_mfma_f32_16x16x32_bf16 v[56:59], v[170:173], v[186:189], v[56:59]
	v_mfma_f32_16x16x32_bf16 v[48:51], v[178:181], v[186:189], v[48:51]
	v_mfma_f32_16x16x32_bf16 v[40:43], v[170:173], v[194:197], v[40:43]
	v_mfma_f32_16x16x32_bf16 v[32:35], v[178:181], v[194:197], v[32:35]
	v_mfma_f32_16x16x32_bf16 v[24:27], v[170:173], v[202:205], v[24:27]
	v_mfma_f32_16x16x32_bf16 v[16:19], v[178:181], v[202:205], v[16:19]
	v_mfma_f32_16x16x32_bf16 v[8:11], v[170:173], v[214:217], v[8:11]
	v_mfma_f32_16x16x32_bf16 v[0:3], v[178:181], v[214:217], v[0:3]
	s_barrier
; #define PG8_STAGE(bufoff, gbase, voff) do { _Pragma("unroll") for (int _i = 0; _i < 2; ++_i) \
;         __builtin_amdgcn_global_load_lds((const unsigned*)((const char*)(gbase) + (voff)[_i]), (PG8_LAS unsigned*)(lds + (bufoff) + ldsw + _i * 8192), 16, 0, 0); } while (0)
; #define PG8_LDA(dst, b, h) do { _Pragma("unroll") for (int m = 0; m < 4; ++m) _Pragma("unroll") for (int k = 0; k < 2; ++k) dst[m][k] = *(const PG8_LAS bf16x8*)(lds + PG8_SA(b, h) + aoff + m * 2048 + k * 1024); } while (0)
; #define PG8_LDB(dst, b, h) do { _Pragma("unroll") for (int n = 0; n < 2; ++n) _Pragma("unroll") for (int k = 0; k < 2; ++k) dst[n][k] = *(const PG8_LAS bf16x8*)(lds + PG8_SB(b, h) + boff + n * 2048 + k * 1024); } while (0)
; #define PG8_MMA(ai, bj, At, Bt) do { __builtin_amdgcn_s_setprio(1); _Pragma("unroll") for (int m = 0; m < 4; ++m) _Pragma("unroll") for (int n = 0; n < 2; ++n) _Pragma("unroll") for (int k = 0; k < 2; ++k) \
;         acc[ai][bj][m][n] = __builtin_amdgcn_mfma_f32_16x16x32_bf16(Bt[n][k], At[m][k], acc[ai][bj][m][n], 0, 0, 0); __builtin_amdgcn_s_setprio(0); } while (0)
; #define PG8_WAIT_V(n) asm volatile("s_waitcnt vmcnt(" #n ")" ::: "memory")
; #define PG8_WAIT_L(n) asm volatile("s_waitcnt lgkmcnt(" #n ")" ::: "memory")
; #define PG8_BAR __builtin_amdgcn_s_barrier()
; #define PG8_SCHED __builtin_amdgcn_sched_barrier(0)
; template <class Epi, class Sched, bool ALIGN_EPI = false, bool SP2 = false>
; __device__ __forceinline__ void gemm_phase(PG8_LAS unsigned char* lds, const Gemm g, const Sched& S, const Epi& E, const int wid) {
;     ...
;             PG8_LDB(B0, 1, 0); PG8_LDB(B1, 1, 1); PG8_SCHED; PG8_LDA(At, 1, 0); PG8_STAGE(PG8_SA(0, 1), a2 + hstep, voffA);
;             PG8_WAIT_V(8); PG8_WAIT_L(0); PG8_BAR; PG8_MMA(0, 0, At, B0); PG8_MMA(0, 1, At, B1); PG8_BAR; PG8_SCHED;
;             PG8_LDA(At, 1, 1); PG8_STAGE(PG8_SB(1, 0), b3, voffB); PG8_STAGE(PG8_SB(1, 1), b3 + hstep, voffB); PG8_STAGE(PG8_SA(1, 0), a3, voffA);
;             PG8_WAIT_V(8); PG8_WAIT_L(0); PG8_BAR; PG8_MMA(1, 0, At, B0); PG8_MMA(1, 1, At, B1); PG8_BAR; PG8_SCHED;
	s_add_i32 s47, 0, 0x18000
	s_add_i32 s48, 0, 0x1c000
	v_add_u32_e32 v162, s47, v149
	v_add_u32_e32 v178, s48, v149
	ds_read_b128 v[144:147], v162
	ds_read_b128 v[154:157], v162 offset:1024
	ds_read_b128 v[158:161], v162 offset:2048
	ds_read_b128 v[162:165], v162 offset:3072
	ds_read_b128 v[166:169], v178
	ds_read_b128 v[170:173], v178 offset:1024
	ds_read_b128 v[174:177], v178 offset:2048
	ds_read_b128 v[178:181], v178 offset:3072
	s_add_u32 s26, s26, 0x40000
	s_addc_u32 s27, s27, 0
	s_mov_b32 m0, s31
	v_lshl_add_u64 v[224:225], s[26:27], 0, v[134:135]
	ds_read_b128 v[182:185], v153 offset:32768
	ds_read_b128 v[186:189], v153 offset:33792
	ds_read_b128 v[190:193], v153 offset:34816
	ds_read_b128 v[194:197], v153 offset:35840
	ds_read_b128 v[198:201], v153 offset:36864
	ds_read_b128 v[202:205], v153 offset:37888
	ds_read_b128 v[210:213], v153 offset:38912
	ds_read_b128 v[214:217], v153 offset:39936
	global_load_lds_dwordx4 v[224:225], off
	v_lshl_add_u64 v[224:225], s[26:27], 0, v[130:131]
	s_mov_b32 m0, s33
	s_nop 0
	global_load_lds_dwordx4 v[224:225], off
	s_waitcnt vmcnt(8)
	s_waitcnt lgkmcnt(0)
	s_barrier
	v_mfma_f32_16x16x32_bf16 v[124:127], v[144:147], v[182:185], v[124:127]
	v_mfma_f32_16x16x32_bf16 v[116:119], v[158:161], v[182:185], v[116:119]
	v_mfma_f32_16x16x32_bf16 v[108:111], v[144:147], v[190:193], v[108:111]
	v_mfma_f32_16x16x32_bf16 v[100:103], v[158:161], v[190:193], v[100:103]
	v_mfma_f32_16x16x32_bf16 v[92:95], v[144:147], v[198:201], v[92:95]
	v_mfma_f32_16x16x32_bf16 v[84:87], v[158:161], v[198:201], v[84:87]
	v_mfma_f32_16x16x32_bf16 v[76:79], v[144:147], v[210:213], v[76:79]
	v_mfma_f32_16x16x32_bf16 v[68:71], v[158:161], v[210:213], v[68:71]
	v_mfma_f32_16x16x32_bf16 v[124:127], v[154:157], v[186:189], v[124:127]
	v_mfma_f32_16x16x32_bf16 v[116:119], v[162:165], v[186:189], v[116:119]
	v_mfma_f32_16x16x32_bf16 v[108:111], v[154:157], v[194:197], v[108:111]
	v_mfma_f32_16x16x32_bf16 v[100:103], v[162:165], v[194:197], v[100:103]
	v_mfma_f32_16x16x32_bf16 v[92:95], v[154:157], v[202:205], v[92:95]
	v_mfma_f32_16x16x32_bf16 v[84:87], v[162:165], v[202:205], v[84:87]
	v_mfma_f32_16x16x32_bf16 v[76:79], v[154:157], v[214:217], v[76:79]
	v_mfma_f32_16x16x32_bf16 v[68:71], v[162:165], v[214:217], v[68:71]
	v_mfma_f32_16x16x32_bf16 v[120:123], v[166:169], v[182:185], v[120:123]
	v_mfma_f32_16x16x32_bf16 v[112:115], v[174:177], v[182:185], v[112:115]
	v_mfma_f32_16x16x32_bf16 v[104:107], v[166:169], v[190:193], v[104:107]
	v_mfma_f32_16x16x32_bf16 v[96:99], v[174:177], v[190:193], v[96:99]
	v_mfma_f32_16x16x32_bf16 v[88:91], v[166:169], v[198:201], v[88:91]
	v_mfma_f32_16x16x32_bf16 v[80:83], v[174:177], v[198:201], v[80:83]
	v_mfma_f32_16x16x32_bf16 v[72:75], v[166:169], v[210:213], v[72:75]
	v_mfma_f32_16x16x32_bf16 v[64:67], v[174:177], v[210:213], v[64:67]
	v_mfma_f32_16x16x32_bf16 v[120:123], v[170:173], v[186:189], v[120:123]
	v_mfma_f32_16x16x32_bf16 v[112:115], v[178:181], v[186:189], v[112:115]
	v_mfma_f32_16x16x32_bf16 v[104:107], v[170:173], v[194:197], v[104:107]
	v_mfma_f32_16x16x32_bf16 v[96:99], v[178:181], v[194:197], v[96:99]
	v_mfma_f32_16x16x32_bf16 v[88:91], v[170:173], v[202:205], v[88:91]
	v_mfma_f32_16x16x32_bf16 v[80:83], v[178:181], v[202:205], v[80:83]
	v_mfma_f32_16x16x32_bf16 v[72:75], v[170:173], v[214:217], v[72:75]
	v_mfma_f32_16x16x32_bf16 v[64:67], v[178:181], v[214:217], v[64:67]
	s_barrier
	s_add_i32 s26, s47, s9
	v_lshl_add_u64 v[206:207], v[206:207], 0, s[2:3]
	s_mov_b32 m0, s26
	ds_read_b128 v[182:185], v153 offset:49152
	ds_read_b128 v[186:189], v153 offset:50176
	ds_read_b128 v[190:193], v153 offset:51200
	ds_read_b128 v[194:197], v153 offset:52224
	ds_read_b128 v[198:201], v153 offset:53248
	ds_read_b128 v[202:205], v153 offset:54272
	ds_read_b128 v[210:213], v153 offset:55296
	ds_read_b128 v[214:217], v153 offset:56320
	global_load_lds_dwordx4 v[206:207], off
	s_add_i32 m0, s26, 0x2000
	s_add_u32 s24, s24, 0x40080
	v_lshl_add_u64 v[206:207], v[218:219], 0, s[2:3]
	s_addc_u32 s25, s25, 0
	s_add_i32 s26, s48, s9
	global_load_lds_dwordx4 v[206:207], off
	v_lshl_add_u64 v[206:207], s[24:25], 0, v[132:133]
	s_mov_b32 m0, s26
	s_nop 0
	global_load_lds_dwordx4 v[206:207], off
	v_lshl_add_u64 v[206:207], s[24:25], 0, v[128:129]
	s_add_i32 m0, s26, 0x2000
	s_nop 0
	global_load_lds_dwordx4 v[206:207], off
	v_lshl_add_u64 v[206:207], v[220:221], 0, s[2:3]
	s_mov_b32 m0, s35
	s_nop 0
	global_load_lds_dwordx4 v[206:207], off
	v_lshl_add_u64 v[206:207], v[222:223], 0, s[2:3]
	s_mov_b32 m0, s36
	s_nop 0
	global_load_lds_dwordx4 v[206:207], off
	s_waitcnt vmcnt(8)
	s_waitcnt lgkmcnt(0)
	s_barrier
	v_mfma_f32_16x16x32_bf16 v[60:63], v[144:147], v[182:185], v[60:63]
	v_mfma_f32_16x16x32_bf16 v[52:55], v[158:161], v[182:185], v[52:55]
	v_mfma_f32_16x16x32_bf16 v[44:47], v[144:147], v[190:193], v[44:47]
	v_mfma_f32_16x16x32_bf16 v[36:39], v[158:161], v[190:193], v[36:39]
	v_mfma_f32_16x16x32_bf16 v[28:31], v[144:147], v[198:201], v[28:31]
	v_mfma_f32_16x16x32_bf16 v[20:23], v[158:161], v[198:201], v[20:23]
	v_mfma_f32_16x16x32_bf16 v[12:15], v[144:147], v[210:213], v[12:15]
	v_mfma_f32_16x16x32_bf16 v[4:7], v[158:161], v[210:213], v[4:7]
	v_mfma_f32_16x16x32_bf16 v[60:63], v[154:157], v[186:189], v[60:63]
	v_mfma_f32_16x16x32_bf16 v[52:55], v[162:165], v[186:189], v[52:55]
	v_mfma_f32_16x16x32_bf16 v[44:47], v[154:157], v[194:197], v[44:47]
	v_mfma_f32_16x16x32_bf16 v[36:39], v[162:165], v[194:197], v[36:39]
	v_mfma_f32_16x16x32_bf16 v[28:31], v[154:157], v[202:205], v[28:31]
	v_mfma_f32_16x16x32_bf16 v[20:23], v[162:165], v[202:205], v[20:23]
	v_mfma_f32_16x16x32_bf16 v[12:15], v[154:157], v[214:217], v[12:15]
	v_mfma_f32_16x16x32_bf16 v[4:7], v[162:165], v[214:217], v[4:7]
	v_mfma_f32_16x16x32_bf16 v[56:59], v[166:169], v[182:185], v[56:59]
	v_mfma_f32_16x16x32_bf16 v[48:51], v[174:177], v[182:185], v[48:51]
	v_mfma_f32_16x16x32_bf16 v[40:43], v[166:169], v[190:193], v[40:43]
	v_mfma_f32_16x16x32_bf16 v[32:35], v[174:177], v[190:193], v[32:35]
	v_mfma_f32_16x16x32_bf16 v[24:27], v[166:169], v[198:201], v[24:27]
	v_mfma_f32_16x16x32_bf16 v[16:19], v[174:177], v[198:201], v[16:19]
	v_mfma_f32_16x16x32_bf16 v[8:11], v[166:169], v[210:213], v[8:11]
	v_mfma_f32_16x16x32_bf16 v[0:3], v[174:177], v[210:213], v[0:3]
	v_mfma_f32_16x16x32_bf16 v[56:59], v[170:173], v[186:189], v[56:59]
	v_mfma_f32_16x16x32_bf16 v[48:51], v[178:181], v[186:189], v[48:51]
	v_mfma_f32_16x16x32_bf16 v[40:43], v[170:173], v[194:197], v[40:43]
	v_mfma_f32_16x16x32_bf16 v[32:35], v[178:181], v[194:197], v[32:35]
	v_mfma_f32_16x16x32_bf16 v[24:27], v[170:173], v[202:205], v[24:27]
	v_mfma_f32_16x16x32_bf16 v[16:19], v[178:181], v[202:205], v[16:19]
	v_mfma_f32_16x16x32_bf16 v[8:11], v[170:173], v[214:217], v[8:11]
	v_mfma_f32_16x16x32_bf16 v[0:3], v[178:181], v[214:217], v[0:3]
	s_barrier
	s_add_i32 s46, s46, 2
	s_add_u32 s22, s22, 0x100
	s_addc_u32 s23, s23, 0
	s_add_u32 s44, s44, 0x100
	s_addc_u32 s45, s45, 0
	s_cmp_gt_u32 s46, 13
	s_cbranch_scc0 .LBB0_1912
	s_branch .Lkp_exit_4
; #define PG8_STAGE(bufoff, gbase, voff) do { _Pragma("unroll") for (int _i = 0; _i < 2; ++_i) \
;         __builtin_amdgcn_global_load_lds((const unsigned*)((const char*)(gbase) + (voff)[_i]), (PG8_LAS unsigned*)(lds + (bufoff) + ldsw + _i * 8192), 16, 0, 0); } while (0)
; #define PG8_LDA(dst, b, h) do { _Pragma("unroll") for (int m = 0; m < 4; ++m) _Pragma("unroll") for (int k = 0; k < 2; ++k) dst[m][k] = *(const PG8_LAS bf16x8*)(lds + PG8_SA(b, h) + aoff + m * 2048 + k * 1024); } while (0)
; #define PG8_LDB(dst, b, h) do { _Pragma("unroll") for (int n = 0; n < 2; ++n) _Pragma("unroll") for (int k = 0; k < 2; ++k) dst[n][k] = *(const PG8_LAS bf16x8*)(lds + PG8_SB(b, h) + boff + n * 2048 + k * 1024); } while (0)
; #define PG8_MMA(ai, bj, At, Bt) do { __builtin_amdgcn_s_setprio(1); _Pragma("unroll") for (int m = 0; m < 4; ++m) _Pragma("unroll") for (int n = 0; n < 2; ++n) _Pragma("unroll") for (int k = 0; k < 2; ++k) \
;         acc[ai][bj][m][n] = __builtin_amdgcn_mfma_f32_16x16x32_bf16(Bt[n][k], At[m][k], acc[ai][bj][m][n], 0, 0, 0); __builtin_amdgcn_s_setprio(0); } while (0)
; #define PG8_WAIT_V(n) asm volatile("s_waitcnt vmcnt(" #n ")" ::: "memory")
; #define PG8_WAIT_L(n) asm volatile("s_waitcnt lgkmcnt(" #n ")" ::: "memory")
; #define PG8_BAR __builtin_amdgcn_s_barrier()
; #define PG8_SCHED __builtin_amdgcn_sched_barrier(0)
; template <class Epi, class Sched, bool ALIGN_EPI = false, bool SP2 = false>
; __device__ __forceinline__ void gemm_phase(PG8_LAS unsigned char* lds, const Gemm g, const Sched& S, const Epi& E, const int wid) {
;     ...
;             PG8_LDB(B0, 0, 0); PG8_LDB(B1, 0, 1); PG8_SCHED; PG8_LDA(At, 0, 0); PG8_STAGE(PG8_SA(1, 1), a1 + hstep, voffA);
;             PG8_WAIT_V(8); PG8_WAIT_L(0); PG8_BAR; PG8_MMA(0, 0, At, B0); PG8_MMA(0, 1, At, B1); PG8_BAR; PG8_SCHED;
;             PG8_LDA(At, 0, 1); PG8_STAGE(PG8_SB(0, 0), b2, voffB); PG8_STAGE(PG8_SB(0, 1), b2 + hstep, voffB); PG8_STAGE(PG8_SA(0, 0), a2, voffA);
;             PG8_WAIT_V(8); PG8_WAIT_L(0); PG8_BAR; PG8_MMA(1, 0, At, B0); PG8_MMA(1, 1, At, B1); PG8_BAR; PG8_SCHED;
.LBB0_1912:
	ds_read_b128 v[144:147], v151
	ds_read_b128 v[154:157], v151 offset:1024
	ds_read_b128 v[158:161], v151 offset:2048
	ds_read_b128 v[162:165], v151 offset:3072
	ds_read_b128 v[166:169], v152
	ds_read_b128 v[170:173], v152 offset:1024
	ds_read_b128 v[174:177], v152 offset:2048
	ds_read_b128 v[178:181], v152 offset:3072
	s_add_u32 s24, s22, 0xfffc0080
	s_addc_u32 s25, s23, -1
	s_cmp_eq_u32 s46, 12
	s_cselect_b32 s27, s15, s25
	s_cselect_b32 s26, s42, s24
	s_cselect_b32 s25, s13, s45
	s_cselect_b32 s24, s43, s44
	v_lshl_add_u64 v[206:207], s[22:23], 0, v[136:137]
	s_add_i32 m0, s21, 0xc000
	ds_read_b128 v[182:185], v153
	ds_read_b128 v[186:189], v153 offset:1024
	ds_read_b128 v[190:193], v153 offset:2048
	ds_read_b128 v[194:197], v153 offset:3072
	ds_read_b128 v[198:201], v153 offset:4096
	ds_read_b128 v[202:205], v153 offset:5120
	ds_read_b128 v[210:213], v153 offset:6144
	ds_read_b128 v[214:217], v153 offset:7168
	global_load_lds_dwordx4 v[206:207], off
	v_lshl_add_u64 v[206:207], s[22:23], 0, v[138:139]
	s_add_i32 m0, s21, 0xe000
	s_nop 0
	global_load_lds_dwordx4 v[206:207], off
	s_waitcnt vmcnt(8)
	s_waitcnt lgkmcnt(0)
	s_barrier
	v_mfma_f32_16x16x32_bf16 v[124:127], v[144:147], v[182:185], v[124:127]
	v_mfma_f32_16x16x32_bf16 v[116:119], v[158:161], v[182:185], v[116:119]
	v_mfma_f32_16x16x32_bf16 v[108:111], v[144:147], v[190:193], v[108:111]
	v_mfma_f32_16x16x32_bf16 v[100:103], v[158:161], v[190:193], v[100:103]
	v_mfma_f32_16x16x32_bf16 v[92:95], v[144:147], v[198:201], v[92:95]
	v_mfma_f32_16x16x32_bf16 v[84:87], v[158:161], v[198:201], v[84:87]
	v_mfma_f32_16x16x32_bf16 v[76:79], v[144:147], v[210:213], v[76:79]
	v_mfma_f32_16x16x32_bf16 v[68:71], v[158:161], v[210:213], v[68:71]
	v_mfma_f32_16x16x32_bf16 v[124:127], v[154:157], v[186:189], v[124:127]
	v_mfma_f32_16x16x32_bf16 v[116:119], v[162:165], v[186:189], v[116:119]
	v_mfma_f32_16x16x32_bf16 v[108:111], v[154:157], v[194:197], v[108:111]
	v_mfma_f32_16x16x32_bf16 v[100:103], v[162:165], v[194:197], v[100:103]
	v_mfma_f32_16x16x32_bf16 v[92:95], v[154:157], v[202:205], v[92:95]
	v_mfma_f32_16x16x32_bf16 v[84:87], v[162:165], v[202:205], v[84:87]
	v_mfma_f32_16x16x32_bf16 v[76:79], v[154:157], v[214:217], v[76:79]
	v_mfma_f32_16x16x32_bf16 v[68:71], v[162:165], v[214:217], v[68:71]
	v_mfma_f32_16x16x32_bf16 v[120:123], v[166:169], v[182:185], v[120:123]
	v_mfma_f32_16x16x32_bf16 v[112:115], v[174:177], v[182:185], v[112:115]
	v_mfma_f32_16x16x32_bf16 v[104:107], v[166:169], v[190:193], v[104:107]
	v_mfma_f32_16x16x32_bf16 v[96:99], v[174:177], v[190:193], v[96:99]
	v_mfma_f32_16x16x32_bf16 v[88:91], v[166:169], v[198:201], v[88:91]
	v_mfma_f32_16x16x32_bf16 v[80:83], v[174:177], v[198:201], v[80:83]
	v_mfma_f32_16x16x32_bf16 v[72:75], v[166:169], v[210:213], v[72:75]
	v_mfma_f32_16x16x32_bf16 v[64:67], v[174:177], v[210:213], v[64:67]
	v_mfma_f32_16x16x32_bf16 v[120:123], v[170:173], v[186:189], v[120:123]
	v_mfma_f32_16x16x32_bf16 v[112:115], v[178:181], v[186:189], v[112:115]
	v_mfma_f32_16x16x32_bf16 v[104:107], v[170:173], v[194:197], v[104:107]
	v_mfma_f32_16x16x32_bf16 v[96:99], v[178:181], v[194:197], v[96:99]
	v_mfma_f32_16x16x32_bf16 v[88:91], v[170:173], v[202:205], v[88:91]
	v_mfma_f32_16x16x32_bf16 v[80:83], v[178:181], v[202:205], v[80:83]
	v_mfma_f32_16x16x32_bf16 v[72:75], v[170:173], v[214:217], v[72:75]
	v_mfma_f32_16x16x32_bf16 v[64:67], v[178:181], v[214:217], v[64:67]
	s_barrier
	s_add_i32 s47, s38, s9
	v_lshl_add_u64 v[206:207], s[24:25], 0, v[132:133]
	s_mov_b32 m0, s47
	ds_read_b128 v[182:185], v153 offset:16384
	ds_read_b128 v[186:189], v153 offset:17408
	ds_read_b128 v[190:193], v153 offset:18432
	ds_read_b128 v[194:197], v153 offset:19456
	ds_read_b128 v[198:201], v153 offset:20480
	ds_read_b128 v[202:205], v153 offset:21504
	ds_read_b128 v[210:213], v153 offset:22528
	ds_read_b128 v[214:217], v153 offset:23552
	global_load_lds_dwordx4 v[206:207], off
	s_add_i32 m0, s47, 0x2000
	s_add_u32 s48, s24, 0x40000
	v_lshl_add_u64 v[218:219], s[24:25], 0, v[128:129]
	s_addc_u32 s49, s25, 0
	s_add_i32 s47, s39, s9
	global_load_lds_dwordx4 v[218:219], off
	v_lshl_add_u64 v[220:221], s[48:49], 0, v[132:133]
	s_mov_b32 m0, s47
	v_lshl_add_u64 v[222:223], s[26:27], 0, v[130:131]
	global_load_lds_dwordx4 v[220:221], off
	v_lshl_add_u64 v[220:221], s[48:49], 0, v[128:129]
	s_add_i32 m0, s47, 0x2000
	s_nop 0
	global_load_lds_dwordx4 v[220:221], off
	v_lshl_add_u64 v[220:221], s[26:27], 0, v[134:135]
	s_mov_b32 m0, s21
	s_nop 0
	global_load_lds_dwordx4 v[220:221], off
	s_mov_b32 m0, s30
	s_nop 0
	global_load_lds_dwordx4 v[222:223], off
	s_waitcnt vmcnt(8)
	s_waitcnt lgkmcnt(0)
	s_barrier
; #define PG8_STAGE(bufoff, gbase, voff) do { _Pragma("unroll") for (int _i = 0; _i < 2; ++_i) \
;         __builtin_amdgcn_global_load_lds((const unsigned*)((const char*)(gbase) + (voff)[_i]), (PG8_LAS unsigned*)(lds + (bufoff) + ldsw + _i * 8192), 16, 0, 0); } while (0)
; #define PG8_LDA(dst, b, h) do { _Pragma("unroll") for (int m = 0; m < 4; ++m) _Pragma("unroll") for (int k = 0; k < 2; ++k) dst[m][k] = *(const PG8_LAS bf16x8*)(lds + PG8_SA(b, h) + aoff + m * 2048 + k * 1024); } while (0)
; #define PG8_LDB(dst, b, h) do { _Pragma("unroll") for (int n = 0; n < 2; ++n) _Pragma("unroll") for (int k = 0; k < 2; ++k) dst[n][k] = *(const PG8_LAS bf16x8*)(lds + PG8_SB(b, h) + boff + n * 2048 + k * 1024); } while (0)
; #define PG8_MMA(ai, bj, At, Bt) do { __builtin_amdgcn_s_setprio(1); _Pragma("unroll") for (int m = 0; m < 4; ++m) _Pragma("unroll") for (int n = 0; n < 2; ++n) _Pragma("unroll") for (int k = 0; k < 2; ++k) \
;         acc[ai][bj][m][n] = __builtin_amdgcn_mfma_f32_16x16x32_bf16(Bt[n][k], At[m][k], acc[ai][bj][m][n], 0, 0, 0); __builtin_amdgcn_s_setprio(0); } while (0)
; #define PG8_WAIT_V(n) asm volatile("s_waitcnt vmcnt(" #n ")" ::: "memory")
; #define PG8_WAIT_L(n) asm volatile("s_waitcnt lgkmcnt(" #n ")" ::: "memory")
; #define PG8_BAR __builtin_amdgcn_s_barrier()
; #define PG8_SCHED __builtin_amdgcn_sched_barrier(0)
; template <class Epi, class Sched, bool ALIGN_EPI = false, bool SP2 = false>
; __device__ __forceinline__ void gemm_phase(PG8_LAS unsigned char* lds, const Gemm g, const Sched& S, const Epi& E, const int wid) {
;     ...
;             PG8_WAIT_V(8); PG8_WAIT_L(0); PG8_BAR; PG8_MMA(1, 0, At, B0); PG8_MMA(1, 1, At, B1); PG8_BAR; PG8_SCHED;
;             PG8_LDB(B0, 1, 0); PG8_LDB(B1, 1, 1); PG8_SCHED; PG8_LDA(At, 1, 0); PG8_STAGE(PG8_SA(0, 1), a2 + hstep, voffA);
;             PG8_WAIT_V(8); PG8_WAIT_L(0); PG8_BAR; PG8_MMA(0, 0, At, B0); PG8_MMA(0, 1, At, B1); PG8_BAR; PG8_SCHED;
	v_mfma_f32_16x16x32_bf16 v[60:63], v[144:147], v[182:185], v[60:63]
	v_mfma_f32_16x16x32_bf16 v[52:55], v[158:161], v[182:185], v[52:55]
	v_mfma_f32_16x16x32_bf16 v[44:47], v[144:147], v[190:193], v[44:47]
	v_mfma_f32_16x16x32_bf16 v[36:39], v[158:161], v[190:193], v[36:39]
	v_mfma_f32_16x16x32_bf16 v[28:31], v[144:147], v[198:201], v[28:31]
	v_mfma_f32_16x16x32_bf16 v[20:23], v[158:161], v[198:201], v[20:23]
	v_mfma_f32_16x16x32_bf16 v[12:15], v[144:147], v[210:213], v[12:15]
	v_mfma_f32_16x16x32_bf16 v[4:7], v[158:161], v[210:213], v[4:7]
	v_mfma_f32_16x16x32_bf16 v[60:63], v[154:157], v[186:189], v[60:63]
	v_mfma_f32_16x16x32_bf16 v[52:55], v[162:165], v[186:189], v[52:55]
	v_mfma_f32_16x16x32_bf16 v[44:47], v[154:157], v[194:197], v[44:47]
	v_mfma_f32_16x16x32_bf16 v[36:39], v[162:165], v[194:197], v[36:39]
	v_mfma_f32_16x16x32_bf16 v[28:31], v[154:157], v[202:205], v[28:31]
	v_mfma_f32_16x16x32_bf16 v[20:23], v[162:165], v[202:205], v[20:23]
	v_mfma_f32_16x16x32_bf16 v[12:15], v[154:157], v[214:217], v[12:15]
	v_mfma_f32_16x16x32_bf16 v[4:7], v[162:165], v[214:217], v[4:7]
	v_mfma_f32_16x16x32_bf16 v[56:59], v[166:169], v[182:185], v[56:59]
	v_mfma_f32_16x16x32_bf16 v[48:51], v[174:177], v[182:185], v[48:51]
	v_mfma_f32_16x16x32_bf16 v[40:43], v[166:169], v[190:193], v[40:43]
	v_mfma_f32_16x16x32_bf16 v[32:35], v[174:177], v[190:193], v[32:35]
	v_mfma_f32_16x16x32_bf16 v[24:27], v[166:169], v[198:201], v[24:27]
	v_mfma_f32_16x16x32_bf16 v[16:19], v[174:177], v[198:201], v[16:19]
	v_mfma_f32_16x16x32_bf16 v[8:11], v[166:169], v[210:213], v[8:11]
	v_mfma_f32_16x16x32_bf16 v[0:3], v[174:177], v[210:213], v[0:3]
	v_mfma_f32_16x16x32_bf16 v[56:59], v[170:173], v[186:189], v[56:59]
	v_mfma_f32_16x16x32_bf16 v[48:51], v[178:181], v[186:189], v[48:51]
	v_mfma_f32_16x16x32_bf16 v[40:43], v[170:173], v[194:197], v[40:43]
	v_mfma_f32_16x16x32_bf16 v[32:35], v[178:181], v[194:197], v[32:35]
	v_mfma_f32_16x16x32_bf16 v[24:27], v[170:173], v[202:205], v[24:27]
	v_mfma_f32_16x16x32_bf16 v[16:19], v[178:181], v[202:205], v[16:19]
	v_mfma_f32_16x16x32_bf16 v[8:11], v[170:173], v[214:217], v[8:11]
	v_mfma_f32_16x16x32_bf16 v[0:3], v[178:181], v[214:217], v[0:3]
	s_barrier
	s_add_i32 s47, 0, 0x18000
	s_add_i32 s48, 0, 0x1c000
	v_add_u32_e32 v162, s47, v149
	v_add_u32_e32 v178, s48, v149
	ds_read_b128 v[144:147], v162
	ds_read_b128 v[154:157], v162 offset:1024
	ds_read_b128 v[158:161], v162 offset:2048
	ds_read_b128 v[162:165], v162 offset:3072
	ds_read_b128 v[166:169], v178
	ds_read_b128 v[170:173], v178 offset:1024
	ds_read_b128 v[174:177], v178 offset:2048
	ds_read_b128 v[178:181], v178 offset:3072
	s_add_u32 s26, s26, 0x40000
	s_addc_u32 s27, s27, 0
	s_mov_b32 m0, s31
	v_lshl_add_u64 v[224:225], s[26:27], 0, v[134:135]
	ds_read_b128 v[182:185], v153 offset:32768
	ds_read_b128 v[186:189], v153 offset:33792
	ds_read_b128 v[190:193], v153 offset:34816
	ds_read_b128 v[194:197], v153 offset:35840
	ds_read_b128 v[198:201], v153 offset:36864
	ds_read_b128 v[202:205], v153 offset:37888
	ds_read_b128 v[210:213], v153 offset:38912
	ds_read_b128 v[214:217], v153 offset:39936
	global_load_lds_dwordx4 v[224:225], off
	v_lshl_add_u64 v[224:225], s[26:27], 0, v[130:131]
	s_mov_b32 m0, s33
	s_nop 0
	global_load_lds_dwordx4 v[224:225], off
	s_waitcnt vmcnt(8)
	s_waitcnt lgkmcnt(0)
	s_barrier
	v_mfma_f32_16x16x32_bf16 v[124:127], v[144:147], v[182:185], v[124:127]
	v_mfma_f32_16x16x32_bf16 v[116:119], v[158:161], v[182:185], v[116:119]
	v_mfma_f32_16x16x32_bf16 v[108:111], v[144:147], v[190:193], v[108:111]
	v_mfma_f32_16x16x32_bf16 v[100:103], v[158:161], v[190:193], v[100:103]
	v_mfma_f32_16x16x32_bf16 v[92:95], v[144:147], v[198:201], v[92:95]
	v_mfma_f32_16x16x32_bf16 v[84:87], v[158:161], v[198:201], v[84:87]
	v_mfma_f32_16x16x32_bf16 v[76:79], v[144:147], v[210:213], v[76:79]
	v_mfma_f32_16x16x32_bf16 v[68:71], v[158:161], v[210:213], v[68:71]
	v_mfma_f32_16x16x32_bf16 v[124:127], v[154:157], v[186:189], v[124:127]
	v_mfma_f32_16x16x32_bf16 v[116:119], v[162:165], v[186:189], v[116:119]
	v_mfma_f32_16x16x32_bf16 v[108:111], v[154:157], v[194:197], v[108:111]
	v_mfma_f32_16x16x32_bf16 v[100:103], v[162:165], v[194:197], v[100:103]
	v_mfma_f32_16x16x32_bf16 v[92:95], v[154:157], v[202:205], v[92:95]
	v_mfma_f32_16x16x32_bf16 v[84:87], v[162:165], v[202:205], v[84:87]
	v_mfma_f32_16x16x32_bf16 v[76:79], v[154:157], v[214:217], v[76:79]
	v_mfma_f32_16x16x32_bf16 v[68:71], v[162:165], v[214:217], v[68:71]
	v_mfma_f32_16x16x32_bf16 v[120:123], v[166:169], v[182:185], v[120:123]
	v_mfma_f32_16x16x32_bf16 v[112:115], v[174:177], v[182:185], v[112:115]
	v_mfma_f32_16x16x32_bf16 v[104:107], v[166:169], v[190:193], v[104:107]
	v_mfma_f32_16x16x32_bf16 v[96:99], v[174:177], v[190:193], v[96:99]
	v_mfma_f32_16x16x32_bf16 v[88:91], v[166:169], v[198:201], v[88:91]
	v_mfma_f32_16x16x32_bf16 v[80:83], v[174:177], v[198:201], v[80:83]
	v_mfma_f32_16x16x32_bf16 v[72:75], v[166:169], v[210:213], v[72:75]
	v_mfma_f32_16x16x32_bf16 v[64:67], v[174:177], v[210:213], v[64:67]
	v_mfma_f32_16x16x32_bf16 v[120:123], v[170:173], v[186:189], v[120:123]
	v_mfma_f32_16x16x32_bf16 v[112:115], v[178:181], v[186:189], v[112:115]
	v_mfma_f32_16x16x32_bf16 v[104:107], v[170:173], v[194:197], v[104:107]
	v_mfma_f32_16x16x32_bf16 v[96:99], v[178:181], v[194:197], v[96:99]
	v_mfma_f32_16x16x32_bf16 v[88:91], v[170:173], v[202:205], v[88:91]
	v_mfma_f32_16x16x32_bf16 v[80:83], v[178:181], v[202:205], v[80:83]
	v_mfma_f32_16x16x32_bf16 v[72:75], v[170:173], v[214:217], v[72:75]
	v_mfma_f32_16x16x32_bf16 v[64:67], v[178:181], v[214:217], v[64:67]
	s_barrier
; #define PG8_STAGE(bufoff, gbase, voff) do { _Pragma("unroll") for (int _i = 0; _i < 2; ++_i) \
;         __builtin_amdgcn_global_load_lds((const unsigned*)((const char*)(gbase) + (voff)[_i]), (PG8_LAS unsigned*)(lds + (bufoff) + ldsw + _i * 8192), 16, 0, 0); } while (0)
; #define PG8_LDA(dst, b, h) do { _Pragma("unroll") for (int m = 0; m < 4; ++m) _Pragma("unroll") for (int k = 0; k < 2; ++k) dst[m][k] = *(const PG8_LAS bf16x8*)(lds + PG8_SA(b, h) + aoff + m * 2048 + k * 1024); } while (0)
; #define PG8_MMA(ai, bj, At, Bt) do { __builtin_amdgcn_s_setprio(1); _Pragma("unroll") for (int m = 0; m < 4; ++m) _Pragma("unroll") for (int n = 0; n < 2; ++n) _Pragma("unroll") for (int k = 0; k < 2; ++k) \
;         acc[ai][bj][m][n] = __builtin_amdgcn_mfma_f32_16x16x32_bf16(Bt[n][k], At[m][k], acc[ai][bj][m][n], 0, 0, 0); __builtin_amdgcn_s_setprio(0); } while (0)
; #define PG8_WAIT_V(n) asm volatile("s_waitcnt vmcnt(" #n ")" ::: "memory")
; #define PG8_WAIT_L(n) asm volatile("s_waitcnt lgkmcnt(" #n ")" ::: "memory")
; #define PG8_BAR __builtin_amdgcn_s_barrier()
; #define PG8_SCHED __builtin_amdgcn_sched_barrier(0)
; template <class Epi, class Sched, bool ALIGN_EPI = false, bool SP2 = false>
; __device__ __forceinline__ void gemm_phase(PG8_LAS unsigned char* lds, const Gemm g, const Sched& S, const Epi& E, const int wid) {
;     ...
;             PG8_LDA(At, 1, 1); PG8_STAGE(PG8_SB(1, 0), b3, voffB); PG8_STAGE(PG8_SB(1, 1), b3 + hstep, voffB); PG8_STAGE(PG8_SA(1, 0), a3, voffA);
;             PG8_WAIT_V(8); PG8_WAIT_L(0); PG8_BAR; PG8_MMA(1, 0, At, B0); PG8_MMA(1, 1, At, B1); PG8_BAR; PG8_SCHED;
	s_add_i32 s26, s47, s9
	v_lshl_add_u64 v[206:207], v[206:207], 0, s[2:3]
	s_mov_b32 m0, s26
	ds_read_b128 v[182:185], v153 offset:49152
	ds_read_b128 v[186:189], v153 offset:50176
	ds_read_b128 v[190:193], v153 offset:51200
	ds_read_b128 v[194:197], v153 offset:52224
	ds_read_b128 v[198:201], v153 offset:53248
	ds_read_b128 v[202:205], v153 offset:54272
	ds_read_b128 v[210:213], v153 offset:55296
	ds_read_b128 v[214:217], v153 offset:56320
	global_load_lds_dwordx4 v[206:207], off
	s_add_i32 m0, s26, 0x2000
	s_add_u32 s24, s24, 0x40080
	v_lshl_add_u64 v[206:207], v[218:219], 0, s[2:3]
	s_addc_u32 s25, s25, 0
	s_add_i32 s26, s48, s9
	global_load_lds_dwordx4 v[206:207], off
	v_lshl_add_u64 v[206:207], s[24:25], 0, v[132:133]
	s_mov_b32 m0, s26
	s_nop 0
	global_load_lds_dwordx4 v[206:207], off
	v_lshl_add_u64 v[206:207], s[24:25], 0, v[128:129]
	s_add_i32 m0, s26, 0x2000
	s_nop 0
	global_load_lds_dwordx4 v[206:207], off
	v_lshl_add_u64 v[206:207], v[220:221], 0, s[2:3]
	s_mov_b32 m0, s35
	s_nop 0
	global_load_lds_dwordx4 v[206:207], off
	v_lshl_add_u64 v[206:207], v[222:223], 0, s[2:3]
	s_mov_b32 m0, s36
	s_nop 0
	global_load_lds_dwordx4 v[206:207], off
	s_waitcnt vmcnt(8)
	s_waitcnt lgkmcnt(0)
	s_barrier
	v_mfma_f32_16x16x32_bf16 v[60:63], v[144:147], v[182:185], v[60:63]
	v_mfma_f32_16x16x32_bf16 v[52:55], v[158:161], v[182:185], v[52:55]
	v_mfma_f32_16x16x32_bf16 v[44:47], v[144:147], v[190:193], v[44:47]
	v_mfma_f32_16x16x32_bf16 v[36:39], v[158:161], v[190:193], v[36:39]
	v_mfma_f32_16x16x32_bf16 v[28:31], v[144:147], v[198:201], v[28:31]
	v_mfma_f32_16x16x32_bf16 v[20:23], v[158:161], v[198:201], v[20:23]
	v_mfma_f32_16x16x32_bf16 v[12:15], v[144:147], v[210:213], v[12:15]
	v_mfma_f32_16x16x32_bf16 v[4:7], v[158:161], v[210:213], v[4:7]
	v_mfma_f32_16x16x32_bf16 v[60:63], v[154:157], v[186:189], v[60:63]
	v_mfma_f32_16x16x32_bf16 v[52:55], v[162:165], v[186:189], v[52:55]
	v_mfma_f32_16x16x32_bf16 v[44:47], v[154:157], v[194:197], v[44:47]
	v_mfma_f32_16x16x32_bf16 v[36:39], v[162:165], v[194:197], v[36:39]
	v_mfma_f32_16x16x32_bf16 v[28:31], v[154:157], v[202:205], v[28:31]
	v_mfma_f32_16x16x32_bf16 v[20:23], v[162:165], v[202:205], v[20:23]
	v_mfma_f32_16x16x32_bf16 v[12:15], v[154:157], v[214:217], v[12:15]
	v_mfma_f32_16x16x32_bf16 v[4:7], v[162:165], v[214:217], v[4:7]
	v_mfma_f32_16x16x32_bf16 v[56:59], v[166:169], v[182:185], v[56:59]
	v_mfma_f32_16x16x32_bf16 v[48:51], v[174:177], v[182:185], v[48:51]
	v_mfma_f32_16x16x32_bf16 v[40:43], v[166:169], v[190:193], v[40:43]
	v_mfma_f32_16x16x32_bf16 v[32:35], v[174:177], v[190:193], v[32:35]
	v_mfma_f32_16x16x32_bf16 v[24:27], v[166:169], v[198:201], v[24:27]
	v_mfma_f32_16x16x32_bf16 v[16:19], v[174:177], v[198:201], v[16:19]
	v_mfma_f32_16x16x32_bf16 v[8:11], v[166:169], v[210:213], v[8:11]
	v_mfma_f32_16x16x32_bf16 v[0:3], v[174:177], v[210:213], v[0:3]
	v_mfma_f32_16x16x32_bf16 v[56:59], v[170:173], v[186:189], v[56:59]
	v_mfma_f32_16x16x32_bf16 v[48:51], v[178:181], v[186:189], v[48:51]
	v_mfma_f32_16x16x32_bf16 v[40:43], v[170:173], v[194:197], v[40:43]
	v_mfma_f32_16x16x32_bf16 v[32:35], v[178:181], v[194:197], v[32:35]
	v_mfma_f32_16x16x32_bf16 v[24:27], v[170:173], v[202:205], v[24:27]
	v_mfma_f32_16x16x32_bf16 v[16:19], v[178:181], v[202:205], v[16:19]
	v_mfma_f32_16x16x32_bf16 v[8:11], v[170:173], v[214:217], v[8:11]
	v_mfma_f32_16x16x32_bf16 v[0:3], v[178:181], v[214:217], v[0:3]
	s_barrier
	s_add_i32 s46, s46, 2
	s_add_u32 s22, s22, 0x100
	s_addc_u32 s23, s23, 0
	s_add_u32 s44, s44, 0x100
	s_addc_u32 s45, s45, 0
	s_cmp_gt_u32 s46, 13
	s_cbranch_scc0 .LBB0_1912

; #define PG8_STAGE(bufoff, gbase, voff) do { _Pragma("unroll") for (int _i = 0; _i < 2; ++_i) \
;         __builtin_amdgcn_global_load_lds((const unsigned*)((const char*)(gbase) + (voff)[_i]), (PG8_LAS unsigned*)(lds + (bufoff) + ldsw + _i * 8192), 16, 0, 0); } while (0)
; #define PG8_LDA(dst, b, h) do { _Pragma("unroll") for (int m = 0; m < 4; ++m) _Pragma("unroll") for (int k = 0; k < 2; ++k) dst[m][k] = *(const PG8_LAS bf16x8*)(lds + PG8_SA(b, h) + aoff + m * 2048 + k * 1024); } while (0)
; #define PG8_LDB(dst, b, h) do { _Pragma("unroll") for (int n = 0; n < 2; ++n) _Pragma("unroll") for (int k = 0; k < 2; ++k) dst[n][k] = *(const PG8_LAS bf16x8*)(lds + PG8_SB(b, h) + boff + n * 2048 + k * 1024); } while (0)
; #define PG8_MMA(ai, bj, At, Bt) do { __builtin_amdgcn_s_setprio(1); _Pragma("unroll") for (int m = 0; m < 4; ++m) _Pragma("unroll") for (int n = 0; n < 2; ++n) _Pragma("unroll") for (int k = 0; k < 2; ++k) \
;         acc[ai][bj][m][n] = __builtin_amdgcn_mfma_f32_16x16x32_bf16(Bt[n][k], At[m][k], acc[ai][bj][m][n], 0, 0, 0); __builtin_amdgcn_s_setprio(0); } while (0)
; #define PG8_WAIT_V(n) asm volatile("s_waitcnt vmcnt(" #n ")" ::: "memory")
; #define PG8_WAIT_L(n) asm volatile("s_waitcnt lgkmcnt(" #n ")" ::: "memory")
; #define PG8_BAR __builtin_amdgcn_s_barrier()
; #define PG8_SCHED __builtin_amdgcn_sched_barrier(0)
; template <class Epi, class Sched, bool ALIGN_EPI = false, bool SP2 = false>
; __device__ __forceinline__ void gemm_phase(PG8_LAS unsigned char* lds, const Gemm g, const Sched& S, const Epi& E, const int wid) {
;     ...
;             PG8_LDB(B0, 0, 0); PG8_LDB(B1, 0, 1); PG8_SCHED; PG8_LDA(At, 0, 0); PG8_STAGE(PG8_SA(1, 1), a1 + hstep, voffA);
;             PG8_WAIT_V(8); PG8_WAIT_L(0); PG8_BAR; PG8_MMA(0, 0, At, B0); PG8_MMA(0, 1, At, B1); PG8_BAR; PG8_SCHED;
;             PG8_LDA(At, 0, 1); PG8_STAGE(PG8_SB(0, 0), b2, voffB); PG8_STAGE(PG8_SB(0, 1), b2 + hstep, voffB); PG8_STAGE(PG8_SA(0, 0), a2, voffA);
;             PG8_WAIT_V(8); PG8_WAIT_L(0); PG8_BAR; PG8_MMA(1, 0, At, B0); PG8_MMA(1, 1, At, B1); PG8_BAR; PG8_SCHED;
.LBB0_2460:
	v_add_u32_e32 v151, s35, v149
	ds_read_b128 v[152:155], v151
	ds_read_b128 v[156:159], v151 offset:1024
	ds_read_b128 v[160:163], v151 offset:2048
	ds_read_b128 v[168:171], v151 offset:3072
	v_add_u32_e32 v151, s36, v149
	s_add_u32 s16, s8, s14
	ds_read_b128 v[172:175], v151
	ds_read_b128 v[178:181], v151 offset:1024
	ds_read_b128 v[182:185], v151 offset:2048
	ds_read_b128 v[186:189], v151 offset:3072
	s_addc_u32 s17, s9, s15
	s_add_u32 s16, s16, 0x100
	s_addc_u32 s17, s17, 0
	s_add_u32 s43, s40, s14
	s_addc_u32 s44, s41, s15
	s_cmpk_eq_i32 s14, 0x1500
	s_cselect_b32 s19, s13, s17
	s_cselect_b32 s18, s12, s16
	s_cselect_b32 s17, s5, s44
	s_cselect_b32 s16, s4, s43
	v_lshl_add_u64 v[222:223], v[144:145], 0, s[14:15]
	s_add_i32 m0, s26, 0xc000
	ds_read_b128 v[190:193], v150
	ds_read_b128 v[194:197], v150 offset:1024
	ds_read_b128 v[198:201], v150 offset:2048
	ds_read_b128 v[202:205], v150 offset:3072
	ds_read_b128 v[206:209], v150 offset:4096
	ds_read_b128 v[210:213], v150 offset:5120
	ds_read_b128 v[214:217], v150 offset:6144
	ds_read_b128 v[218:221], v150 offset:7168
	global_load_lds_dwordx4 v[222:223], off
	v_lshl_add_u64 v[222:223], v[146:147], 0, s[14:15]
	s_add_i32 m0, s26, 0xe000
	s_nop 0
	global_load_lds_dwordx4 v[222:223], off
	s_waitcnt vmcnt(8)
	s_waitcnt lgkmcnt(0)
	s_barrier
	v_mfma_f32_16x16x32_bf16 v[124:127], v[152:155], v[190:193], v[124:127]
	v_mfma_f32_16x16x32_bf16 v[120:123], v[160:163], v[190:193], v[120:123]
	v_mfma_f32_16x16x32_bf16 v[112:115], v[152:155], v[198:201], v[112:115]
	v_mfma_f32_16x16x32_bf16 v[104:107], v[160:163], v[198:201], v[104:107]
	v_mfma_f32_16x16x32_bf16 v[96:99], v[152:155], v[206:209], v[96:99]
	v_mfma_f32_16x16x32_bf16 v[88:91], v[160:163], v[206:209], v[88:91]
	v_mfma_f32_16x16x32_bf16 v[80:83], v[152:155], v[214:217], v[80:83]
	v_mfma_f32_16x16x32_bf16 v[72:75], v[160:163], v[214:217], v[72:75]
	v_mfma_f32_16x16x32_bf16 v[124:127], v[156:159], v[194:197], v[124:127]
	v_mfma_f32_16x16x32_bf16 v[120:123], v[168:171], v[194:197], v[120:123]
	v_mfma_f32_16x16x32_bf16 v[112:115], v[156:159], v[202:205], v[112:115]
	v_mfma_f32_16x16x32_bf16 v[104:107], v[168:171], v[202:205], v[104:107]
	v_mfma_f32_16x16x32_bf16 v[96:99], v[156:159], v[210:213], v[96:99]
	v_mfma_f32_16x16x32_bf16 v[88:91], v[168:171], v[210:213], v[88:91]
	v_mfma_f32_16x16x32_bf16 v[80:83], v[156:159], v[218:221], v[80:83]
	v_mfma_f32_16x16x32_bf16 v[72:75], v[168:171], v[218:221], v[72:75]
	v_mfma_f32_16x16x32_bf16 v[116:119], v[172:175], v[190:193], v[116:119]
	v_mfma_f32_16x16x32_bf16 v[108:111], v[182:185], v[190:193], v[108:111]
	v_mfma_f32_16x16x32_bf16 v[100:103], v[172:175], v[198:201], v[100:103]
	v_mfma_f32_16x16x32_bf16 v[92:95], v[182:185], v[198:201], v[92:95]
	v_mfma_f32_16x16x32_bf16 v[84:87], v[172:175], v[206:209], v[84:87]
	v_mfma_f32_16x16x32_bf16 v[76:79], v[182:185], v[206:209], v[76:79]
	v_mfma_f32_16x16x32_bf16 v[68:71], v[172:175], v[214:217], v[68:71]
	v_mfma_f32_16x16x32_bf16 v[64:67], v[182:185], v[214:217], v[64:67]
	v_mfma_f32_16x16x32_bf16 v[116:119], v[178:181], v[194:197], v[116:119]
	v_mfma_f32_16x16x32_bf16 v[108:111], v[186:189], v[194:197], v[108:111]
	v_mfma_f32_16x16x32_bf16 v[100:103], v[178:181], v[202:205], v[100:103]
	v_mfma_f32_16x16x32_bf16 v[92:95], v[186:189], v[202:205], v[92:95]
	v_mfma_f32_16x16x32_bf16 v[84:87], v[178:181], v[210:213], v[84:87]
	v_mfma_f32_16x16x32_bf16 v[76:79], v[186:189], v[210:213], v[76:79]
	v_mfma_f32_16x16x32_bf16 v[68:71], v[178:181], v[218:221], v[68:71]
	v_mfma_f32_16x16x32_bf16 v[64:67], v[186:189], v[218:221], v[64:67]
	s_barrier
	s_add_i32 s43, s35, s24
	v_lshl_add_u64 v[222:223], s[16:17], 0, v[130:131]
	s_mov_b32 m0, s43
	ds_read_b128 v[190:193], v150 offset:16384
	ds_read_b128 v[194:197], v150 offset:17408
	ds_read_b128 v[198:201], v150 offset:18432
	ds_read_b128 v[202:205], v150 offset:19456
	ds_read_b128 v[206:209], v150 offset:20480
	ds_read_b128 v[210:213], v150 offset:21504
	ds_read_b128 v[214:217], v150 offset:22528
	ds_read_b128 v[218:221], v150 offset:23552
	global_load_lds_dwordx4 v[222:223], off
	s_add_i32 m0, s43, 0x2000
	s_add_u32 s44, s16, 0xb0000
	v_lshl_add_u64 v[224:225], s[16:17], 0, v[134:135]
	s_addc_u32 s45, s17, 0
	s_add_i32 s43, s36, s24
	global_load_lds_dwordx4 v[224:225], off
	v_lshl_add_u64 v[226:227], s[44:45], 0, v[130:131]
	s_mov_b32 m0, s43
	v_lshl_add_u64 v[228:229], s[18:19], 0, v[132:133]
	global_load_lds_dwordx4 v[226:227], off
	v_lshl_add_u64 v[226:227], s[44:45], 0, v[134:135]
	s_add_i32 m0, s43, 0x2000
	s_nop 0
	global_load_lds_dwordx4 v[226:227], off
	v_lshl_add_u64 v[226:227], s[18:19], 0, v[128:129]
	s_mov_b32 m0, s26
	s_nop 0
	global_load_lds_dwordx4 v[226:227], off
	s_mov_b32 m0, s27
	s_nop 0
	global_load_lds_dwordx4 v[228:229], off
	s_waitcnt vmcnt(8)
	s_waitcnt lgkmcnt(0)
	s_barrier
; #define PG8_STAGE(bufoff, gbase, voff) do { _Pragma("unroll") for (int _i = 0; _i < 2; ++_i) \
;         __builtin_amdgcn_global_load_lds((const unsigned*)((const char*)(gbase) + (voff)[_i]), (PG8_LAS unsigned*)(lds + (bufoff) + ldsw + _i * 8192), 16, 0, 0); } while (0)
; #define PG8_LDA(dst, b, h) do { _Pragma("unroll") for (int m = 0; m < 4; ++m) _Pragma("unroll") for (int k = 0; k < 2; ++k) dst[m][k] = *(const PG8_LAS bf16x8*)(lds + PG8_SA(b, h) + aoff + m * 2048 + k * 1024); } while (0)
; #define PG8_LDB(dst, b, h) do { _Pragma("unroll") for (int n = 0; n < 2; ++n) _Pragma("unroll") for (int k = 0; k < 2; ++k) dst[n][k] = *(const PG8_LAS bf16x8*)(lds + PG8_SB(b, h) + boff + n * 2048 + k * 1024); } while (0)
; #define PG8_MMA(ai, bj, At, Bt) do { __builtin_amdgcn_s_setprio(1); _Pragma("unroll") for (int m = 0; m < 4; ++m) _Pragma("unroll") for (int n = 0; n < 2; ++n) _Pragma("unroll") for (int k = 0; k < 2; ++k) \
;         acc[ai][bj][m][n] = __builtin_amdgcn_mfma_f32_16x16x32_bf16(Bt[n][k], At[m][k], acc[ai][bj][m][n], 0, 0, 0); __builtin_amdgcn_s_setprio(0); } while (0)
; #define PG8_WAIT_V(n) asm volatile("s_waitcnt vmcnt(" #n ")" ::: "memory")
; #define PG8_WAIT_L(n) asm volatile("s_waitcnt lgkmcnt(" #n ")" ::: "memory")
; #define PG8_BAR __builtin_amdgcn_s_barrier()
; #define PG8_SCHED __builtin_amdgcn_sched_barrier(0)
; template <class Epi, class Sched, bool ALIGN_EPI = false, bool SP2 = false>
; __device__ __forceinline__ void gemm_phase(PG8_LAS unsigned char* lds, const Gemm g, const Sched& S, const Epi& E, const int wid) {
;     ...
;             PG8_WAIT_V(8); PG8_WAIT_L(0); PG8_BAR; PG8_MMA(1, 0, At, B0); PG8_MMA(1, 1, At, B1); PG8_BAR; PG8_SCHED;
;             PG8_LDB(B0, 1, 0); PG8_LDB(B1, 1, 1); PG8_SCHED; PG8_LDA(At, 1, 0); PG8_STAGE(PG8_SA(0, 1), a2 + hstep, voffA);
;             PG8_WAIT_V(8); PG8_WAIT_L(0); PG8_BAR; PG8_MMA(0, 0, At, B0); PG8_MMA(0, 1, At, B1); PG8_BAR; PG8_SCHED;
	v_mfma_f32_16x16x32_bf16 v[60:63], v[152:155], v[190:193], v[60:63]
	v_mfma_f32_16x16x32_bf16 v[56:59], v[160:163], v[190:193], v[56:59]
	v_mfma_f32_16x16x32_bf16 v[44:47], v[152:155], v[198:201], v[44:47]
	v_mfma_f32_16x16x32_bf16 v[40:43], v[160:163], v[198:201], v[40:43]
	v_mfma_f32_16x16x32_bf16 v[28:31], v[152:155], v[206:209], v[28:31]
	v_mfma_f32_16x16x32_bf16 v[24:27], v[160:163], v[206:209], v[24:27]
	v_mfma_f32_16x16x32_bf16 v[12:15], v[152:155], v[214:217], v[12:15]
	v_mfma_f32_16x16x32_bf16 v[8:11], v[160:163], v[214:217], v[8:11]
	v_mfma_f32_16x16x32_bf16 v[60:63], v[156:159], v[194:197], v[60:63]
	v_mfma_f32_16x16x32_bf16 v[56:59], v[168:171], v[194:197], v[56:59]
	v_mfma_f32_16x16x32_bf16 v[44:47], v[156:159], v[202:205], v[44:47]
	v_mfma_f32_16x16x32_bf16 v[40:43], v[168:171], v[202:205], v[40:43]
	v_mfma_f32_16x16x32_bf16 v[28:31], v[156:159], v[210:213], v[28:31]
	v_mfma_f32_16x16x32_bf16 v[24:27], v[168:171], v[210:213], v[24:27]
	v_mfma_f32_16x16x32_bf16 v[12:15], v[156:159], v[218:221], v[12:15]
	v_mfma_f32_16x16x32_bf16 v[8:11], v[168:171], v[218:221], v[8:11]
	v_mfma_f32_16x16x32_bf16 v[52:55], v[172:175], v[190:193], v[52:55]
	v_mfma_f32_16x16x32_bf16 v[48:51], v[182:185], v[190:193], v[48:51]
	v_mfma_f32_16x16x32_bf16 v[36:39], v[172:175], v[198:201], v[36:39]
	v_mfma_f32_16x16x32_bf16 v[32:35], v[182:185], v[198:201], v[32:35]
	v_mfma_f32_16x16x32_bf16 v[20:23], v[172:175], v[206:209], v[20:23]
	v_mfma_f32_16x16x32_bf16 v[16:19], v[182:185], v[206:209], v[16:19]
	v_mfma_f32_16x16x32_bf16 v[4:7], v[172:175], v[214:217], v[4:7]
	v_mfma_f32_16x16x32_bf16 v[0:3], v[182:185], v[214:217], v[0:3]
	v_mfma_f32_16x16x32_bf16 v[52:55], v[178:181], v[194:197], v[52:55]
	v_mfma_f32_16x16x32_bf16 v[48:51], v[186:189], v[194:197], v[48:51]
	v_mfma_f32_16x16x32_bf16 v[36:39], v[178:181], v[202:205], v[36:39]
	v_mfma_f32_16x16x32_bf16 v[32:35], v[186:189], v[202:205], v[32:35]
	v_mfma_f32_16x16x32_bf16 v[20:23], v[178:181], v[210:213], v[20:23]
	v_mfma_f32_16x16x32_bf16 v[16:19], v[186:189], v[210:213], v[16:19]
	v_mfma_f32_16x16x32_bf16 v[4:7], v[178:181], v[218:221], v[4:7]
	v_mfma_f32_16x16x32_bf16 v[0:3], v[186:189], v[218:221], v[0:3]
	s_barrier
	s_add_i32 s43, 0, 0x18000
	v_add_u32_e32 v151, s43, v149
	s_add_i32 s44, 0, 0x1c000
	ds_read_b128 v[152:155], v151
	ds_read_b128 v[156:159], v151 offset:1024
	ds_read_b128 v[160:163], v151 offset:2048
	ds_read_b128 v[168:171], v151 offset:3072
	v_add_u32_e32 v151, s44, v149
	ds_read_b128 v[172:175], v151
	ds_read_b128 v[178:181], v151 offset:1024
	ds_read_b128 v[182:185], v151 offset:2048
	ds_read_b128 v[186:189], v151 offset:3072
	s_add_u32 s18, s18, 0xb0000
	s_addc_u32 s19, s19, 0
	s_mov_b32 m0, s28
	v_lshl_add_u64 v[230:231], s[18:19], 0, v[128:129]
	ds_read_b128 v[190:193], v150 offset:32768
	ds_read_b128 v[194:197], v150 offset:33792
	ds_read_b128 v[198:201], v150 offset:34816
	ds_read_b128 v[202:205], v150 offset:35840
	ds_read_b128 v[206:209], v150 offset:36864
	ds_read_b128 v[210:213], v150 offset:37888
	ds_read_b128 v[214:217], v150 offset:38912
	ds_read_b128 v[218:221], v150 offset:39936
	global_load_lds_dwordx4 v[230:231], off
	v_lshl_add_u64 v[230:231], s[18:19], 0, v[132:133]
	s_mov_b32 m0, s29
	s_nop 0
	global_load_lds_dwordx4 v[230:231], off
	s_waitcnt vmcnt(8)
	s_waitcnt lgkmcnt(0)
	s_barrier
	v_mfma_f32_16x16x32_bf16 v[124:127], v[152:155], v[190:193], v[124:127]
	v_mfma_f32_16x16x32_bf16 v[120:123], v[160:163], v[190:193], v[120:123]
	v_mfma_f32_16x16x32_bf16 v[112:115], v[152:155], v[198:201], v[112:115]
	v_mfma_f32_16x16x32_bf16 v[104:107], v[160:163], v[198:201], v[104:107]
	v_mfma_f32_16x16x32_bf16 v[96:99], v[152:155], v[206:209], v[96:99]
	v_mfma_f32_16x16x32_bf16 v[88:91], v[160:163], v[206:209], v[88:91]
	v_mfma_f32_16x16x32_bf16 v[80:83], v[152:155], v[214:217], v[80:83]
	v_mfma_f32_16x16x32_bf16 v[72:75], v[160:163], v[214:217], v[72:75]
	v_mfma_f32_16x16x32_bf16 v[124:127], v[156:159], v[194:197], v[124:127]
	v_mfma_f32_16x16x32_bf16 v[120:123], v[168:171], v[194:197], v[120:123]
	v_mfma_f32_16x16x32_bf16 v[112:115], v[156:159], v[202:205], v[112:115]
	v_mfma_f32_16x16x32_bf16 v[104:107], v[168:171], v[202:205], v[104:107]
	v_mfma_f32_16x16x32_bf16 v[96:99], v[156:159], v[210:213], v[96:99]
	v_mfma_f32_16x16x32_bf16 v[88:91], v[168:171], v[210:213], v[88:91]
	v_mfma_f32_16x16x32_bf16 v[80:83], v[156:159], v[218:221], v[80:83]
	v_mfma_f32_16x16x32_bf16 v[72:75], v[168:171], v[218:221], v[72:75]
	v_mfma_f32_16x16x32_bf16 v[116:119], v[172:175], v[190:193], v[116:119]
	v_mfma_f32_16x16x32_bf16 v[108:111], v[182:185], v[190:193], v[108:111]
	v_mfma_f32_16x16x32_bf16 v[100:103], v[172:175], v[198:201], v[100:103]
	v_mfma_f32_16x16x32_bf16 v[92:95], v[182:185], v[198:201], v[92:95]
	v_mfma_f32_16x16x32_bf16 v[84:87], v[172:175], v[206:209], v[84:87]
	v_mfma_f32_16x16x32_bf16 v[76:79], v[182:185], v[206:209], v[76:79]
	v_mfma_f32_16x16x32_bf16 v[68:71], v[172:175], v[214:217], v[68:71]
	v_mfma_f32_16x16x32_bf16 v[64:67], v[182:185], v[214:217], v[64:67]
	v_mfma_f32_16x16x32_bf16 v[116:119], v[178:181], v[194:197], v[116:119]
	v_mfma_f32_16x16x32_bf16 v[108:111], v[186:189], v[194:197], v[108:111]
	v_mfma_f32_16x16x32_bf16 v[100:103], v[178:181], v[202:205], v[100:103]
	v_mfma_f32_16x16x32_bf16 v[92:95], v[186:189], v[202:205], v[92:95]
	v_mfma_f32_16x16x32_bf16 v[84:87], v[178:181], v[210:213], v[84:87]
	v_mfma_f32_16x16x32_bf16 v[76:79], v[186:189], v[210:213], v[76:79]
	v_mfma_f32_16x16x32_bf16 v[68:71], v[178:181], v[218:221], v[68:71]
	v_mfma_f32_16x16x32_bf16 v[64:67], v[186:189], v[218:221], v[64:67]
	s_barrier
; #define PG8_STAGE(bufoff, gbase, voff) do { _Pragma("unroll") for (int _i = 0; _i < 2; ++_i) \
;         __builtin_amdgcn_global_load_lds((const unsigned*)((const char*)(gbase) + (voff)[_i]), (PG8_LAS unsigned*)(lds + (bufoff) + ldsw + _i * 8192), 16, 0, 0); } while (0)
; #define PG8_LDA(dst, b, h) do { _Pragma("unroll") for (int m = 0; m < 4; ++m) _Pragma("unroll") for (int k = 0; k < 2; ++k) dst[m][k] = *(const PG8_LAS bf16x8*)(lds + PG8_SA(b, h) + aoff + m * 2048 + k * 1024); } while (0)
; #define PG8_MMA(ai, bj, At, Bt) do { __builtin_amdgcn_s_setprio(1); _Pragma("unroll") for (int m = 0; m < 4; ++m) _Pragma("unroll") for (int n = 0; n < 2; ++n) _Pragma("unroll") for (int k = 0; k < 2; ++k) \
;         acc[ai][bj][m][n] = __builtin_amdgcn_mfma_f32_16x16x32_bf16(Bt[n][k], At[m][k], acc[ai][bj][m][n], 0, 0, 0); __builtin_amdgcn_s_setprio(0); } while (0)
; #define PG8_WAIT_V(n) asm volatile("s_waitcnt vmcnt(" #n ")" ::: "memory")
; #define PG8_WAIT_L(n) asm volatile("s_waitcnt lgkmcnt(" #n ")" ::: "memory")
; #define PG8_BAR __builtin_amdgcn_s_barrier()
; #define PG8_SCHED __builtin_amdgcn_sched_barrier(0)
; template <class Epi, class Sched, bool ALIGN_EPI = false, bool SP2 = false>
; __device__ __forceinline__ void gemm_phase(PG8_LAS unsigned char* lds, const Gemm g, const Sched& S, const Epi& E, const int wid) {
;     ...
;             PG8_LDA(At, 1, 1); PG8_STAGE(PG8_SB(1, 0), b3, voffB); PG8_STAGE(PG8_SB(1, 1), b3 + hstep, voffB); PG8_STAGE(PG8_SA(1, 0), a3, voffA);
;             PG8_WAIT_V(8); PG8_WAIT_L(0); PG8_BAR; PG8_MMA(1, 0, At, B0); PG8_MMA(1, 1, At, B1); PG8_BAR; PG8_SCHED;
;     ...
;         if (!has_next) break;
; #pragma unroll
;         for (int a = 0; a < 2; ++a)
; #pragma unroll
;             for (int b = 0; b < 2; ++b)
; #pragma unroll
;                 for (int m = 0; m < 4; ++m)
; #pragma unroll
;                     for (int n = 0; n < 2; ++n) acc[a][b][m][n] = (f32x4){0.f, 0.f, 0.f, 0.f};
;         cur = nxt; cA = nA; cB = nB; ++ui;
	s_add_i32 s18, s43, s24
	v_lshl_add_u64 v[222:223], v[222:223], 0, s[10:11]
	s_mov_b32 m0, s18
	ds_read_b128 v[190:193], v150 offset:49152
	ds_read_b128 v[194:197], v150 offset:50176
	ds_read_b128 v[198:201], v150 offset:51200
	ds_read_b128 v[202:205], v150 offset:52224
	ds_read_b128 v[206:209], v150 offset:53248
	ds_read_b128 v[210:213], v150 offset:54272
	ds_read_b128 v[214:217], v150 offset:55296
	ds_read_b128 v[218:221], v150 offset:56320
	global_load_lds_dwordx4 v[222:223], off
	s_add_i32 m0, s18, 0x2000
	s_add_u32 s16, s16, 0xb0080
	v_lshl_add_u64 v[222:223], v[224:225], 0, s[10:11]
	s_addc_u32 s17, s17, 0
	s_add_i32 s18, s44, s24
	global_load_lds_dwordx4 v[222:223], off
	v_lshl_add_u64 v[222:223], s[16:17], 0, v[130:131]
	s_mov_b32 m0, s18
	s_nop 0
	global_load_lds_dwordx4 v[222:223], off
	v_lshl_add_u64 v[222:223], s[16:17], 0, v[134:135]
	s_add_i32 m0, s18, 0x2000
	s_nop 0
	global_load_lds_dwordx4 v[222:223], off
	v_lshl_add_u64 v[222:223], v[226:227], 0, s[10:11]
	s_mov_b32 m0, s31
	s_nop 0
	global_load_lds_dwordx4 v[222:223], off
	v_lshl_add_u64 v[222:223], v[228:229], 0, s[10:11]
	s_mov_b32 m0, s33
	s_nop 0
	global_load_lds_dwordx4 v[222:223], off
	s_waitcnt vmcnt(8)
	s_waitcnt lgkmcnt(0)
	s_barrier
	v_mfma_f32_16x16x32_bf16 v[60:63], v[152:155], v[190:193], v[60:63]
	v_mfma_f32_16x16x32_bf16 v[56:59], v[160:163], v[190:193], v[56:59]
	v_mfma_f32_16x16x32_bf16 v[44:47], v[152:155], v[198:201], v[44:47]
	v_mfma_f32_16x16x32_bf16 v[40:43], v[160:163], v[198:201], v[40:43]
	v_mfma_f32_16x16x32_bf16 v[28:31], v[152:155], v[206:209], v[28:31]
	v_mfma_f32_16x16x32_bf16 v[24:27], v[160:163], v[206:209], v[24:27]
	v_mfma_f32_16x16x32_bf16 v[12:15], v[152:155], v[214:217], v[12:15]
	v_mfma_f32_16x16x32_bf16 v[8:11], v[160:163], v[214:217], v[8:11]
	v_mfma_f32_16x16x32_bf16 v[60:63], v[156:159], v[194:197], v[60:63]
	v_mfma_f32_16x16x32_bf16 v[56:59], v[168:171], v[194:197], v[56:59]
	v_mfma_f32_16x16x32_bf16 v[44:47], v[156:159], v[202:205], v[44:47]
	v_mfma_f32_16x16x32_bf16 v[40:43], v[168:171], v[202:205], v[40:43]
	v_mfma_f32_16x16x32_bf16 v[28:31], v[156:159], v[210:213], v[28:31]
	v_mfma_f32_16x16x32_bf16 v[24:27], v[168:171], v[210:213], v[24:27]
	v_mfma_f32_16x16x32_bf16 v[12:15], v[156:159], v[218:221], v[12:15]
	v_mfma_f32_16x16x32_bf16 v[8:11], v[168:171], v[218:221], v[8:11]
	v_mfma_f32_16x16x32_bf16 v[52:55], v[172:175], v[190:193], v[52:55]
	v_mfma_f32_16x16x32_bf16 v[48:51], v[182:185], v[190:193], v[48:51]
	v_mfma_f32_16x16x32_bf16 v[36:39], v[172:175], v[198:201], v[36:39]
	v_mfma_f32_16x16x32_bf16 v[32:35], v[182:185], v[198:201], v[32:35]
	v_mfma_f32_16x16x32_bf16 v[20:23], v[172:175], v[206:209], v[20:23]
	v_mfma_f32_16x16x32_bf16 v[16:19], v[182:185], v[206:209], v[16:19]
	v_mfma_f32_16x16x32_bf16 v[4:7], v[172:175], v[214:217], v[4:7]
	v_mfma_f32_16x16x32_bf16 v[0:3], v[182:185], v[214:217], v[0:3]
	v_mfma_f32_16x16x32_bf16 v[52:55], v[178:181], v[194:197], v[52:55]
	v_mfma_f32_16x16x32_bf16 v[48:51], v[186:189], v[194:197], v[48:51]
	v_mfma_f32_16x16x32_bf16 v[36:39], v[178:181], v[202:205], v[36:39]
	v_mfma_f32_16x16x32_bf16 v[32:35], v[186:189], v[202:205], v[32:35]
	v_mfma_f32_16x16x32_bf16 v[20:23], v[178:181], v[210:213], v[20:23]
	v_mfma_f32_16x16x32_bf16 v[16:19], v[186:189], v[210:213], v[16:19]
	v_mfma_f32_16x16x32_bf16 v[4:7], v[178:181], v[218:221], v[4:7]
	v_mfma_f32_16x16x32_bf16 v[0:3], v[186:189], v[218:221], v[0:3]
	s_barrier
	s_add_i32 s42, s42, 2
	s_add_u32 s14, s14, 0x100
	s_addc_u32 s15, s15, 0
	s_cmp_gt_u32 s42, 41
	s_cbranch_scc0 .LBB0_2460
	s_add_u32 s14, s40, 0xffffff00
	s_addc_u32 s15, s41, -1
	s_and_b64 vcc, exec, s[6:7]
	s_cbranch_vccnz .LBB0_2447
	v_mov_b32_e32 v0, 0
	s_mov_b32 s2, s37
	s_mov_b32 s20, s38
	s_mov_b64 s[8:9], s[12:13]
	s_mov_b32 s34, s39
	v_mov_b32_e32 v1, v0
	v_mov_b32_e32 v2, v0
	v_mov_b32_e32 v3, v0
	v_mov_b32_e32 v4, v0
	v_mov_b32_e32 v5, v0
	v_mov_b32_e32 v6, v0
	v_mov_b32_e32 v7, v0
	v_mov_b32_e32 v16, v0
	v_mov_b32_e32 v17, v0
	v_mov_b32_e32 v18, v0
	v_mov_b32_e32 v19, v0
	v_mov_b32_e32 v20, v0
	v_mov_b32_e32 v21, v0
	v_mov_b32_e32 v22, v0
	v_mov_b32_e32 v23, v0
	v_mov_b32_e32 v32, v0
	v_mov_b32_e32 v33, v0
	v_mov_b32_e32 v34, v0
	v_mov_b32_e32 v35, v0
	v_mov_b32_e32 v36, v0
	v_mov_b32_e32 v37, v0
	v_mov_b32_e32 v38, v0
	v_mov_b32_e32 v39, v0
	v_mov_b32_e32 v48, v0
	v_mov_b32_e32 v49, v0
	v_mov_b32_e32 v50, v0
	v_mov_b32_e32 v51, v0
	v_mov_b32_e32 v52, v0
	v_mov_b32_e32 v53, v0
	v_mov_b32_e32 v54, v0
	v_mov_b32_e32 v55, v0
	v_mov_b32_e32 v8, v0
	v_mov_b32_e32 v9, v0
	v_mov_b32_e32 v10, v0
	v_mov_b32_e32 v11, v0
	v_mov_b32_e32 v12, v0
	v_mov_b32_e32 v13, v0
	v_mov_b32_e32 v14, v0
	v_mov_b32_e32 v15, v0
	v_mov_b32_e32 v24, v0
	v_mov_b32_e32 v25, v0
	v_mov_b32_e32 v26, v0
	v_mov_b32_e32 v27, v0
	v_mov_b32_e32 v28, v0
	v_mov_b32_e32 v29, v0
	v_mov_b32_e32 v30, v0
	v_mov_b32_e32 v31, v0
	v_mov_b32_e32 v40, v0
	v_mov_b32_e32 v41, v0
	v_mov_b32_e32 v42, v0
	v_mov_b32_e32 v43, v0
	v_mov_b32_e32 v44, v0
	v_mov_b32_e32 v45, v0
	v_mov_b32_e32 v46, v0
	v_mov_b32_e32 v47, v0
	v_mov_b32_e32 v56, v0
	v_mov_b32_e32 v57, v0
	v_mov_b32_e32 v58, v0
	v_mov_b32_e32 v59, v0
	v_mov_b32_e32 v60, v0
	v_mov_b32_e32 v61, v0
	v_mov_b32_e32 v62, v0
	v_mov_b32_e32 v63, v0
	v_mov_b32_e32 v64, v0
	v_mov_b32_e32 v65, v0
	v_mov_b32_e32 v66, v0
	v_mov_b32_e32 v67, v0
	v_mov_b32_e32 v68, v0
	v_mov_b32_e32 v69, v0
	v_mov_b32_e32 v70, v0
	v_mov_b32_e32 v71, v0
	v_mov_b32_e32 v76, v0
	v_mov_b32_e32 v77, v0
	v_mov_b32_e32 v78, v0
	v_mov_b32_e32 v79, v0
	v_mov_b32_e32 v84, v0
	v_mov_b32_e32 v85, v0
	v_mov_b32_e32 v86, v0
	v_mov_b32_e32 v87, v0
	v_mov_b32_e32 v92, v0
	v_mov_b32_e32 v93, v0
	v_mov_b32_e32 v94, v0
	v_mov_b32_e32 v95, v0
	v_mov_b32_e32 v100, v0
	v_mov_b32_e32 v101, v0
	v_mov_b32_e32 v102, v0
	v_mov_b32_e32 v103, v0
	v_mov_b32_e32 v108, v0
	v_mov_b32_e32 v109, v0
	v_mov_b32_e32 v110, v0
	v_mov_b32_e32 v111, v0
	v_mov_b32_e32 v116, v0
	v_mov_b32_e32 v117, v0
	v_mov_b32_e32 v118, v0
	v_mov_b32_e32 v119, v0
	v_mov_b32_e32 v72, v0
	v_mov_b32_e32 v73, v0
	v_mov_b32_e32 v74, v0
	v_mov_b32_e32 v75, v0
	v_mov_b32_e32 v80, v0
	v_mov_b32_e32 v81, v0
	v_mov_b32_e32 v82, v0
	v_mov_b32_e32 v83, v0
	v_mov_b32_e32 v88, v0
	v_mov_b32_e32 v89, v0
	v_mov_b32_e32 v90, v0
	v_mov_b32_e32 v91, v0
	v_mov_b32_e32 v96, v0
	v_mov_b32_e32 v97, v0
	v_mov_b32_e32 v98, v0
	v_mov_b32_e32 v99, v0
	v_mov_b32_e32 v104, v0
	v_mov_b32_e32 v105, v0
	v_mov_b32_e32 v106, v0
	v_mov_b32_e32 v107, v0
	v_mov_b32_e32 v112, v0
	v_mov_b32_e32 v113, v0
	v_mov_b32_e32 v114, v0
	v_mov_b32_e32 v115, v0
	v_mov_b32_e32 v120, v0
	v_mov_b32_e32 v121, v0
	v_mov_b32_e32 v122, v0
	v_mov_b32_e32 v123, v0
	v_mov_b32_e32 v124, v0
	v_mov_b32_e32 v125, v0
	v_mov_b32_e32 v126, v0
	v_mov_b32_e32 v127, v0
	s_andn2_b64 vcc, exec, s[0:1]
	s_cbranch_vccnz .LBB0_2448
